# removed per-segment s_setprio flips in the 7 rebalanced GEMM K-loops (on top of read rebalancing, vmcnt(10) guards, Mx rewrite)
# speedup vs baseline: 1.0084x; 1.0056x over previous
; #define PG8_STAGE(bufoff, gbase, voff) do { _Pragma("unroll") for (int _i = 0; _i < 2; ++_i) \
;         __builtin_amdgcn_global_load_lds((const unsigned*)((const char*)(gbase) + (voff)[_i]), (LAS unsigned*)(lds + (bufoff) + ldsw + _i * 8192), 16, 0, 0); } while (0)
; #define PG8_STAGE_A(bufoff, ptr, half, rev) do { if (REVA && (rev)) { const char* _p = (ptr) - ((half) ? hstepA : 0); PG8_STAGE(bufoff, _p, voffAr); } else { const char* _p = (ptr) + ((half) ? hstepA : 0); PG8_STAGE(bufoff, _p, voffA); } } while (0)
; #define PG8_LDA(dst, b, h) do { _Pragma("unroll") for (int m = 0; m < 4; ++m) _Pragma("unroll") for (int k = 0; k < 2; ++k) dst[m][k] = *(const LAS bf16x8*)(lds + PG8_SA(b, h) + aoff + m * 2048 + k * 1024); } while (0)
; #define PG8_LDB(dst, b, h) do { _Pragma("unroll") for (int n = 0; n < 2; ++n) _Pragma("unroll") for (int k = 0; k < 2; ++k) dst[n][k] = *(const LAS bf16x8*)(lds + PG8_SB(b, h) + boff + n * 2048 + k * 1024); } while (0)
; #define PG8_WAIT_L(n) asm volatile("s_waitcnt lgkmcnt(" #n ")" ::: "memory")
;     ...
;     for (;;) {
;         const bool has_next = next_unit(ui + 1, nM, nN, MP, nxt, rot);
;         const char* nA = has_next ? nxt.a : cA; const char* nB = has_next ? nxt.b : cB; const char* nAr = has_next ? nxt.ar : cAr; const size_t nHb = has_next ? nxt.hb : cHb;
;         for (int t = 0; t < nt; t += 2) {
;             const bool last = (t == nt - 2);
;             const char* a1 = PG8_APTR(cA, cAr, t + 1); const bool r1 = REVA && ((t + 1) & 4);
;             const char* a2 = last ? nA : PG8_APTR(cA, cAr, t + 2); const bool r2 = REVA && !last && ((t + 2) & 4);
;             const char* a3 = last ? nA + kstep : PG8_APTR(cA, cAr, t + 3); const bool r3 = REVA && !last && ((t + 3) & 4);
;             const char* b2 = last ? nB : cB + (size_t)(t + 2) * kstep; const char* b3 = b2 + kstep; const size_t hb2 = last ? nHb : cHb;
;             PG8_LDB(B0, 0, 0); PG8_SCHED; PG8_LDA(At, 0, 0); PG8_STAGE_A(PG8_SA(1, 1), a1, 1, r1);
;             PG8_WAIT_L(8); PG8_BAR; PG8_WAIT_L(0); PG8_MMA(0, 0, At, B0); PG8_BAR; PG8_SCHED;
;             PG8_LDB(B1, 0, 1); PG8_STAGE(PG8_SB(0, 0), b2, voffB);
;             PG8_BAR; PG8_WAIT_L(0); PG8_MMA(0, 1, At, B1); PG8_BAR;
;             PG8_LDA(At, 0, 1); PG8_STAGE_A(PG8_SA(0, 0), a2, 0, r2);
;             PG8_BAR; PG8_WAIT_L(0); PG8_MMA(1, 0, At, B0); PG8_BAR; PG8_SCHED;
.LBB0_234:
	s_add_u32 s10, s38, vcc_lo
	s_addc_u32 s11, s39, vcc_hi
	s_add_u32 s16, s10, 0x100
	s_addc_u32 s17, s11, 0
	s_add_u32 s10, s10, 0x180
	s_addc_u32 s11, s11, 0
	s_add_u32 s14, s7, vcc_lo
	s_addc_u32 s15, s8, vcc_hi
	s_add_i32 s27, 0, 0x10000
	s_cmpk_eq_i32 vcc_lo, 0xf00
	s_cselect_b32 s15, s71, s15
	s_cselect_b32 s14, s70, s14
	s_cselect_b32 s21, s1, s17
	s_cselect_b32 s20, s0, s16
	s_cselect_b32 s17, s6, s11
	s_cselect_b32 s16, s3, s10
	v_lshl_add_u64 v[154:155], v[88:89], 0, vcc
	s_add_i32 m0, s91, 0xc000
	ds_read_b128 v[180:183], v171
	ds_read_b128 v[204:207], v171 offset:1024
	ds_read_b128 v[208:211], v171 offset:2048
	ds_read_b128 v[212:215], v171 offset:3072
	ds_read_b128 v[216:219], v171 offset:4096
	ds_read_b128 v[220:223], v171 offset:5120
	ds_read_b128 v[224:227], v171 offset:6144
	ds_read_b128 v[228:231], v171 offset:7168
	global_load_lds_dwordx4 v[154:155], off
	v_lshl_add_u64 v[154:155], v[90:91], 0, vcc
	s_add_i32 m0, s91, 0xe000
	s_nop 0
	global_load_lds_dwordx4 v[154:155], off
	s_waitcnt lgkmcnt(8)
	s_waitcnt vmcnt(10)
	s_barrier
	s_waitcnt lgkmcnt(0)
	s_waitcnt lgkmcnt(0)
	v_mfma_f32_16x16x32_bf16 v[104:107], v[92:95], v[180:183], v[104:107]
	v_mfma_f32_16x16x32_bf16 v[136:139], v[172:175], v[180:183], v[136:139]
	v_mfma_f32_16x16x32_bf16 v[84:87], v[92:95], v[208:211], v[84:87]
	v_mfma_f32_16x16x32_bf16 v[128:131], v[172:175], v[208:211], v[128:131]
	v_mfma_f32_16x16x32_bf16 v[76:79], v[92:95], v[216:219], v[76:79]
	v_mfma_f32_16x16x32_bf16 v[120:123], v[172:175], v[216:219], v[120:123]
	v_mfma_f32_16x16x32_bf16 v[68:71], v[92:95], v[224:227], v[68:71]
	v_mfma_f32_16x16x32_bf16 v[112:115], v[172:175], v[224:227], v[112:115]
	v_mfma_f32_16x16x32_bf16 v[104:107], v[96:99], v[204:207], v[104:107]
	v_mfma_f32_16x16x32_bf16 v[136:139], v[176:179], v[204:207], v[136:139]
	v_mfma_f32_16x16x32_bf16 v[84:87], v[96:99], v[212:215], v[84:87]
	v_mfma_f32_16x16x32_bf16 v[128:131], v[176:179], v[212:215], v[128:131]
	v_mfma_f32_16x16x32_bf16 v[76:79], v[96:99], v[220:223], v[76:79]
	v_mfma_f32_16x16x32_bf16 v[120:123], v[176:179], v[220:223], v[120:123]
	v_mfma_f32_16x16x32_bf16 v[68:71], v[96:99], v[228:231], v[68:71]
	v_mfma_f32_16x16x32_bf16 v[112:115], v[176:179], v[228:231], v[112:115]
	s_barrier
	s_add_i32 s37, 0, 0x14000
	v_add_u32_e32 v154, s37, v156
	s_add_i32 s10, s27, s90
	ds_read_b128 v[232:235], v154
	ds_read_b128 v[236:239], v154 offset:1024
	ds_read_b128 v[240:243], v154 offset:2048
	ds_read_b128 v[244:247], v154 offset:3072
	v_lshl_add_u64 v[154:155], s[14:15], 0, v[160:161]
	s_mov_b32 m0, s10
	v_lshl_add_u64 v[184:185], s[14:15], 0, v[140:141]
	global_load_lds_dwordx4 v[154:155], off
	s_add_i32 m0, s10, 0x2000
	s_nop 0
	global_load_lds_dwordx4 v[184:185], off
	s_waitcnt vmcnt(10)
	s_barrier
	s_waitcnt lgkmcnt(0)
	s_waitcnt lgkmcnt(0)
	v_mfma_f32_16x16x32_bf16 v[132:135], v[232:235], v[180:183], v[132:135]
	v_mfma_f32_16x16x32_bf16 v[100:103], v[240:243], v[180:183], v[100:103]
	v_mfma_f32_16x16x32_bf16 v[124:127], v[232:235], v[208:211], v[124:127]
	v_mfma_f32_16x16x32_bf16 v[80:83], v[240:243], v[208:211], v[80:83]
	v_mfma_f32_16x16x32_bf16 v[116:119], v[232:235], v[216:219], v[116:119]
	v_mfma_f32_16x16x32_bf16 v[72:75], v[240:243], v[216:219], v[72:75]
	v_mfma_f32_16x16x32_bf16 v[108:111], v[232:235], v[224:227], v[108:111]
	v_mfma_f32_16x16x32_bf16 v[64:67], v[240:243], v[224:227], v[64:67]
	v_mfma_f32_16x16x32_bf16 v[132:135], v[236:239], v[204:207], v[132:135]
	v_mfma_f32_16x16x32_bf16 v[100:103], v[244:247], v[204:207], v[100:103]
	v_mfma_f32_16x16x32_bf16 v[124:127], v[236:239], v[212:215], v[124:127]
	v_mfma_f32_16x16x32_bf16 v[80:83], v[244:247], v[212:215], v[80:83]
	v_mfma_f32_16x16x32_bf16 v[116:119], v[236:239], v[220:223], v[116:119]
	v_mfma_f32_16x16x32_bf16 v[72:75], v[244:247], v[220:223], v[72:75]
	v_mfma_f32_16x16x32_bf16 v[108:111], v[236:239], v[228:231], v[108:111]
	v_mfma_f32_16x16x32_bf16 v[64:67], v[244:247], v[228:231], v[64:67]
	s_mov_b32 m0, s91
	v_lshl_add_u64 v[190:191], s[20:21], 0, v[160:161]
	s_barrier
	ds_read_b128 v[180:183], v171 offset:16384
	ds_read_b128 v[204:207], v171 offset:17408
	ds_read_b128 v[208:211], v171 offset:18432
	ds_read_b128 v[212:215], v171 offset:19456
	ds_read_b128 v[216:219], v171 offset:20480
	ds_read_b128 v[220:223], v171 offset:21504
	ds_read_b128 v[224:227], v171 offset:22528
	ds_read_b128 v[228:231], v171 offset:23552
	global_load_lds_dwordx4 v[190:191], off
	v_lshl_add_u64 v[190:191], s[20:21], 0, v[140:141]
	s_mov_b32 m0, s92
	s_nop 0
	global_load_lds_dwordx4 v[190:191], off
	s_waitcnt vmcnt(10)
	s_barrier
	s_waitcnt lgkmcnt(0)
	s_waitcnt lgkmcnt(0)
	v_mfma_f32_16x16x32_bf16 v[28:31], v[92:95], v[180:183], v[28:31]
	v_mfma_f32_16x16x32_bf16 v[60:63], v[172:175], v[180:183], v[60:63]
	v_mfma_f32_16x16x32_bf16 v[20:23], v[92:95], v[208:211], v[20:23]
	v_mfma_f32_16x16x32_bf16 v[52:55], v[172:175], v[208:211], v[52:55]
	v_mfma_f32_16x16x32_bf16 v[12:15], v[92:95], v[216:219], v[12:15]
	v_mfma_f32_16x16x32_bf16 v[44:47], v[172:175], v[216:219], v[44:47]
	v_mfma_f32_16x16x32_bf16 v[4:7], v[92:95], v[224:227], v[4:7]
	v_mfma_f32_16x16x32_bf16 v[36:39], v[172:175], v[224:227], v[36:39]
	v_mfma_f32_16x16x32_bf16 v[28:31], v[96:99], v[204:207], v[28:31]
	v_mfma_f32_16x16x32_bf16 v[60:63], v[176:179], v[204:207], v[60:63]
	v_mfma_f32_16x16x32_bf16 v[20:23], v[96:99], v[212:215], v[20:23]
	v_mfma_f32_16x16x32_bf16 v[52:55], v[176:179], v[212:215], v[52:55]
	v_mfma_f32_16x16x32_bf16 v[12:15], v[96:99], v[220:223], v[12:15]
	v_mfma_f32_16x16x32_bf16 v[44:47], v[176:179], v[220:223], v[44:47]
	v_mfma_f32_16x16x32_bf16 v[4:7], v[96:99], v[228:231], v[4:7]
	v_mfma_f32_16x16x32_bf16 v[36:39], v[176:179], v[228:231], v[36:39]
	s_barrier
; #define PG8_STAGE(bufoff, gbase, voff) do { _Pragma("unroll") for (int _i = 0; _i < 2; ++_i) \
;         __builtin_amdgcn_global_load_lds((const unsigned*)((const char*)(gbase) + (voff)[_i]), (LAS unsigned*)(lds + (bufoff) + ldsw + _i * 8192), 16, 0, 0); } while (0)
; #define PG8_STAGE_A(bufoff, ptr, half, rev) do { if (REVA && (rev)) { const char* _p = (ptr) - ((half) ? hstepA : 0); PG8_STAGE(bufoff, _p, voffAr); } else { const char* _p = (ptr) + ((half) ? hstepA : 0); PG8_STAGE(bufoff, _p, voffA); } } while (0)
; #define PG8_LDA(dst, b, h) do { _Pragma("unroll") for (int m = 0; m < 4; ++m) _Pragma("unroll") for (int k = 0; k < 2; ++k) dst[m][k] = *(const LAS bf16x8*)(lds + PG8_SA(b, h) + aoff + m * 2048 + k * 1024); } while (0)
; #define PG8_LDB(dst, b, h) do { _Pragma("unroll") for (int n = 0; n < 2; ++n) _Pragma("unroll") for (int k = 0; k < 2; ++k) dst[n][k] = *(const LAS bf16x8*)(lds + PG8_SB(b, h) + boff + n * 2048 + k * 1024); } while (0)
; #define PG8_MMA(ai, bj, At, Bt) do { __builtin_amdgcn_s_setprio(1); _Pragma("unroll") for (int m = 0; m < 4; ++m) _Pragma("unroll") for (int n = 0; n < 2; ++n) _Pragma("unroll") for (int k = 0; k < 2; ++k) \
;         acc[ai][bj][m][n] = __builtin_amdgcn_mfma_f32_16x16x32_bf16(Bt[n][k], At[m][k], acc[ai][bj][m][n], 0, 0, 0); __builtin_amdgcn_s_setprio(0); } while (0)
; #define PG8_WAIT_V(n) asm volatile("s_waitcnt vmcnt(" #n ")" ::: "memory")
; #define PG8_WAIT_L(n) asm volatile("s_waitcnt lgkmcnt(" #n ")" ::: "memory")
; #define PG8_BAR __builtin_amdgcn_s_barrier()
; #define PG8_SCHED __builtin_amdgcn_sched_barrier(0)
;     ...
;             PG8_STAGE(PG8_SB(0, 1), b2 + hb2, voffB);
;             PG8_WAIT_V(6); PG8_BAR; PG8_MMA(1, 1, At, B1); PG8_BAR;
;             PG8_LDB(B0, 1, 0); PG8_SCHED; PG8_LDA(At, 1, 0); PG8_STAGE_A(PG8_SA(0, 1), a2, 1, r2);
;             PG8_WAIT_L(8); PG8_BAR; PG8_WAIT_L(0); PG8_MMA(0, 0, At, B0); PG8_BAR; PG8_SCHED;
;             PG8_LDB(B1, 1, 1); PG8_STAGE(PG8_SB(1, 0), b3, voffB);
;             PG8_BAR; PG8_WAIT_L(0); PG8_MMA(0, 1, At, B1); PG8_BAR;
;             PG8_LDA(At, 1, 1); PG8_STAGE_A(PG8_SA(1, 0), a3, 0, r3);
;             PG8_BAR; PG8_WAIT_L(0); PG8_MMA(1, 0, At, B0); PG8_BAR; PG8_SCHED;
	s_add_u32 s10, s14, 0x80000
	s_addc_u32 s11, s15, 0
	s_add_i32 s27, s37, s90
	v_lshl_add_u64 v[92:93], s[10:11], 0, v[160:161]
	s_mov_b32 m0, s27
	s_nop 0
	global_load_lds_dwordx4 v[92:93], off
	v_lshl_add_u64 v[92:93], s[10:11], 0, v[140:141]
	s_add_i32 m0, s27, 0x2000
	s_nop 0
	global_load_lds_dwordx4 v[92:93], off
	v_add_u32_e32 v176, 0x18000, v156
	ds_read_b128 v[92:95], v176
	ds_read_b128 v[96:99], v176 offset:1024
	ds_read_b128 v[172:175], v176 offset:2048
	ds_read_b128 v[176:179], v176 offset:3072
	s_waitcnt vmcnt(10)
	s_barrier
	v_mfma_f32_16x16x32_bf16 v[56:59], v[232:235], v[180:183], v[56:59]
	v_mfma_f32_16x16x32_bf16 v[24:27], v[240:243], v[180:183], v[24:27]
	v_mfma_f32_16x16x32_bf16 v[48:51], v[232:235], v[208:211], v[48:51]
	v_mfma_f32_16x16x32_bf16 v[16:19], v[240:243], v[208:211], v[16:19]
	v_mfma_f32_16x16x32_bf16 v[40:43], v[232:235], v[216:219], v[40:43]
	v_mfma_f32_16x16x32_bf16 v[8:11], v[240:243], v[216:219], v[8:11]
	v_mfma_f32_16x16x32_bf16 v[32:35], v[232:235], v[224:227], v[32:35]
	v_mfma_f32_16x16x32_bf16 v[0:3], v[240:243], v[224:227], v[0:3]
	v_mfma_f32_16x16x32_bf16 v[56:59], v[236:239], v[204:207], v[56:59]
	v_mfma_f32_16x16x32_bf16 v[24:27], v[244:247], v[204:207], v[24:27]
	v_mfma_f32_16x16x32_bf16 v[48:51], v[236:239], v[212:215], v[48:51]
	v_mfma_f32_16x16x32_bf16 v[16:19], v[244:247], v[212:215], v[16:19]
	v_mfma_f32_16x16x32_bf16 v[40:43], v[236:239], v[220:223], v[40:43]
	v_mfma_f32_16x16x32_bf16 v[8:11], v[244:247], v[220:223], v[8:11]
	v_mfma_f32_16x16x32_bf16 v[32:35], v[236:239], v[228:231], v[32:35]
	v_mfma_f32_16x16x32_bf16 v[0:3], v[244:247], v[228:231], v[0:3]
	s_add_i32 s27, 0, 0x18000
	s_barrier
	s_add_u32 s10, s20, 0x80000
	s_addc_u32 s11, s21, 0
	s_mov_b32 m0, s93
	v_lshl_add_u64 v[190:191], s[10:11], 0, v[160:161]
	ds_read_b128 v[180:183], v171 offset:32768
	ds_read_b128 v[204:207], v171 offset:33792
	ds_read_b128 v[208:211], v171 offset:34816
	ds_read_b128 v[212:215], v171 offset:35840
	ds_read_b128 v[216:219], v171 offset:36864
	ds_read_b128 v[220:223], v171 offset:37888
	ds_read_b128 v[224:227], v171 offset:38912
	ds_read_b128 v[228:231], v171 offset:39936
	global_load_lds_dwordx4 v[190:191], off
	v_lshl_add_u64 v[190:191], s[10:11], 0, v[140:141]
	s_mov_b32 m0, s94
	s_nop 0
	global_load_lds_dwordx4 v[190:191], off
	s_waitcnt lgkmcnt(8)
	s_waitcnt vmcnt(10)
	s_barrier
	s_waitcnt lgkmcnt(0)
	s_waitcnt lgkmcnt(0)
	v_mfma_f32_16x16x32_bf16 v[104:107], v[92:95], v[180:183], v[104:107]
	v_mfma_f32_16x16x32_bf16 v[136:139], v[172:175], v[180:183], v[136:139]
	v_mfma_f32_16x16x32_bf16 v[84:87], v[92:95], v[208:211], v[84:87]
	v_mfma_f32_16x16x32_bf16 v[128:131], v[172:175], v[208:211], v[128:131]
	v_mfma_f32_16x16x32_bf16 v[76:79], v[92:95], v[216:219], v[76:79]
	v_mfma_f32_16x16x32_bf16 v[120:123], v[172:175], v[216:219], v[120:123]
	v_mfma_f32_16x16x32_bf16 v[68:71], v[92:95], v[224:227], v[68:71]
	v_mfma_f32_16x16x32_bf16 v[112:115], v[172:175], v[224:227], v[112:115]
	v_mfma_f32_16x16x32_bf16 v[104:107], v[96:99], v[204:207], v[104:107]
	v_mfma_f32_16x16x32_bf16 v[136:139], v[176:179], v[204:207], v[136:139]
	v_mfma_f32_16x16x32_bf16 v[84:87], v[96:99], v[212:215], v[84:87]
	v_mfma_f32_16x16x32_bf16 v[128:131], v[176:179], v[212:215], v[128:131]
	v_mfma_f32_16x16x32_bf16 v[76:79], v[96:99], v[220:223], v[76:79]
	v_mfma_f32_16x16x32_bf16 v[120:123], v[176:179], v[220:223], v[120:123]
	v_mfma_f32_16x16x32_bf16 v[68:71], v[96:99], v[228:231], v[68:71]
	v_mfma_f32_16x16x32_bf16 v[112:115], v[176:179], v[228:231], v[112:115]
	s_barrier
	s_add_i32 s20, 0, 0x1c000
	s_add_i32 s10, s27, s90
	v_add_u32_e32 v190, s20, v156
	v_lshl_add_u64 v[154:155], v[154:155], 0, s[28:29]
	s_mov_b32 m0, s10
	ds_read_b128 v[232:235], v190
	ds_read_b128 v[236:239], v190 offset:1024
	ds_read_b128 v[240:243], v190 offset:2048
	ds_read_b128 v[244:247], v190 offset:3072
	global_load_lds_dwordx4 v[154:155], off
	v_lshl_add_u64 v[154:155], v[184:185], 0, s[28:29]
	s_add_i32 m0, s10, 0x2000
	s_nop 0
	global_load_lds_dwordx4 v[154:155], off
	s_waitcnt vmcnt(10)
	s_barrier
	s_waitcnt lgkmcnt(0)
	s_waitcnt lgkmcnt(0)
	v_mfma_f32_16x16x32_bf16 v[132:135], v[232:235], v[180:183], v[132:135]
	v_mfma_f32_16x16x32_bf16 v[100:103], v[240:243], v[180:183], v[100:103]
	v_mfma_f32_16x16x32_bf16 v[124:127], v[232:235], v[208:211], v[124:127]
	v_mfma_f32_16x16x32_bf16 v[80:83], v[240:243], v[208:211], v[80:83]
	v_mfma_f32_16x16x32_bf16 v[116:119], v[232:235], v[216:219], v[116:119]
	v_mfma_f32_16x16x32_bf16 v[72:75], v[240:243], v[216:219], v[72:75]
	v_mfma_f32_16x16x32_bf16 v[108:111], v[232:235], v[224:227], v[108:111]
	v_mfma_f32_16x16x32_bf16 v[64:67], v[240:243], v[224:227], v[64:67]
	v_mfma_f32_16x16x32_bf16 v[132:135], v[236:239], v[204:207], v[132:135]
	v_mfma_f32_16x16x32_bf16 v[100:103], v[244:247], v[204:207], v[100:103]
	v_mfma_f32_16x16x32_bf16 v[124:127], v[236:239], v[212:215], v[124:127]
	v_mfma_f32_16x16x32_bf16 v[80:83], v[244:247], v[212:215], v[80:83]
	v_mfma_f32_16x16x32_bf16 v[116:119], v[236:239], v[220:223], v[116:119]
	v_mfma_f32_16x16x32_bf16 v[72:75], v[244:247], v[220:223], v[72:75]
	v_mfma_f32_16x16x32_bf16 v[108:111], v[236:239], v[228:231], v[108:111]
	v_mfma_f32_16x16x32_bf16 v[64:67], v[244:247], v[228:231], v[64:67]
	s_mov_b32 m0, s95
	v_lshl_add_u64 v[154:155], s[16:17], 0, v[160:161]
	s_barrier
	ds_read_b128 v[180:183], v171 offset:49152
	ds_read_b128 v[204:207], v171 offset:50176
	ds_read_b128 v[208:211], v171 offset:51200
	ds_read_b128 v[212:215], v171 offset:52224
	ds_read_b128 v[216:219], v171 offset:53248
	ds_read_b128 v[220:223], v171 offset:54272
	ds_read_b128 v[224:227], v171 offset:55296
	ds_read_b128 v[228:231], v171 offset:56320
	global_load_lds_dwordx4 v[154:155], off
	v_lshl_add_u64 v[154:155], s[16:17], 0, v[140:141]
	s_mov_b32 m0, s96
	s_nop 0
	global_load_lds_dwordx4 v[154:155], off
	s_waitcnt vmcnt(10)
	s_barrier
; #define PG8_STAGE(bufoff, gbase, voff) do { _Pragma("unroll") for (int _i = 0; _i < 2; ++_i) \
;         __builtin_amdgcn_global_load_lds((const unsigned*)((const char*)(gbase) + (voff)[_i]), (LAS unsigned*)(lds + (bufoff) + ldsw + _i * 8192), 16, 0, 0); } while (0)
; #define PG8_MMA(ai, bj, At, Bt) do { __builtin_amdgcn_s_setprio(1); _Pragma("unroll") for (int m = 0; m < 4; ++m) _Pragma("unroll") for (int n = 0; n < 2; ++n) _Pragma("unroll") for (int k = 0; k < 2; ++k) \
;         acc[ai][bj][m][n] = __builtin_amdgcn_mfma_f32_16x16x32_bf16(Bt[n][k], At[m][k], acc[ai][bj][m][n], 0, 0, 0); __builtin_amdgcn_s_setprio(0); } while (0)
; #define PG8_WAIT_V(n) asm volatile("s_waitcnt vmcnt(" #n ")" ::: "memory")
; #define PG8_WAIT_L(n) asm volatile("s_waitcnt lgkmcnt(" #n ")" ::: "memory")
; #define PG8_BAR __builtin_amdgcn_s_barrier()
; #define PG8_SCHED __builtin_amdgcn_sched_barrier(0)
;     ...
;             PG8_BAR; PG8_WAIT_L(0); PG8_MMA(1, 0, At, B0); PG8_BAR; PG8_SCHED;
;             PG8_STAGE(PG8_SB(1, 1), b3 + hb2, voffB);
;             PG8_WAIT_V(6); PG8_BAR; PG8_MMA(1, 1, At, B1); PG8_BAR;
;     __device__ __forceinline__ void operator()(const f32x4 (&acc)[2][2][4][2], const Unit& u, int wr, int wc, int fr, int fq, int lane) const {
;         const int ch = u.pn * 64 + wc * 16 + 4 * fq;
;         const f32x4 w0 = *(const f32x4*)(cw + ch), w1 = *(const f32x4*)(cw + 4096 + ch), w2 = *(const f32x4*)(cw + 8192 + ch);
; #pragma unroll
;         for (int ai = 0; ai < 2; ++ai) {
;             f32x4 z[4], up[4], dn[4];
; #pragma unroll
;             for (int m = 0; m < 4; ++m) {
;                 z[m] = acc[ai][0][m][1] * acc[ai][1][m][0];
; #pragma unroll
;                 for (int j = 0; j < 4; ++j) { up[m][j] = __int_as_float(__builtin_amdgcn_update_dpp(0, __float_as_int(z[m][j]), 0x121, 0xF, 0xF, false));
;                                               dn[m][j] = __int_as_float(__builtin_amdgcn_update_dpp(0, __float_as_int(z[m][j]), 0x12F, 0xF, 0xF, false)); }
;             }
	s_waitcnt lgkmcnt(0)
	s_waitcnt lgkmcnt(0)
	v_mfma_f32_16x16x32_bf16 v[28:31], v[92:95], v[180:183], v[28:31]
	v_mfma_f32_16x16x32_bf16 v[60:63], v[172:175], v[180:183], v[60:63]
	v_mfma_f32_16x16x32_bf16 v[20:23], v[92:95], v[208:211], v[20:23]
	v_mfma_f32_16x16x32_bf16 v[52:55], v[172:175], v[208:211], v[52:55]
	v_mfma_f32_16x16x32_bf16 v[12:15], v[92:95], v[216:219], v[12:15]
	v_mfma_f32_16x16x32_bf16 v[44:47], v[172:175], v[216:219], v[44:47]
	v_mfma_f32_16x16x32_bf16 v[4:7], v[92:95], v[224:227], v[4:7]
	v_mfma_f32_16x16x32_bf16 v[36:39], v[172:175], v[224:227], v[36:39]
	v_mfma_f32_16x16x32_bf16 v[28:31], v[96:99], v[204:207], v[28:31]
	v_mfma_f32_16x16x32_bf16 v[60:63], v[176:179], v[204:207], v[60:63]
	v_mfma_f32_16x16x32_bf16 v[20:23], v[96:99], v[212:215], v[20:23]
	v_mfma_f32_16x16x32_bf16 v[52:55], v[176:179], v[212:215], v[52:55]
	v_mfma_f32_16x16x32_bf16 v[12:15], v[96:99], v[220:223], v[12:15]
	v_mfma_f32_16x16x32_bf16 v[44:47], v[176:179], v[220:223], v[44:47]
	v_mfma_f32_16x16x32_bf16 v[4:7], v[96:99], v[228:231], v[4:7]
	v_mfma_f32_16x16x32_bf16 v[36:39], v[176:179], v[228:231], v[36:39]
	s_barrier
	s_add_u32 s10, s14, 0x80080
	s_addc_u32 s11, s15, 0
	s_add_i32 s14, s20, s90
	v_lshl_add_u64 v[92:93], s[10:11], 0, v[160:161]
	s_mov_b32 m0, s14
	s_nop 0
	global_load_lds_dwordx4 v[92:93], off
	v_lshl_add_u64 v[92:93], s[10:11], 0, v[140:141]
	s_add_i32 m0, s14, 0x2000
	s_nop 0
	global_load_lds_dwordx4 v[92:93], off
	v_add_u32_e32 v154, 0x10000, v156
	ds_read_b128 v[92:95], v154
	ds_read_b128 v[96:99], v154 offset:1024
	ds_read_b128 v[172:175], v154 offset:2048
	ds_read_b128 v[176:179], v154 offset:3072
	s_waitcnt vmcnt(10)
	s_barrier
	v_mfma_f32_16x16x32_bf16 v[56:59], v[232:235], v[180:183], v[56:59]
	v_mfma_f32_16x16x32_bf16 v[24:27], v[240:243], v[180:183], v[24:27]
	v_mfma_f32_16x16x32_bf16 v[48:51], v[232:235], v[208:211], v[48:51]
	v_mfma_f32_16x16x32_bf16 v[16:19], v[240:243], v[208:211], v[16:19]
	v_mfma_f32_16x16x32_bf16 v[40:43], v[232:235], v[216:219], v[40:43]
	v_mfma_f32_16x16x32_bf16 v[8:11], v[240:243], v[216:219], v[8:11]
	v_mfma_f32_16x16x32_bf16 v[32:35], v[232:235], v[224:227], v[32:35]
	v_mfma_f32_16x16x32_bf16 v[0:3], v[240:243], v[224:227], v[0:3]
	v_mfma_f32_16x16x32_bf16 v[56:59], v[236:239], v[204:207], v[56:59]
	v_mfma_f32_16x16x32_bf16 v[24:27], v[244:247], v[204:207], v[24:27]
	v_mfma_f32_16x16x32_bf16 v[48:51], v[236:239], v[212:215], v[48:51]
	v_mfma_f32_16x16x32_bf16 v[16:19], v[244:247], v[212:215], v[16:19]
	v_mfma_f32_16x16x32_bf16 v[40:43], v[236:239], v[220:223], v[40:43]
	v_mfma_f32_16x16x32_bf16 v[8:11], v[244:247], v[220:223], v[8:11]
	v_mfma_f32_16x16x32_bf16 v[32:35], v[236:239], v[228:231], v[32:35]
	v_mfma_f32_16x16x32_bf16 v[0:3], v[244:247], v[228:231], v[0:3]
	s_add_i32 s9, s9, 2
	s_add_u32 vcc_lo, vcc_lo, 0x100
	s_addc_u32 vcc_hi, vcc_hi, 0
	s_cmp_gt_u32 s9, 29
	s_barrier
	s_cbranch_scc0 .LBB0_234
	s_waitcnt lgkmcnt(0)
	s_nop 0
	v_lshl_or_b32 v154, s5, 6, v158
	v_ashrrev_i32_e32 v155, 31, v154
	v_lshlrev_b64 v[92:93], 2, v[154:155]
	v_lshl_add_u64 v[88:89], v[142:143], 0, v[92:93]
	v_lshl_add_u64 v[90:91], v[144:145], 0, v[92:93]
	global_load_dwordx4 v[96:99], v[88:89], off
	s_nop 0
	global_load_dwordx4 v[88:91], v[90:91], off
	v_lshl_add_u64 v[92:93], v[146:147], 0, v[92:93]
	global_load_dwordx4 v[92:95], v[92:93], off
	v_pk_mul_f32 v[134:135], v[138:139], v[134:135]
	v_mov_b32_e32 v172, v161
	v_mov_b32_e32 v174, v161
	v_mov_b32_e32 v173, v161
	v_mov_b32_dpp v172, v134 row_ror:1 row_mask:0xf bank_mask:0xf
	v_mov_b32_dpp v174, v135 row_ror:1 row_mask:0xf bank_mask:0xf
	v_mov_b32_e32 v175, v161
	v_pk_mul_f32 v[126:127], v[130:131], v[126:127]
	v_mov_b32_e32 v177, v161
	v_mov_b32_e32 v179, v161
	v_pk_mul_f32 v[116:117], v[120:121], v[116:117]
	v_cndmask_b32_e64 v120, v172, 0, s[42:43]
	v_cndmask_b32_e64 v121, v174, 0, s[42:43]
	v_mov_b32_dpp v173, v134 row_ror:15 row_mask:0xf bank_mask:0xf
	v_mov_b32_dpp v175, v135 row_ror:15 row_mask:0xf bank_mask:0xf
	v_mov_b32_dpp v177, v126 row_ror:15 row_mask:0xf bank_mask:0xf
	v_mov_b32_dpp v179, v127 row_ror:15 row_mask:0xf bank_mask:0xf
	v_pk_mul_f32 v[132:133], v[136:137], v[132:133]
	v_mov_b32_e32 v136, v161
	v_mov_b32_e32 v138, v161
	v_pk_mul_f32 v[118:119], v[122:123], v[118:119]
	v_cndmask_b32_e64 v122, v173, v177, s[44:45]
	v_cndmask_b32_e64 v123, v175, v179, s[44:45]
	v_mov_b32_dpp v136, v132 row_ror:1 row_mask:0xf bank_mask:0xf
	v_mov_b32_dpp v138, v133 row_ror:1 row_mask:0xf bank_mask:0xf
	v_mov_b32_e32 v137, v161
	v_mov_b32_e32 v139, v161
	v_pk_mul_f32 v[124:125], v[128:129], v[124:125]
	v_mov_b32_e32 v129, v161
	v_mov_b32_e32 v131, v161
	v_pk_mul_f32 v[108:109], v[112:113], v[108:109]
	v_cndmask_b32_e64 v112, v136, 0, s[42:43]
	v_cndmask_b32_e64 v113, v138, 0, s[42:43]
	v_mov_b32_dpp v137, v132 row_ror:15 row_mask:0xf bank_mask:0xf
	v_mov_b32_dpp v139, v133 row_ror:15 row_mask:0xf bank_mask:0xf
	v_mov_b32_dpp v129, v124 row_ror:15 row_mask:0xf bank_mask:0xf
	v_mov_b32_dpp v131, v125 row_ror:15 row_mask:0xf bank_mask:0xf
	v_pk_mul_f32 v[110:111], v[114:115], v[110:111]
	v_cndmask_b32_e64 v114, v137, v129, s[44:45]
	v_cndmask_b32_e64 v115, v139, v131, s[44:45]
	v_mov_b32_e32 v176, v161
	v_mov_b32_e32 v178, v161
	v_mov_b32_e32 v185, v161
	v_mov_b32_dpp v176, v126 row_ror:1 row_mask:0xf bank_mask:0xf
	v_mov_b32_dpp v178, v127 row_ror:1 row_mask:0xf bank_mask:0xf
	v_mov_b32_e32 v191, v161
	v_mov_b32_dpp v185, v118 row_ror:15 row_mask:0xf bank_mask:0xf
	v_mov_b32_e32 v128, v161
	v_mov_b32_dpp v191, v119 row_ror:15 row_mask:0xf bank_mask:0xf
	v_mov_b32_e32 v130, v161
	v_mov_b32_dpp v128, v124 row_ror:1 row_mask:0xf bank_mask:0xf
	v_mov_b32_e32 v181, v161
	v_mov_b32_dpp v130, v125 row_ror:1 row_mask:0xf bank_mask:0xf
	v_mov_b32_e32 v183, v161
	v_mov_b32_dpp v181, v116 row_ror:15 row_mask:0xf bank_mask:0xf
	v_mov_b32_e32 v184, v161
	v_mov_b32_dpp v183, v117 row_ror:15 row_mask:0xf bank_mask:0xf
	v_mov_b32_e32 v190, v161
	v_mov_b32_dpp v184, v118 row_ror:1 row_mask:0xf bank_mask:0xf
	v_mov_b32_e32 v209, v161
	v_mov_b32_dpp v190, v119 row_ror:1 row_mask:0xf bank_mask:0xf
	v_mov_b32_e32 v211, v161
	v_mov_b32_dpp v209, v110 row_ror:15 row_mask:0xf bank_mask:0xf
	v_mov_b32_e32 v180, v161
	v_mov_b32_dpp v211, v111 row_ror:15 row_mask:0xf bank_mask:0xf
	v_mov_b32_e32 v182, v161
	v_mov_b32_dpp v180, v116 row_ror:1 row_mask:0xf bank_mask:0xf
	v_mov_b32_e32 v205, v161
	v_mov_b32_dpp v182, v117 row_ror:1 row_mask:0xf bank_mask:0xf
	v_mov_b32_e32 v207, v161
	v_mov_b32_dpp v205, v108 row_ror:15 row_mask:0xf bank_mask:0xf
	v_mov_b32_e32 v208, v161
	v_mov_b32_dpp v207, v109 row_ror:15 row_mask:0xf bank_mask:0xf
	v_mov_b32_e32 v210, v161
	v_mov_b32_dpp v208, v110 row_ror:1 row_mask:0xf bank_mask:0xf
	v_mov_b32_e32 v204, v161
	s_waitcnt vmcnt(0)
; __device__ __forceinline__ unsigned cvt_pk_bf16(float lo, float hi) { unsigned r; asm volatile("v_cvt_pk_bf16_f32 %0, %1, %2" : "=v"(r) : "v"(lo), "v"(hi)); return r; }
; __device__ __forceinline__ float silu_f(float x) { return x * __builtin_amdgcn_rcpf(1.f + __expf(-x)); }
;     __device__ __forceinline__ void operator()(const f32x4 (&acc)[2][2][4][2], const Unit& u, int wr, int wc, int fr, int fq, int lane) const {
;     ...
;             for (int m = 0; m < 4; ++m) {
;                 f32x4 zp, zn;
; #pragma unroll
;                 for (int j = 0; j < 4; ++j) {
;                     zp[j] = (fr > 0) ? up[m][j] : (m > 0 ? up[m > 0 ? m - 1 : 0][j] : 0.f);
;                     zn[j] = (fr < 15) ? dn[m][j] : (m < 3 ? dn[m < 3 ? m + 1 : 3][j] : 0.f);
;                 }
;                 f32x4 y = w0 * zp + w1 * z[m] + w2 * zn;
;                 const f32x4 bg = acc[ai][0][m][0], g = acc[ai][1][m][1];
; #pragma unroll
;                 for (int j = 0; j < 4; ++j) y[j] = y[j] * bg[j] * silu_f(g[j]);
;                 wv[m].x = cvt_pk_bf16(y[0], y[1]); wv[m].y = cvt_pk_bf16(y[2], y[3]);
;             }
;             if (u.pm < 128) {
	v_pk_mul_f32 v[120:121], v[98:99], v[120:121]
	v_pk_mul_f32 v[112:113], v[96:97], v[112:113]
	v_pk_fma_f32 v[120:121], v[134:135], v[90:91], v[120:121]
	v_mul_f32_e32 v134, 0xbfb8aa3b, v100
	v_exp_f32_e32 v134, v134
	v_pk_fma_f32 v[120:121], v[94:95], v[122:123], v[120:121]
	v_mov_b32_e32 v122, v100
	v_mul_f32_e32 v100, 0xbfb8aa3b, v101
	v_exp_f32_e32 v100, v100
	v_pk_fma_f32 v[112:113], v[132:133], v[88:89], v[112:113]
	v_mov_b32_e32 v123, v104
	v_pk_fma_f32 v[112:113], v[92:93], v[114:115], v[112:113]
	v_add_f32_e32 v114, 1.0, v134
	v_rcp_f32_e32 v114, v114
	v_add_f32_e32 v100, 1.0, v100
	v_mov_b32_e32 v115, v112
	v_rcp_f32_e32 v112, v100
	v_pk_mul_f32 v[114:115], v[122:123], v[114:115]
	v_mul_f32_e32 v100, 0xbfb8aa3b, v102
	v_mov_b32_e32 v104, v101
	v_mul_f32_e32 v114, v114, v115
	v_exp_f32_e32 v115, v100
	v_pk_mul_f32 v[100:101], v[104:105], v[112:113]
	v_mov_b32_e32 v104, v102
	v_mul_f32_e32 v112, v100, v101
	v_mul_f32_e32 v101, 0xbfb8aa3b, v103
	v_exp_f32_e32 v113, v101
	v_add_f32_e32 v100, 1.0, v115
	v_rcp_f32_e32 v100, v100
	v_mov_b32_e32 v101, v120
	v_add_f32_e32 v102, 1.0, v113
	v_rcp_f32_e32 v120, v102
	v_mov_b32_e32 v105, v106
	v_pk_mul_f32 v[100:101], v[104:105], v[100:101]
	v_mov_b32_e32 v106, v103
	v_mul_f32_e32 v102, v100, v101
	v_pk_mul_f32 v[100:101], v[106:107], v[120:121]
	v_cndmask_b32_e64 v106, v176, v172, s[42:43]
	v_cndmask_b32_e64 v107, v178, v174, s[42:43]
	v_pk_mul_f32 v[106:107], v[98:99], v[106:107]
	v_mul_f32_e32 v101, v100, v101
	v_cvt_pk_bf16_f32 v100, v114, v112
	v_cndmask_b32_e64 v112, v177, v185, s[44:45]
	v_cndmask_b32_e64 v113, v179, v191, s[44:45]
	v_pk_fma_f32 v[106:107], v[126:127], v[90:91], v[106:107]
	v_mul_f32_e32 v114, 0xbfb8aa3b, v80
	v_exp_f32_e32 v114, v114
	v_pk_fma_f32 v[106:107], v[94:95], v[112:113], v[106:107]
	v_mov_b32_e32 v112, v80
	v_mul_f32_e32 v80, 0xbfb8aa3b, v81
	v_cvt_pk_bf16_f32 v101, v102, v101
	v_cndmask_b32_e64 v102, v128, v136, s[42:43]
	v_cndmask_b32_e64 v103, v130, v138, s[42:43]
	v_exp_f32_e32 v80, v80
	v_pk_mul_f32 v[102:103], v[96:97], v[102:103]
	v_cndmask_b32_e64 v104, v129, v181, s[44:45]
	v_cndmask_b32_e64 v105, v131, v183, s[44:45]
	v_pk_fma_f32 v[102:103], v[124:125], v[88:89], v[102:103]
	v_add_f32_e32 v80, 1.0, v80
	v_pk_fma_f32 v[102:103], v[92:93], v[104:105], v[102:103]
	v_add_f32_e32 v104, 1.0, v114
	v_rcp_f32_e32 v104, v104
	v_mov_b32_e32 v105, v102
	v_rcp_f32_e32 v102, v80
	v_mov_b32_e32 v113, v84
	v_pk_mul_f32 v[104:105], v[112:113], v[104:105]
	v_mul_f32_e32 v80, 0xbfb8aa3b, v82
	v_mov_b32_e32 v84, v81
	v_mul_f32_e32 v104, v104, v105
	v_exp_f32_e32 v105, v80
	v_pk_mul_f32 v[80:81], v[84:85], v[102:103]
	v_mov_b32_e32 v84, v82
	v_mul_f32_e32 v102, v80, v81
	v_mul_f32_e32 v81, 0xbfb8aa3b, v83
	v_exp_f32_e32 v103, v81
	v_add_f32_e32 v80, 1.0, v105
	v_rcp_f32_e32 v80, v80
	v_mov_b32_e32 v81, v106
	v_add_f32_e32 v82, 1.0, v103
	v_rcp_f32_e32 v106, v82
	v_mov_b32_e32 v85, v86
	v_pk_mul_f32 v[80:81], v[84:85], v[80:81]
	v_mov_b32_e32 v86, v83
	v_mul_f32_e32 v82, v80, v81
	v_pk_mul_f32 v[80:81], v[86:87], v[106:107]
	v_cndmask_b32_e64 v86, v184, v176, s[42:43]
	v_cndmask_b32_e64 v87, v190, v178, s[42:43]
	v_pk_mul_f32 v[86:87], v[98:99], v[86:87]
	v_mul_f32_e32 v81, v80, v81
	v_cvt_pk_bf16_f32 v80, v104, v102
	v_cndmask_b32_e64 v102, v185, v209, s[44:45]
	v_cndmask_b32_e64 v103, v191, v211, s[44:45]
	v_pk_fma_f32 v[86:87], v[118:119], v[90:91], v[86:87]
	v_mul_f32_e32 v104, 0xbfb8aa3b, v72
	v_exp_f32_e32 v104, v104
	v_pk_fma_f32 v[86:87], v[94:95], v[102:103], v[86:87]
	v_mov_b32_e32 v102, v72
	v_mul_f32_e32 v72, 0xbfb8aa3b, v73
	v_cvt_pk_bf16_f32 v81, v82, v81
	v_cndmask_b32_e64 v82, v180, v128, s[42:43]
	v_cndmask_b32_e64 v83, v182, v130, s[42:43]
	v_exp_f32_e32 v72, v72
	v_pk_mul_f32 v[82:83], v[96:97], v[82:83]
	v_cndmask_b32_e64 v84, v181, v205, s[44:45]
	v_cndmask_b32_e64 v85, v183, v207, s[44:45]
	v_pk_fma_f32 v[82:83], v[116:117], v[88:89], v[82:83]
	v_add_f32_e32 v72, 1.0, v72
	v_pk_fma_f32 v[82:83], v[92:93], v[84:85], v[82:83]
	v_add_f32_e32 v84, 1.0, v104
	v_rcp_f32_e32 v84, v84
	v_mov_b32_e32 v85, v82
	v_rcp_f32_e32 v82, v72
	v_mov_b32_e32 v103, v76
	v_pk_mul_f32 v[84:85], v[102:103], v[84:85]
	v_mul_f32_e32 v72, 0xbfb8aa3b, v74
	v_mov_b32_e32 v76, v73
	v_mul_f32_e32 v84, v84, v85
	v_exp_f32_e32 v85, v72
	v_pk_mul_f32 v[72:73], v[76:77], v[82:83]
	v_mov_b32_e32 v76, v74
	v_mul_f32_e32 v82, v72, v73
	v_mul_f32_e32 v73, 0xbfb8aa3b, v75
	v_exp_f32_e32 v83, v73
	v_add_f32_e32 v72, 1.0, v85
	v_rcp_f32_e32 v72, v72
	v_mov_b32_e32 v73, v86
	v_add_f32_e32 v74, 1.0, v83
	v_rcp_f32_e32 v86, v74
	v_mov_b32_e32 v77, v78
	v_mov_b32_dpp v210, v111 row_ror:1 row_mask:0xf bank_mask:0xf
	v_pk_mul_f32 v[72:73], v[76:77], v[72:73]
	v_mov_b32_e32 v78, v75
	v_mul_f32_e32 v74, v72, v73
	v_pk_mul_f32 v[72:73], v[78:79], v[86:87]
	v_cndmask_b32_e64 v78, v208, v184, s[42:43]
	v_cndmask_b32_e64 v79, v210, v190, s[42:43]
	v_pk_mul_f32 v[78:79], v[98:99], v[78:79]
	v_mov_b32_e32 v206, v161
	v_mul_f32_e32 v73, v72, v73
	v_cvt_pk_bf16_f32 v72, v84, v82
	v_cndmask_b32_e64 v82, v209, 0, s[44:45]
	v_cndmask_b32_e64 v83, v211, 0, s[44:45]
	v_pk_fma_f32 v[78:79], v[110:111], v[90:91], v[78:79]
	v_mul_f32_e32 v84, 0xbfb8aa3b, v64
	v_mov_b32_dpp v204, v108 row_ror:1 row_mask:0xf bank_mask:0xf
	v_mov_b32_dpp v206, v109 row_ror:1 row_mask:0xf bank_mask:0xf
	v_exp_f32_e32 v84, v84
	v_pk_fma_f32 v[78:79], v[94:95], v[82:83], v[78:79]
	v_mov_b32_e32 v82, v64
	v_mul_f32_e32 v64, 0xbfb8aa3b, v65
	v_cvt_pk_bf16_f32 v73, v74, v73
	v_cndmask_b32_e64 v74, v204, v180, s[42:43]
	v_cndmask_b32_e64 v75, v206, v182, s[42:43]
	v_exp_f32_e32 v64, v64
	v_pk_mul_f32 v[74:75], v[96:97], v[74:75]
	v_cndmask_b32_e64 v76, v205, 0, s[44:45]
	v_cndmask_b32_e64 v77, v207, 0, s[44:45]
	v_pk_fma_f32 v[74:75], v[108:109], v[88:89], v[74:75]
	v_add_f32_e32 v64, 1.0, v64
	v_pk_fma_f32 v[74:75], v[92:93], v[76:77], v[74:75]
	v_add_f32_e32 v76, 1.0, v84
	v_rcp_f32_e32 v76, v76
	v_mov_b32_e32 v77, v74
	v_rcp_f32_e32 v74, v64
	v_mov_b32_e32 v83, v68
	v_pk_mul_f32 v[76:77], v[82:83], v[76:77]
	v_mul_f32_e32 v64, 0xbfb8aa3b, v66
	v_mov_b32_e32 v68, v65
	v_mul_f32_e32 v76, v76, v77
	v_exp_f32_e32 v77, v64
	v_pk_mul_f32 v[64:65], v[68:69], v[74:75]
	v_mov_b32_e32 v68, v66
	v_mul_f32_e32 v74, v64, v65
	v_mul_f32_e32 v65, 0xbfb8aa3b, v67
	v_exp_f32_e32 v75, v65
	v_add_f32_e32 v64, 1.0, v77
	v_rcp_f32_e32 v64, v64
	v_mov_b32_e32 v65, v78
	v_add_f32_e32 v66, 1.0, v75
	v_rcp_f32_e32 v78, v66
	s_cmpk_gt_i32 s36, 0x7f
	v_mov_b32_e32 v69, v70
	s_cselect_b64 s[38:39], -1, 0
	s_lshl_b32 s3, s36, 2
	v_pk_mul_f32 v[64:65], v[68:69], v[64:65]
	v_mov_b32_e32 v70, v67
	s_add_i32 s3, s4, s3
	v_mul_f32_e32 v68, v64, v65
	v_pk_mul_f32 v[64:65], v[70:71], v[78:79]
	s_and_b64 vcc, exec, s[38:39]
	v_mul_f32_e32 v64, v64, v65
	v_cvt_pk_bf16_f32 v66, v76, v74
	v_cvt_pk_bf16_f32 v67, v68, v64
	s_cbranch_vccz .LBB0_241
;     __device__ __forceinline__ void operator()(const f32x4 (&acc)[2][2][4][2], const Unit& u, int wr, int wc, int fr, int fq, int lane) const {
;     ...
;                 const int gidx = (u.pm - 128) * 4 + ai * 2 + wr, b = gidx / 5, g5 = gidx - b * 5, t0 = 62 * g5 - 1;
;                 bf16_t* p = O + ((size_t)(TL + b * 256 + t0 + fr)) * 4096 + ch;
; #pragma unroll
;                 for (int m = 0; m < 4; ++m) { const int i2 = m * 16 + fr; if (i2 >= 1 && i2 <= 62 && t0 + i2 < 256) *(u32x2*)(p + (size_t)(m * 16) * 4096) = wv[m]; }
	s_mul_hi_i32 s5, s3, 0x66666667
	s_lshr_b32 s6, s5, 31
	s_ashr_i32 s5, s5, 1
	s_add_i32 s6, s5, s6
	s_mul_i32 s5, s6, -5
	s_add_i32 s5, s5, s3
	s_mul_i32 s5, s5, 62
	s_lshl_b32 s6, s6, 8
	s_add_i32 s6, s5, s6
	v_add_u32_e32 v64, s6, v170
	v_ashrrev_i32_e32 v65, 31, v64
	v_lshlrev_b64 v[68:69], 13, v[64:65]
	v_lshl_add_u64 v[64:65], s[24:25], 0, v[68:69]
	v_cmp_le_i32_e32 vcc, s5, v157
	v_lshl_add_u64 v[64:65], v[154:155], 1, v[64:65]
	s_and_b64 s[6:7], s[46:47], vcc
	s_and_saveexec_b64 s[14:15], s[6:7]
	s_cbranch_execnz .LBB0_256
	s_or_b64 exec, exec, s[14:15]
	v_cmp_le_i32_e32 vcc, s5, v159
	s_and_saveexec_b64 s[14:15], vcc
	s_cbranch_execnz .LBB0_257

; #define PG8_STAGE(bufoff, gbase, voff) do { _Pragma("unroll") for (int _i = 0; _i < 2; ++_i) \
;         __builtin_amdgcn_global_load_lds((const unsigned*)((const char*)(gbase) + (voff)[_i]), (LAS unsigned*)(lds + (bufoff) + ldsw + _i * 8192), 16, 0, 0); } while (0)
; #define PG8_STAGE_A(bufoff, ptr, half, rev) do { if (REVA && (rev)) { const char* _p = (ptr) - ((half) ? hstepA : 0); PG8_STAGE(bufoff, _p, voffAr); } else { const char* _p = (ptr) + ((half) ? hstepA : 0); PG8_STAGE(bufoff, _p, voffA); } } while (0)
; #define PG8_LDA(dst, b, h) do { _Pragma("unroll") for (int m = 0; m < 4; ++m) _Pragma("unroll") for (int k = 0; k < 2; ++k) dst[m][k] = *(const LAS bf16x8*)(lds + PG8_SA(b, h) + aoff + m * 2048 + k * 1024); } while (0)
; #define PG8_LDB(dst, b, h) do { _Pragma("unroll") for (int n = 0; n < 2; ++n) _Pragma("unroll") for (int k = 0; k < 2; ++k) dst[n][k] = *(const LAS bf16x8*)(lds + PG8_SB(b, h) + boff + n * 2048 + k * 1024); } while (0)
; #define PG8_MMA(ai, bj, At, Bt) do { __builtin_amdgcn_s_setprio(1); _Pragma("unroll") for (int m = 0; m < 4; ++m) _Pragma("unroll") for (int n = 0; n < 2; ++n) _Pragma("unroll") for (int k = 0; k < 2; ++k) \
;         acc[ai][bj][m][n] = __builtin_amdgcn_mfma_f32_16x16x32_bf16(Bt[n][k], At[m][k], acc[ai][bj][m][n], 0, 0, 0); __builtin_amdgcn_s_setprio(0); } while (0)
; #define PG8_WAIT_L(n) asm volatile("s_waitcnt lgkmcnt(" #n ")" ::: "memory")
; #define PG8_BAR __builtin_amdgcn_s_barrier()
; #define PG8_SCHED __builtin_amdgcn_sched_barrier(0)
;     ...
;             PG8_LDB(B0, 0, 0); PG8_SCHED; PG8_LDA(At, 0, 0); PG8_STAGE_A(PG8_SA(1, 1), a1, 1, r1);
;             PG8_WAIT_L(8); PG8_BAR; PG8_WAIT_L(0); PG8_MMA(0, 0, At, B0); PG8_BAR; PG8_SCHED;
;             PG8_LDB(B1, 0, 1); PG8_STAGE(PG8_SB(0, 0), b2, voffB);
;             PG8_BAR; PG8_WAIT_L(0); PG8_MMA(0, 1, At, B1); PG8_BAR;
;             PG8_LDA(At, 0, 1); PG8_STAGE_A(PG8_SA(0, 0), a2, 0, r2);
;             PG8_BAR; PG8_WAIT_L(0); PG8_MMA(1, 0, At, B0); PG8_BAR; PG8_SCHED;
.LBB0_335:
	s_add_u32 s10, s44, s46
	s_addc_u32 s11, s45, s47
	s_add_u32 s16, s10, 0x100
	s_addc_u32 s17, s11, 0
	s_add_u32 s10, s10, 0x180
	s_addc_u32 s11, s11, 0
	s_add_u32 s14, s27, s46
	s_addc_u32 s15, s91, s47
	s_add_i32 s93, 0, 0x10000
	s_cmpk_eq_i32 s46, 0x1f00
	s_cselect_b32 s15, s39, s15
	s_cselect_b32 s14, s38, s14
	s_cselect_b32 s21, s37, s17
	s_cselect_b32 s20, s36, s16
	s_cselect_b32 s17, s9, s11
	s_cselect_b32 s16, s3, s10
	v_lshl_add_u64 v[154:155], v[128:129], 0, s[46:47]
	s_add_i32 m0, s1, 0xc000
	ds_read_b128 v[172:175], v158
	ds_read_b128 v[176:179], v158 offset:1024
	ds_read_b128 v[180:183], v158 offset:2048
	ds_read_b128 v[204:207], v158 offset:3072
	ds_read_b128 v[208:211], v158 offset:4096
	ds_read_b128 v[212:215], v158 offset:5120
	ds_read_b128 v[216:219], v158 offset:6144
	ds_read_b128 v[220:223], v158 offset:7168
	global_load_lds_dwordx4 v[154:155], off
	v_lshl_add_u64 v[154:155], v[130:131], 0, s[46:47]
	s_add_i32 m0, s1, 0xe000
	s_nop 0
	global_load_lds_dwordx4 v[154:155], off
	s_waitcnt lgkmcnt(8)
	s_waitcnt vmcnt(10)
	s_barrier
	s_waitcnt lgkmcnt(0)
	s_waitcnt lgkmcnt(0)
	v_mfma_f32_16x16x32_bf16 v[124:127], v[132:135], v[172:175], v[124:127]
	v_mfma_f32_16x16x32_bf16 v[120:123], v[140:143], v[172:175], v[120:123]
	v_mfma_f32_16x16x32_bf16 v[116:119], v[132:135], v[180:183], v[116:119]
	v_mfma_f32_16x16x32_bf16 v[108:111], v[140:143], v[180:183], v[108:111]
	v_mfma_f32_16x16x32_bf16 v[92:95], v[132:135], v[208:211], v[92:95]
	v_mfma_f32_16x16x32_bf16 v[88:91], v[140:143], v[208:211], v[88:91]
	v_mfma_f32_16x16x32_bf16 v[84:87], v[132:135], v[216:219], v[84:87]
	v_mfma_f32_16x16x32_bf16 v[76:79], v[140:143], v[216:219], v[76:79]
	v_mfma_f32_16x16x32_bf16 v[124:127], v[136:139], v[176:179], v[124:127]
	v_mfma_f32_16x16x32_bf16 v[120:123], v[168:171], v[176:179], v[120:123]
	v_mfma_f32_16x16x32_bf16 v[116:119], v[136:139], v[204:207], v[116:119]
	v_mfma_f32_16x16x32_bf16 v[108:111], v[168:171], v[204:207], v[108:111]
	v_mfma_f32_16x16x32_bf16 v[92:95], v[136:139], v[212:215], v[92:95]
	v_mfma_f32_16x16x32_bf16 v[88:91], v[168:171], v[212:215], v[88:91]
	v_mfma_f32_16x16x32_bf16 v[84:87], v[136:139], v[220:223], v[84:87]
	v_mfma_f32_16x16x32_bf16 v[76:79], v[168:171], v[220:223], v[76:79]
	s_barrier
	s_add_i32 s94, 0, 0x14000
	v_add_u32_e32 v154, s94, v157
	s_add_i32 s10, s93, s52
	ds_read_b128 v[224:227], v154
	ds_read_b128 v[228:231], v154 offset:1024
	ds_read_b128 v[232:235], v154 offset:2048
	ds_read_b128 v[236:239], v154 offset:3072
	v_lshl_add_u64 v[154:155], s[14:15], 0, v[146:147]
	s_mov_b32 m0, s10
	v_lshl_add_u64 v[184:185], s[14:15], 0, v[144:145]
	global_load_lds_dwordx4 v[154:155], off
	s_add_i32 m0, s10, 0x2000
	s_nop 0
	global_load_lds_dwordx4 v[184:185], off
	s_waitcnt vmcnt(10)
	s_barrier
	s_waitcnt lgkmcnt(0)
	s_waitcnt lgkmcnt(0)
	v_mfma_f32_16x16x32_bf16 v[112:115], v[224:227], v[172:175], v[112:115]
	v_mfma_f32_16x16x32_bf16 v[104:107], v[232:235], v[172:175], v[104:107]
	v_mfma_f32_16x16x32_bf16 v[100:103], v[224:227], v[180:183], v[100:103]
	v_mfma_f32_16x16x32_bf16 v[96:99], v[232:235], v[180:183], v[96:99]
	v_mfma_f32_16x16x32_bf16 v[80:83], v[224:227], v[208:211], v[80:83]
	v_mfma_f32_16x16x32_bf16 v[72:75], v[232:235], v[208:211], v[72:75]
	v_mfma_f32_16x16x32_bf16 v[68:71], v[224:227], v[216:219], v[68:71]
	v_mfma_f32_16x16x32_bf16 v[64:67], v[232:235], v[216:219], v[64:67]
	v_mfma_f32_16x16x32_bf16 v[112:115], v[228:231], v[176:179], v[112:115]
	v_mfma_f32_16x16x32_bf16 v[104:107], v[236:239], v[176:179], v[104:107]
	v_mfma_f32_16x16x32_bf16 v[100:103], v[228:231], v[204:207], v[100:103]
	v_mfma_f32_16x16x32_bf16 v[96:99], v[236:239], v[204:207], v[96:99]
	v_mfma_f32_16x16x32_bf16 v[80:83], v[228:231], v[212:215], v[80:83]
	v_mfma_f32_16x16x32_bf16 v[72:75], v[236:239], v[212:215], v[72:75]
	v_mfma_f32_16x16x32_bf16 v[68:71], v[228:231], v[220:223], v[68:71]
	v_mfma_f32_16x16x32_bf16 v[64:67], v[236:239], v[220:223], v[64:67]
	s_mov_b32 m0, s1
	v_lshl_add_u64 v[190:191], s[20:21], 0, v[146:147]
	s_barrier
	ds_read_b128 v[172:175], v158 offset:16384
	ds_read_b128 v[176:179], v158 offset:17408
	ds_read_b128 v[180:183], v158 offset:18432
	ds_read_b128 v[204:207], v158 offset:19456
	ds_read_b128 v[208:211], v158 offset:20480
	ds_read_b128 v[212:215], v158 offset:21504
	ds_read_b128 v[216:219], v158 offset:22528
	ds_read_b128 v[220:223], v158 offset:23552
	global_load_lds_dwordx4 v[190:191], off
	v_lshl_add_u64 v[190:191], s[20:21], 0, v[144:145]
	s_mov_b32 m0, s53
	s_nop 0
	global_load_lds_dwordx4 v[190:191], off
	s_waitcnt vmcnt(10)
	s_barrier
	s_waitcnt lgkmcnt(0)
	s_waitcnt lgkmcnt(0)
	v_mfma_f32_16x16x32_bf16 v[60:63], v[132:135], v[172:175], v[60:63]
	v_mfma_f32_16x16x32_bf16 v[56:59], v[140:143], v[172:175], v[56:59]
	v_mfma_f32_16x16x32_bf16 v[52:55], v[132:135], v[180:183], v[52:55]
	v_mfma_f32_16x16x32_bf16 v[44:47], v[140:143], v[180:183], v[44:47]
	v_mfma_f32_16x16x32_bf16 v[28:31], v[132:135], v[208:211], v[28:31]
	v_mfma_f32_16x16x32_bf16 v[24:27], v[140:143], v[208:211], v[24:27]
	v_mfma_f32_16x16x32_bf16 v[20:23], v[132:135], v[216:219], v[20:23]
	v_mfma_f32_16x16x32_bf16 v[12:15], v[140:143], v[216:219], v[12:15]
	v_mfma_f32_16x16x32_bf16 v[60:63], v[136:139], v[176:179], v[60:63]
	v_mfma_f32_16x16x32_bf16 v[56:59], v[168:171], v[176:179], v[56:59]
	v_mfma_f32_16x16x32_bf16 v[52:55], v[136:139], v[204:207], v[52:55]
	v_mfma_f32_16x16x32_bf16 v[44:47], v[168:171], v[204:207], v[44:47]
	v_mfma_f32_16x16x32_bf16 v[28:31], v[136:139], v[212:215], v[28:31]
	v_mfma_f32_16x16x32_bf16 v[24:27], v[168:171], v[212:215], v[24:27]
	v_mfma_f32_16x16x32_bf16 v[20:23], v[136:139], v[220:223], v[20:23]
	v_mfma_f32_16x16x32_bf16 v[12:15], v[168:171], v[220:223], v[12:15]
	s_barrier
; #define PG8_STAGE(bufoff, gbase, voff) do { _Pragma("unroll") for (int _i = 0; _i < 2; ++_i) \
;         __builtin_amdgcn_global_load_lds((const unsigned*)((const char*)(gbase) + (voff)[_i]), (LAS unsigned*)(lds + (bufoff) + ldsw + _i * 8192), 16, 0, 0); } while (0)
; #define PG8_STAGE_A(bufoff, ptr, half, rev) do { if (REVA && (rev)) { const char* _p = (ptr) - ((half) ? hstepA : 0); PG8_STAGE(bufoff, _p, voffAr); } else { const char* _p = (ptr) + ((half) ? hstepA : 0); PG8_STAGE(bufoff, _p, voffA); } } while (0)
; #define PG8_LDA(dst, b, h) do { _Pragma("unroll") for (int m = 0; m < 4; ++m) _Pragma("unroll") for (int k = 0; k < 2; ++k) dst[m][k] = *(const LAS bf16x8*)(lds + PG8_SA(b, h) + aoff + m * 2048 + k * 1024); } while (0)
; #define PG8_LDB(dst, b, h) do { _Pragma("unroll") for (int n = 0; n < 2; ++n) _Pragma("unroll") for (int k = 0; k < 2; ++k) dst[n][k] = *(const LAS bf16x8*)(lds + PG8_SB(b, h) + boff + n * 2048 + k * 1024); } while (0)
; #define PG8_MMA(ai, bj, At, Bt) do { __builtin_amdgcn_s_setprio(1); _Pragma("unroll") for (int m = 0; m < 4; ++m) _Pragma("unroll") for (int n = 0; n < 2; ++n) _Pragma("unroll") for (int k = 0; k < 2; ++k) \
;         acc[ai][bj][m][n] = __builtin_amdgcn_mfma_f32_16x16x32_bf16(Bt[n][k], At[m][k], acc[ai][bj][m][n], 0, 0, 0); __builtin_amdgcn_s_setprio(0); } while (0)
; #define PG8_WAIT_V(n) asm volatile("s_waitcnt vmcnt(" #n ")" ::: "memory")
; #define PG8_WAIT_L(n) asm volatile("s_waitcnt lgkmcnt(" #n ")" ::: "memory")
; #define PG8_BAR __builtin_amdgcn_s_barrier()
; #define PG8_SCHED __builtin_amdgcn_sched_barrier(0)
;     ...
;             PG8_STAGE(PG8_SB(0, 1), b2 + hb2, voffB);
;             PG8_WAIT_V(6); PG8_BAR; PG8_MMA(1, 1, At, B1); PG8_BAR;
;             PG8_LDB(B0, 1, 0); PG8_SCHED; PG8_LDA(At, 1, 0); PG8_STAGE_A(PG8_SA(0, 1), a2, 1, r2);
;             PG8_WAIT_L(8); PG8_BAR; PG8_WAIT_L(0); PG8_MMA(0, 0, At, B0); PG8_BAR; PG8_SCHED;
;             PG8_LDB(B1, 1, 1); PG8_STAGE(PG8_SB(1, 0), b3, voffB);
;             PG8_BAR; PG8_WAIT_L(0); PG8_MMA(0, 1, At, B1); PG8_BAR;
;             PG8_LDA(At, 1, 1); PG8_STAGE_A(PG8_SA(1, 0), a3, 0, r3);
	s_add_u32 s10, s14, 0x100000
	s_addc_u32 s11, s15, 0
	s_add_i32 s93, s94, s52
	v_lshl_add_u64 v[132:133], s[10:11], 0, v[146:147]
	s_mov_b32 m0, s93
	s_nop 0
	global_load_lds_dwordx4 v[132:133], off
	v_lshl_add_u64 v[132:133], s[10:11], 0, v[144:145]
	s_add_i32 m0, s93, 0x2000
	s_nop 0
	global_load_lds_dwordx4 v[132:133], off
	v_add_u32_e32 v159, 0x18000, v157
	ds_read_b128 v[132:135], v159
	ds_read_b128 v[136:139], v159 offset:1024
	ds_read_b128 v[140:143], v159 offset:2048
	ds_read_b128 v[168:171], v159 offset:3072
	s_waitcnt vmcnt(10)
	s_barrier
	v_mfma_f32_16x16x32_bf16 v[48:51], v[224:227], v[172:175], v[48:51]
	v_mfma_f32_16x16x32_bf16 v[40:43], v[232:235], v[172:175], v[40:43]
	v_mfma_f32_16x16x32_bf16 v[36:39], v[224:227], v[180:183], v[36:39]
	v_mfma_f32_16x16x32_bf16 v[32:35], v[232:235], v[180:183], v[32:35]
	v_mfma_f32_16x16x32_bf16 v[16:19], v[224:227], v[208:211], v[16:19]
	v_mfma_f32_16x16x32_bf16 v[8:11], v[232:235], v[208:211], v[8:11]
	v_mfma_f32_16x16x32_bf16 v[4:7], v[224:227], v[216:219], v[4:7]
	v_mfma_f32_16x16x32_bf16 v[0:3], v[232:235], v[216:219], v[0:3]
	v_mfma_f32_16x16x32_bf16 v[48:51], v[228:231], v[176:179], v[48:51]
	v_mfma_f32_16x16x32_bf16 v[40:43], v[236:239], v[176:179], v[40:43]
	v_mfma_f32_16x16x32_bf16 v[36:39], v[228:231], v[204:207], v[36:39]
	v_mfma_f32_16x16x32_bf16 v[32:35], v[236:239], v[204:207], v[32:35]
	v_mfma_f32_16x16x32_bf16 v[16:19], v[228:231], v[212:215], v[16:19]
	v_mfma_f32_16x16x32_bf16 v[8:11], v[236:239], v[212:215], v[8:11]
	v_mfma_f32_16x16x32_bf16 v[4:7], v[228:231], v[220:223], v[4:7]
	v_mfma_f32_16x16x32_bf16 v[0:3], v[236:239], v[220:223], v[0:3]
	s_add_i32 s93, 0, 0x18000
	s_barrier
	s_add_u32 s10, s20, 0x100000
	s_addc_u32 s11, s21, 0
	s_mov_b32 m0, s6
	v_lshl_add_u64 v[190:191], s[10:11], 0, v[146:147]
	ds_read_b128 v[172:175], v158 offset:32768
	ds_read_b128 v[176:179], v158 offset:33792
	ds_read_b128 v[180:183], v158 offset:34816
	ds_read_b128 v[204:207], v158 offset:35840
	ds_read_b128 v[208:211], v158 offset:36864
	ds_read_b128 v[212:215], v158 offset:37888
	ds_read_b128 v[216:219], v158 offset:38912
	ds_read_b128 v[220:223], v158 offset:39936
	global_load_lds_dwordx4 v[190:191], off
	v_lshl_add_u64 v[190:191], s[10:11], 0, v[144:145]
	s_mov_b32 m0, s7
	s_nop 0
	global_load_lds_dwordx4 v[190:191], off
	s_waitcnt lgkmcnt(8)
	s_waitcnt vmcnt(10)
	s_barrier
	s_waitcnt lgkmcnt(0)
	s_waitcnt lgkmcnt(0)
	v_mfma_f32_16x16x32_bf16 v[124:127], v[132:135], v[172:175], v[124:127]
	v_mfma_f32_16x16x32_bf16 v[120:123], v[140:143], v[172:175], v[120:123]
	v_mfma_f32_16x16x32_bf16 v[116:119], v[132:135], v[180:183], v[116:119]
	v_mfma_f32_16x16x32_bf16 v[108:111], v[140:143], v[180:183], v[108:111]
	v_mfma_f32_16x16x32_bf16 v[92:95], v[132:135], v[208:211], v[92:95]
	v_mfma_f32_16x16x32_bf16 v[88:91], v[140:143], v[208:211], v[88:91]
	v_mfma_f32_16x16x32_bf16 v[84:87], v[132:135], v[216:219], v[84:87]
	v_mfma_f32_16x16x32_bf16 v[76:79], v[140:143], v[216:219], v[76:79]
	v_mfma_f32_16x16x32_bf16 v[124:127], v[136:139], v[176:179], v[124:127]
	v_mfma_f32_16x16x32_bf16 v[120:123], v[168:171], v[176:179], v[120:123]
	v_mfma_f32_16x16x32_bf16 v[116:119], v[136:139], v[204:207], v[116:119]
	v_mfma_f32_16x16x32_bf16 v[108:111], v[168:171], v[204:207], v[108:111]
	v_mfma_f32_16x16x32_bf16 v[92:95], v[136:139], v[212:215], v[92:95]
	v_mfma_f32_16x16x32_bf16 v[88:91], v[168:171], v[212:215], v[88:91]
	v_mfma_f32_16x16x32_bf16 v[84:87], v[136:139], v[220:223], v[84:87]
	v_mfma_f32_16x16x32_bf16 v[76:79], v[168:171], v[220:223], v[76:79]
	s_barrier
	s_add_i32 s20, 0, 0x1c000
	s_add_i32 s10, s93, s52
	v_add_u32_e32 v159, s20, v157
	v_lshl_add_u64 v[154:155], v[154:155], 0, s[28:29]
	s_mov_b32 m0, s10
	ds_read_b128 v[224:227], v159
	ds_read_b128 v[228:231], v159 offset:1024
	ds_read_b128 v[232:235], v159 offset:2048
	ds_read_b128 v[236:239], v159 offset:3072
	global_load_lds_dwordx4 v[154:155], off
	v_lshl_add_u64 v[154:155], v[184:185], 0, s[28:29]
	s_add_i32 m0, s10, 0x2000
	s_nop 0
	global_load_lds_dwordx4 v[154:155], off
	s_waitcnt vmcnt(10)
	s_barrier
	s_waitcnt lgkmcnt(0)
	s_waitcnt lgkmcnt(0)
	v_mfma_f32_16x16x32_bf16 v[112:115], v[224:227], v[172:175], v[112:115]
	v_mfma_f32_16x16x32_bf16 v[104:107], v[232:235], v[172:175], v[104:107]
	v_mfma_f32_16x16x32_bf16 v[100:103], v[224:227], v[180:183], v[100:103]
	v_mfma_f32_16x16x32_bf16 v[96:99], v[232:235], v[180:183], v[96:99]
	v_mfma_f32_16x16x32_bf16 v[80:83], v[224:227], v[208:211], v[80:83]
	v_mfma_f32_16x16x32_bf16 v[72:75], v[232:235], v[208:211], v[72:75]
	v_mfma_f32_16x16x32_bf16 v[68:71], v[224:227], v[216:219], v[68:71]
	v_mfma_f32_16x16x32_bf16 v[64:67], v[232:235], v[216:219], v[64:67]
	v_mfma_f32_16x16x32_bf16 v[112:115], v[228:231], v[176:179], v[112:115]
	v_mfma_f32_16x16x32_bf16 v[104:107], v[236:239], v[176:179], v[104:107]
	v_mfma_f32_16x16x32_bf16 v[100:103], v[228:231], v[204:207], v[100:103]
	v_mfma_f32_16x16x32_bf16 v[96:99], v[236:239], v[204:207], v[96:99]
	v_mfma_f32_16x16x32_bf16 v[80:83], v[228:231], v[212:215], v[80:83]
	v_mfma_f32_16x16x32_bf16 v[72:75], v[236:239], v[212:215], v[72:75]
	v_mfma_f32_16x16x32_bf16 v[68:71], v[228:231], v[220:223], v[68:71]
	v_mfma_f32_16x16x32_bf16 v[64:67], v[236:239], v[220:223], v[64:67]
	s_mov_b32 m0, s70
	v_lshl_add_u64 v[154:155], s[16:17], 0, v[146:147]
	s_barrier
	ds_read_b128 v[172:175], v158 offset:49152
	ds_read_b128 v[176:179], v158 offset:50176
	ds_read_b128 v[180:183], v158 offset:51200
	ds_read_b128 v[204:207], v158 offset:52224
	ds_read_b128 v[208:211], v158 offset:53248
	ds_read_b128 v[212:215], v158 offset:54272
	ds_read_b128 v[216:219], v158 offset:55296
	ds_read_b128 v[220:223], v158 offset:56320
	global_load_lds_dwordx4 v[154:155], off
	v_lshl_add_u64 v[154:155], s[16:17], 0, v[144:145]
	s_mov_b32 m0, s71
	s_nop 0
	global_load_lds_dwordx4 v[154:155], off
	s_waitcnt vmcnt(10)
	s_barrier
; #define PG8_STAGE(bufoff, gbase, voff) do { _Pragma("unroll") for (int _i = 0; _i < 2; ++_i) \
;         __builtin_amdgcn_global_load_lds((const unsigned*)((const char*)(gbase) + (voff)[_i]), (LAS unsigned*)(lds + (bufoff) + ldsw + _i * 8192), 16, 0, 0); } while (0)
; #define PG8_MMA(ai, bj, At, Bt) do { __builtin_amdgcn_s_setprio(1); _Pragma("unroll") for (int m = 0; m < 4; ++m) _Pragma("unroll") for (int n = 0; n < 2; ++n) _Pragma("unroll") for (int k = 0; k < 2; ++k) \
;         acc[ai][bj][m][n] = __builtin_amdgcn_mfma_f32_16x16x32_bf16(Bt[n][k], At[m][k], acc[ai][bj][m][n], 0, 0, 0); __builtin_amdgcn_s_setprio(0); } while (0)
; #define PG8_WAIT_V(n) asm volatile("s_waitcnt vmcnt(" #n ")" ::: "memory")
; #define PG8_WAIT_L(n) asm volatile("s_waitcnt lgkmcnt(" #n ")" ::: "memory")
; #define PG8_BAR __builtin_amdgcn_s_barrier()
; #define PG8_SCHED __builtin_amdgcn_sched_barrier(0)
;     ...
;             PG8_BAR; PG8_WAIT_L(0); PG8_MMA(1, 0, At, B0); PG8_BAR; PG8_SCHED;
;             PG8_STAGE(PG8_SB(1, 1), b3 + hb2, voffB);
;             PG8_WAIT_V(6); PG8_BAR; PG8_MMA(1, 1, At, B1); PG8_BAR;
;     __device__ __forceinline__ void operator()(const f32x4 (&acc)[2][2][4][2], const Unit& u, int wr, int wc, int fr, int fq, int lane) const {
;         const bool lat = u.pm < 128;
;         const int s = lat ? (u.pm >> 4) : 8;
;         const float* gate = modi + s * 6144 + 4096 + u.pn * BM + wc * 32 + 4 * fq;
;         const size_t r0 = lat ? (size_t)u.pm * BM : (size_t)(u.pm - 128) * BM;
;         const float* base = (lat ? baseL : baseC) + u.pn * BM + wc * 32 + 4 * fq;
;         float* out = (lat ? outL : outC) + u.pn * BM + wc * 32 + 4 * fq;
;         f32x4 gv[2][2];
; #pragma unroll
;         for (int bj = 0; bj < 2; ++bj)
; #pragma unroll
;             for (int n = 0; n < 2; ++n) gv[bj][n] = *(const f32x4*)(gate + bj * HALF + n * 16);
	s_waitcnt lgkmcnt(0)
	s_waitcnt lgkmcnt(0)
	v_mfma_f32_16x16x32_bf16 v[60:63], v[132:135], v[172:175], v[60:63]
	v_mfma_f32_16x16x32_bf16 v[56:59], v[140:143], v[172:175], v[56:59]
	v_mfma_f32_16x16x32_bf16 v[52:55], v[132:135], v[180:183], v[52:55]
	v_mfma_f32_16x16x32_bf16 v[44:47], v[140:143], v[180:183], v[44:47]
	v_mfma_f32_16x16x32_bf16 v[28:31], v[132:135], v[208:211], v[28:31]
	v_mfma_f32_16x16x32_bf16 v[24:27], v[140:143], v[208:211], v[24:27]
	v_mfma_f32_16x16x32_bf16 v[20:23], v[132:135], v[216:219], v[20:23]
	v_mfma_f32_16x16x32_bf16 v[12:15], v[140:143], v[216:219], v[12:15]
	v_mfma_f32_16x16x32_bf16 v[60:63], v[136:139], v[176:179], v[60:63]
	v_mfma_f32_16x16x32_bf16 v[56:59], v[168:171], v[176:179], v[56:59]
	v_mfma_f32_16x16x32_bf16 v[52:55], v[136:139], v[204:207], v[52:55]
	v_mfma_f32_16x16x32_bf16 v[44:47], v[168:171], v[204:207], v[44:47]
	v_mfma_f32_16x16x32_bf16 v[28:31], v[136:139], v[212:215], v[28:31]
	v_mfma_f32_16x16x32_bf16 v[24:27], v[168:171], v[212:215], v[24:27]
	v_mfma_f32_16x16x32_bf16 v[20:23], v[136:139], v[220:223], v[20:23]
	v_mfma_f32_16x16x32_bf16 v[12:15], v[168:171], v[220:223], v[12:15]
	s_barrier
	s_add_u32 s10, s14, 0x100080
	s_addc_u32 s11, s15, 0
	s_add_i32 s14, s20, s52
	v_lshl_add_u64 v[132:133], s[10:11], 0, v[146:147]
	s_mov_b32 m0, s14
	s_nop 0
	global_load_lds_dwordx4 v[132:133], off
	v_lshl_add_u64 v[132:133], s[10:11], 0, v[144:145]
	s_add_i32 m0, s14, 0x2000
	s_nop 0
	global_load_lds_dwordx4 v[132:133], off
	v_add_u32_e32 v154, 0x10000, v157
	ds_read_b128 v[132:135], v154
	ds_read_b128 v[136:139], v154 offset:1024
	ds_read_b128 v[140:143], v154 offset:2048
	ds_read_b128 v[168:171], v154 offset:3072
	s_waitcnt vmcnt(10)
	s_barrier
	v_mfma_f32_16x16x32_bf16 v[48:51], v[224:227], v[172:175], v[48:51]
	v_mfma_f32_16x16x32_bf16 v[40:43], v[232:235], v[172:175], v[40:43]
	v_mfma_f32_16x16x32_bf16 v[36:39], v[224:227], v[180:183], v[36:39]
	v_mfma_f32_16x16x32_bf16 v[32:35], v[232:235], v[180:183], v[32:35]
	v_mfma_f32_16x16x32_bf16 v[16:19], v[224:227], v[208:211], v[16:19]
	v_mfma_f32_16x16x32_bf16 v[8:11], v[232:235], v[208:211], v[8:11]
	v_mfma_f32_16x16x32_bf16 v[4:7], v[224:227], v[216:219], v[4:7]
	v_mfma_f32_16x16x32_bf16 v[0:3], v[232:235], v[216:219], v[0:3]
	v_mfma_f32_16x16x32_bf16 v[48:51], v[228:231], v[176:179], v[48:51]
	v_mfma_f32_16x16x32_bf16 v[40:43], v[236:239], v[176:179], v[40:43]
	v_mfma_f32_16x16x32_bf16 v[36:39], v[228:231], v[204:207], v[36:39]
	v_mfma_f32_16x16x32_bf16 v[32:35], v[236:239], v[204:207], v[32:35]
	v_mfma_f32_16x16x32_bf16 v[16:19], v[228:231], v[212:215], v[16:19]
	v_mfma_f32_16x16x32_bf16 v[8:11], v[236:239], v[212:215], v[8:11]
	v_mfma_f32_16x16x32_bf16 v[4:7], v[228:231], v[220:223], v[4:7]
	v_mfma_f32_16x16x32_bf16 v[0:3], v[236:239], v[220:223], v[0:3]
	s_add_i32 s92, s92, 2
	s_add_u32 s46, s46, 0x100
	s_addc_u32 s47, s47, 0
	s_cmp_gt_u32 s92, 61
	s_barrier
	s_cbranch_scc0 .LBB0_335
	s_waitcnt lgkmcnt(0)
	s_cmpk_lt_i32 s0, 0x80
	s_cselect_b32 s3, s61, s67
	s_cselect_b32 s16, s60, s66
	s_add_i32 s9, s0, 0xffffff80
	s_cmpk_lt_i32 s0, 0x80
	s_cselect_b32 s10, s0, s9
	s_lshr_b32 s9, s0, 4
	s_cmpk_lt_i32 s0, 0x80
	s_mulk_i32 s9, 0x1800
	s_cselect_b32 s14, s9, 0xc000
	s_ashr_i32 s15, s14, 31
	s_lshl_b64 s[14:15], s[14:15], 2
	s_add_u32 s0, s68, s14
	s_addc_u32 s11, s69, s15
	s_lshl_b32 s8, s8, 8
	s_ashr_i32 s9, s8, 31
	s_lshl_b64 s[8:9], s[8:9], 2
	s_add_u32 s0, s0, s8
	s_addc_u32 s11, s11, s9
	s_add_u32 s14, s0, s90
	s_addc_u32 s15, s11, 0
	s_ashr_i32 s11, s10, 31
	s_add_u32 s0, s16, s8
	s_addc_u32 s3, s3, s9
	s_add_u32 s8, s0, s90
	s_addc_u32 s9, s3, 0
	v_lshl_add_u64 v[128:129], s[14:15], 0, v[160:161]
	s_mov_b64 s[14:15], 0x704000
	s_mov_b32 s0, 0x704000
	v_lshl_add_u64 v[154:155], s[8:9], 0, v[160:161]
	s_lshl_b64 s[8:9], s[10:11], 21
	v_lshl_add_u64 v[130:131], v[128:129], 0, s[14:15]
	v_add_co_u32_e32 v128, vcc, s0, v128
	v_lshl_add_u64 v[154:155], v[154:155], 0, s[8:9]
	s_nop 0
	v_addc_co_u32_e32 v129, vcc, 0, v129, vcc
	v_lshl_add_u64 v[154:155], v[154:155], 0, v[148:149]
	s_mov_b32 s0, 0x20000
	v_add_co_u32_e32 v184, vcc, s0, v154
	global_load_dwordx4 v[136:139], v[130:131], off offset:64
	global_load_dwordx4 v[132:135], v[130:131], off offset:512
	global_load_dwordx4 v[140:143], v[128:129], off
	s_nop 0
	global_load_dwordx4 v[128:131], v[130:131], off offset:576
	v_addc_co_u32_e32 v185, vcc, 0, v155, vcc
	global_load_dwordx4 v[168:171], v[154:155], off
	global_load_dwordx4 v[172:175], v[154:155], off offset:64
	global_load_dwordx4 v[176:179], v[154:155], off offset:512
	global_load_dwordx4 v[180:183], v[154:155], off offset:576
	global_load_dwordx4 v[204:207], v[184:185], off
	global_load_dwordx4 v[208:211], v[184:185], off offset:64
	global_load_dwordx4 v[212:215], v[184:185], off offset:512
	global_load_dwordx4 v[216:219], v[184:185], off offset:576
	s_waitcnt vmcnt(0)
;     __device__ __forceinline__ void operator()(const f32x4 (&acc)[2][2][4][2], const Unit& u, int wr, int wc, int fr, int fq, int lane) const {
;     ...
;         for (int ai = 0; ai < 2; ++ai)
; #pragma unroll
;           for (int mh = 0; mh < 2; ++mh) {
;             f32x4 bs[2][2][2];
; #pragma unroll
;             for (int m2 = 0; m2 < 2; ++m2) {
;                 const size_t ro = (r0 + ai * HALF + wr * 64 + (mh * 2 + m2) * 16 + fr) * (size_t)D;
; #pragma unroll
;                 for (int bj = 0; bj < 2; ++bj)
; #pragma unroll
;                     for (int n = 0; n < 2; ++n) bs[m2][bj][n] = *(const f32x4*)(base + ro + bj * HALF + n * 16);
;             }
;             __builtin_amdgcn_sched_barrier(0);
; #pragma unroll
;             for (int m2 = 0; m2 < 2; ++m2) {
;                 const size_t ro = (r0 + ai * HALF + wr * 64 + (mh * 2 + m2) * 16 + fr) * (size_t)D;
; #pragma unroll
;                 for (int bj = 0; bj < 2; ++bj)
; #pragma unroll
;                     for (int n = 0; n < 2; ++n) *(f32x4*)(out + ro + bj * HALF + n * 16) = bs[m2][bj][n] + gv[bj][n] * acc[ai][bj][mh * 2 + m2][n];
;             }
;             __builtin_amdgcn_sched_barrier(0);
	v_pk_fma_f32 v[106:107], v[106:107], v[130:131], v[182:183]
	v_pk_fma_f32 v[104:105], v[104:105], v[128:129], v[180:181]
	global_store_dwordx4 v[154:155], v[104:107], off offset:576
	v_pk_fma_f32 v[126:127], v[126:127], v[142:143], v[170:171]
	v_pk_fma_f32 v[124:125], v[124:125], v[140:141], v[168:169]
	v_pk_fma_f32 v[106:107], v[118:119], v[142:143], v[206:207]
	v_pk_fma_f32 v[104:105], v[116:117], v[140:141], v[204:205]
	v_pk_fma_f32 v[122:123], v[122:123], v[138:139], v[174:175]
	v_pk_fma_f32 v[120:121], v[120:121], v[136:137], v[172:173]
	v_pk_fma_f32 v[114:115], v[114:115], v[134:135], v[178:179]
	v_pk_fma_f32 v[112:113], v[112:113], v[132:133], v[176:177]
	global_store_dwordx4 v[184:185], v[104:107], off
	v_pk_fma_f32 v[102:103], v[102:103], v[134:135], v[214:215]
	v_pk_fma_f32 v[100:101], v[100:101], v[132:133], v[212:213]
	v_pk_fma_f32 v[106:107], v[110:111], v[138:139], v[210:211]
	v_pk_fma_f32 v[104:105], v[108:109], v[136:137], v[208:209]
	v_pk_fma_f32 v[98:99], v[98:99], v[130:131], v[218:219]
	v_pk_fma_f32 v[96:97], v[96:97], v[128:129], v[216:217]
	global_store_dwordx4 v[154:155], v[124:127], off
	global_store_dwordx4 v[154:155], v[120:123], off offset:64
	global_store_dwordx4 v[154:155], v[112:115], off offset:512
	global_store_dwordx4 v[184:185], v[104:107], off offset:64
	global_store_dwordx4 v[184:185], v[100:103], off offset:512
	global_store_dwordx4 v[184:185], v[96:99], off offset:576
	s_mov_b32 s0, 0x40000
	v_add_co_u32_e32 v168, vcc, s0, v154
	s_mov_b32 s0, 0x60000
	s_nop 0
	v_addc_co_u32_e32 v169, vcc, 0, v155, vcc
	v_add_co_u32_e32 v170, vcc, s0, v154
	global_load_dwordx4 v[96:99], v[168:169], off
	global_load_dwordx4 v[100:103], v[168:169], off offset:64
	global_load_dwordx4 v[104:107], v[168:169], off offset:512
	global_load_dwordx4 v[108:111], v[168:169], off offset:576
	v_addc_co_u32_e32 v171, vcc, 0, v155, vcc
	global_load_dwordx4 v[112:115], v[170:171], off
	global_load_dwordx4 v[116:119], v[170:171], off offset:64
	global_load_dwordx4 v[120:123], v[170:171], off offset:512
	global_load_dwordx4 v[124:127], v[170:171], off offset:576
	s_waitcnt vmcnt(0)
	v_pk_fma_f32 v[74:75], v[74:75], v[130:131], v[110:111]
	v_pk_fma_f32 v[72:73], v[72:73], v[128:129], v[108:109]
	global_store_dwordx4 v[168:169], v[72:75], off offset:576
	v_pk_fma_f32 v[94:95], v[94:95], v[142:143], v[98:99]
	v_pk_fma_f32 v[92:93], v[92:93], v[140:141], v[96:97]
	v_pk_fma_f32 v[74:75], v[86:87], v[142:143], v[114:115]
	v_pk_fma_f32 v[72:73], v[84:85], v[140:141], v[112:113]
	v_pk_fma_f32 v[90:91], v[90:91], v[138:139], v[102:103]
	v_pk_fma_f32 v[88:89], v[88:89], v[136:137], v[100:101]
	v_pk_fma_f32 v[82:83], v[82:83], v[134:135], v[106:107]
	v_pk_fma_f32 v[80:81], v[80:81], v[132:133], v[104:105]
	global_store_dwordx4 v[170:171], v[72:75], off
	v_pk_fma_f32 v[70:71], v[70:71], v[134:135], v[122:123]
	v_pk_fma_f32 v[68:69], v[68:69], v[132:133], v[120:121]
	v_pk_fma_f32 v[74:75], v[78:79], v[138:139], v[118:119]
	v_pk_fma_f32 v[72:73], v[76:77], v[136:137], v[116:117]
	v_pk_fma_f32 v[66:67], v[66:67], v[130:131], v[126:127]
	v_pk_fma_f32 v[64:65], v[64:65], v[128:129], v[124:125]
	global_store_dwordx4 v[168:169], v[92:95], off
	global_store_dwordx4 v[168:169], v[88:91], off offset:64
	global_store_dwordx4 v[168:169], v[80:83], off offset:512
	global_store_dwordx4 v[170:171], v[72:75], off offset:64
	global_store_dwordx4 v[170:171], v[68:71], off offset:512
	global_store_dwordx4 v[170:171], v[64:67], off offset:576
	v_add_co_u32_e32 v96, vcc, s76, v154
	s_nop 1
	v_addc_co_u32_e32 v97, vcc, 0, v155, vcc
	v_add_co_u32_e32 v98, vcc, s77, v154
	global_load_dwordx4 v[64:67], v[96:97], off
	global_load_dwordx4 v[68:71], v[96:97], off offset:64
	global_load_dwordx4 v[72:75], v[96:97], off offset:512
	global_load_dwordx4 v[76:79], v[96:97], off offset:576
	v_addc_co_u32_e32 v99, vcc, 0, v155, vcc
	global_load_dwordx4 v[80:83], v[98:99], off
	global_load_dwordx4 v[84:87], v[98:99], off offset:64
	global_load_dwordx4 v[88:91], v[98:99], off offset:512
	global_load_dwordx4 v[92:95], v[98:99], off offset:576
	s_waitcnt vmcnt(0)
;     ...
;         if (!has_next) break;
; #pragma unroll
;         for (int a = 0; a < 2; ++a)
; #pragma unroll
;             for (int b = 0; b < 2; ++b)
; #pragma unroll
;                 for (int m = 0; m < 4; ++m)
; #pragma unroll
;                     for (int n = 0; n < 2; ++n) acc[a][b][m][n] = (f32x4){0.f, 0.f, 0.f, 0.f};
;         cur = nxt; cA = nA; cB = nB; cAr = nAr; cHb = nHb; ++ui;
;     __device__ __forceinline__ void operator()(const f32x4 (&acc)[2][2][4][2], const Unit& u, int wr, int wc, int fr, int fq, int lane) const {
;     ...
;             for (int m2 = 0; m2 < 2; ++m2) {
;                 const size_t ro = (r0 + ai * HALF + wr * 64 + (mh * 2 + m2) * 16 + fr) * (size_t)D;
; #pragma unroll
;                 for (int bj = 0; bj < 2; ++bj)
; #pragma unroll
;                     for (int n = 0; n < 2; ++n) *(f32x4*)(out + ro + bj * HALF + n * 16) = bs[m2][bj][n] + gv[bj][n] * acc[ai][bj][mh * 2 + m2][n];
;             }
;             __builtin_amdgcn_sched_barrier(0);
	v_pk_fma_f32 v[42:43], v[42:43], v[130:131], v[78:79]
	v_pk_fma_f32 v[40:41], v[40:41], v[128:129], v[76:77]
	global_store_dwordx4 v[96:97], v[40:43], off offset:576
	v_pk_fma_f32 v[62:63], v[62:63], v[142:143], v[66:67]
	v_pk_fma_f32 v[60:61], v[60:61], v[140:141], v[64:65]
	v_pk_fma_f32 v[42:43], v[54:55], v[142:143], v[82:83]
	v_pk_fma_f32 v[40:41], v[52:53], v[140:141], v[80:81]
	v_pk_fma_f32 v[58:59], v[58:59], v[138:139], v[70:71]
	v_pk_fma_f32 v[56:57], v[56:57], v[136:137], v[68:69]
	v_pk_fma_f32 v[50:51], v[50:51], v[134:135], v[74:75]
	v_pk_fma_f32 v[48:49], v[48:49], v[132:133], v[72:73]
	global_store_dwordx4 v[98:99], v[40:43], off
	v_pk_fma_f32 v[38:39], v[38:39], v[134:135], v[90:91]
	v_pk_fma_f32 v[36:37], v[36:37], v[132:133], v[88:89]
	v_pk_fma_f32 v[42:43], v[46:47], v[138:139], v[86:87]
	v_pk_fma_f32 v[40:41], v[44:45], v[136:137], v[84:85]
	v_pk_fma_f32 v[34:35], v[34:35], v[130:131], v[94:95]
	v_pk_fma_f32 v[32:33], v[32:33], v[128:129], v[92:93]
	global_store_dwordx4 v[96:97], v[60:63], off
	global_store_dwordx4 v[96:97], v[56:59], off offset:64
	global_store_dwordx4 v[96:97], v[48:51], off offset:512
	global_store_dwordx4 v[98:99], v[40:43], off offset:64
	global_store_dwordx4 v[98:99], v[36:39], off offset:512
	global_store_dwordx4 v[98:99], v[32:35], off offset:576
	v_add_co_u32_e32 v64, vcc, s18, v154
	s_nop 1
	v_addc_co_u32_e32 v65, vcc, 0, v155, vcc
	v_add_co_u32_e32 v66, vcc, s54, v154
	global_load_dwordx4 v[32:35], v[64:65], off
	global_load_dwordx4 v[36:39], v[64:65], off offset:64
	global_load_dwordx4 v[40:43], v[64:65], off offset:512
	global_load_dwordx4 v[44:47], v[64:65], off offset:576
	v_addc_co_u32_e32 v67, vcc, 0, v155, vcc
	global_load_dwordx4 v[48:51], v[66:67], off
	global_load_dwordx4 v[52:55], v[66:67], off offset:64
	global_load_dwordx4 v[56:59], v[66:67], off offset:512
	global_load_dwordx4 v[60:63], v[66:67], off offset:576
	s_waitcnt vmcnt(0)
	v_pk_fma_f32 v[10:11], v[10:11], v[130:131], v[46:47]
	v_pk_fma_f32 v[8:9], v[8:9], v[128:129], v[44:45]
	global_store_dwordx4 v[64:65], v[8:11], off offset:576
	v_pk_fma_f32 v[30:31], v[30:31], v[142:143], v[34:35]
	v_pk_fma_f32 v[28:29], v[28:29], v[140:141], v[32:33]
	v_pk_fma_f32 v[10:11], v[22:23], v[142:143], v[50:51]
	v_pk_fma_f32 v[8:9], v[20:21], v[140:141], v[48:49]
	v_pk_fma_f32 v[26:27], v[26:27], v[138:139], v[38:39]
	v_pk_fma_f32 v[24:25], v[24:25], v[136:137], v[36:37]
	v_pk_fma_f32 v[18:19], v[18:19], v[134:135], v[42:43]
	v_pk_fma_f32 v[16:17], v[16:17], v[132:133], v[40:41]
	global_store_dwordx4 v[66:67], v[8:11], off
	v_pk_fma_f32 v[6:7], v[6:7], v[134:135], v[58:59]
	v_pk_fma_f32 v[4:5], v[4:5], v[132:133], v[56:57]
	v_pk_fma_f32 v[10:11], v[14:15], v[138:139], v[54:55]
	v_pk_fma_f32 v[8:9], v[12:13], v[136:137], v[52:53]
	v_pk_fma_f32 v[2:3], v[2:3], v[130:131], v[62:63]
	v_pk_fma_f32 v[0:1], v[0:1], v[128:129], v[60:61]
	global_store_dwordx4 v[64:65], v[28:31], off
	global_store_dwordx4 v[64:65], v[24:27], off offset:64
	global_store_dwordx4 v[64:65], v[16:19], off offset:512
	global_store_dwordx4 v[66:67], v[8:11], off offset:64
	global_store_dwordx4 v[66:67], v[4:7], off offset:512
	global_store_dwordx4 v[66:67], v[0:3], off offset:576
	s_and_b64 vcc, exec, s[42:43]
	s_mov_b32 s8, s2
	s_mov_b32 s0, s26
	s_mov_b64 s[20:21], s[38:39]
	s_mov_b64 s[44:45], s[36:37]
	s_cbranch_vccz .LBB0_332
	s_waitcnt vmcnt(0)
	s_cmpk_gt_u32 s5, 0xff
	s_cbranch_scc1 .LBB0_339
	s_barrier

; #define PG8_STAGE(bufoff, gbase, voff) do { _Pragma("unroll") for (int _i = 0; _i < 2; ++_i) \
;         __builtin_amdgcn_global_load_lds((const unsigned*)((const char*)(gbase) + (voff)[_i]), (LAS unsigned*)(lds + (bufoff) + ldsw + _i * 8192), 16, 0, 0); } while (0)
; #define PG8_STAGE_A(bufoff, ptr, half, rev) do { if (REVA && (rev)) { const char* _p = (ptr) - ((half) ? hstepA : 0); PG8_STAGE(bufoff, _p, voffAr); } else { const char* _p = (ptr) + ((half) ? hstepA : 0); PG8_STAGE(bufoff, _p, voffA); } } while (0)
; #define PG8_LDA(dst, b, h) do { _Pragma("unroll") for (int m = 0; m < 4; ++m) _Pragma("unroll") for (int k = 0; k < 2; ++k) dst[m][k] = *(const LAS bf16x8*)(lds + PG8_SA(b, h) + aoff + m * 2048 + k * 1024); } while (0)
; #define PG8_LDB(dst, b, h) do { _Pragma("unroll") for (int n = 0; n < 2; ++n) _Pragma("unroll") for (int k = 0; k < 2; ++k) dst[n][k] = *(const LAS bf16x8*)(lds + PG8_SB(b, h) + boff + n * 2048 + k * 1024); } while (0)
; #define PG8_MMA(ai, bj, At, Bt) do { __builtin_amdgcn_s_setprio(1); _Pragma("unroll") for (int m = 0; m < 4; ++m) _Pragma("unroll") for (int n = 0; n < 2; ++n) _Pragma("unroll") for (int k = 0; k < 2; ++k) \
;         acc[ai][bj][m][n] = __builtin_amdgcn_mfma_f32_16x16x32_bf16(Bt[n][k], At[m][k], acc[ai][bj][m][n], 0, 0, 0); __builtin_amdgcn_s_setprio(0); } while (0)
; #define PG8_WAIT_L(n) asm volatile("s_waitcnt lgkmcnt(" #n ")" ::: "memory")
; #define PG8_BAR __builtin_amdgcn_s_barrier()
; #define PG8_SCHED __builtin_amdgcn_sched_barrier(0)
;     ...
;             PG8_LDB(B0, 0, 0); PG8_SCHED; PG8_LDA(At, 0, 0); PG8_STAGE_A(PG8_SA(1, 1), a1, 1, r1);
;             PG8_WAIT_L(8); PG8_BAR; PG8_WAIT_L(0); PG8_MMA(0, 0, At, B0); PG8_BAR; PG8_SCHED;
;             PG8_LDB(B1, 0, 1); PG8_STAGE(PG8_SB(0, 0), b2, voffB);
;             PG8_BAR; PG8_WAIT_L(0); PG8_MMA(0, 1, At, B1); PG8_BAR;
;             PG8_LDA(At, 0, 1); PG8_STAGE_A(PG8_SA(0, 0), a2, 0, r2);
;             PG8_BAR; PG8_WAIT_L(0); PG8_MMA(1, 0, At, B0); PG8_BAR; PG8_SCHED;
.LBB0_522:
	s_add_u32 s10, s44, s0
	s_addc_u32 s11, s45, s1
	s_add_u32 s14, s10, 0x100
	s_addc_u32 s15, s11, 0
	s_add_u32 s10, s10, 0x180
	s_addc_u32 s11, s11, 0
	s_add_u32 s16, s8, s0
	s_addc_u32 s17, s9, s1
	s_add_i32 s27, 0, 0x10000
	s_cmpk_eq_i32 s0, 0xf00
	s_cselect_b32 s21, s47, s17
	s_cselect_b32 s20, s46, s16
	s_cselect_b32 s17, s39, s15
	s_cselect_b32 s16, s38, s14
	s_cselect_b32 s90, s37, s3
	s_cselect_b32 s91, s36, s2
	s_cselect_b32 s15, s7, s11
	s_cselect_b32 s14, s6, s10
	v_lshl_add_u64 v[184:185], v[144:145], 0, s[0:1]
	s_add_i32 m0, s66, 0xc000
	ds_read_b128 v[180:183], v155
	ds_read_b128 v[204:207], v155 offset:1024
	ds_read_b128 v[208:211], v155 offset:2048
	ds_read_b128 v[212:215], v155 offset:3072
	ds_read_b128 v[216:219], v155 offset:4096
	ds_read_b128 v[220:223], v155 offset:5120
	ds_read_b128 v[224:227], v155 offset:6144
	ds_read_b128 v[228:231], v155 offset:7168
	global_load_lds_dwordx4 v[184:185], off
	v_lshl_add_u64 v[184:185], v[146:147], 0, s[0:1]
	s_add_i32 m0, s66, 0xe000
	s_nop 0
	global_load_lds_dwordx4 v[184:185], off
	s_waitcnt lgkmcnt(8)
	s_waitcnt vmcnt(10)
	s_barrier
	s_waitcnt lgkmcnt(0)
	s_waitcnt lgkmcnt(0)
	v_mfma_f32_16x16x32_bf16 v[124:127], v[156:159], v[180:183], v[124:127]
	v_mfma_f32_16x16x32_bf16 v[120:123], v[172:175], v[180:183], v[120:123]
	v_mfma_f32_16x16x32_bf16 v[108:111], v[156:159], v[208:211], v[108:111]
	v_mfma_f32_16x16x32_bf16 v[104:107], v[172:175], v[208:211], v[104:107]
	v_mfma_f32_16x16x32_bf16 v[92:95], v[156:159], v[216:219], v[92:95]
	v_mfma_f32_16x16x32_bf16 v[88:91], v[172:175], v[216:219], v[88:91]
	v_mfma_f32_16x16x32_bf16 v[76:79], v[156:159], v[224:227], v[76:79]
	v_mfma_f32_16x16x32_bf16 v[72:75], v[172:175], v[224:227], v[72:75]
	v_mfma_f32_16x16x32_bf16 v[124:127], v[168:171], v[204:207], v[124:127]
	v_mfma_f32_16x16x32_bf16 v[120:123], v[176:179], v[204:207], v[120:123]
	v_mfma_f32_16x16x32_bf16 v[108:111], v[168:171], v[212:215], v[108:111]
	v_mfma_f32_16x16x32_bf16 v[104:107], v[176:179], v[212:215], v[104:107]
	v_mfma_f32_16x16x32_bf16 v[92:95], v[168:171], v[220:223], v[92:95]
	v_mfma_f32_16x16x32_bf16 v[88:91], v[176:179], v[220:223], v[88:91]
	v_mfma_f32_16x16x32_bf16 v[76:79], v[168:171], v[228:231], v[76:79]
	v_mfma_f32_16x16x32_bf16 v[72:75], v[176:179], v[228:231], v[72:75]
	s_barrier
	s_add_i32 s10, 0, 0x14000
	s_add_i32 s11, s27, s53
	v_add_u32_e32 v160, s10, v139
	v_lshl_add_u64 v[184:185], s[20:21], 0, v[130:131]
	s_mov_b32 m0, s11
	ds_read_b128 v[232:235], v160
	ds_read_b128 v[236:239], v160 offset:1024
	ds_read_b128 v[240:243], v160 offset:2048
	ds_read_b128 v[244:247], v160 offset:3072
	global_load_lds_dwordx4 v[184:185], off
	v_lshl_add_u64 v[248:249], s[20:21], 0, v[134:135]
	s_add_i32 m0, s11, 0x2000
	s_nop 0
	global_load_lds_dwordx4 v[248:249], off
	s_waitcnt vmcnt(10)
	s_barrier
	s_waitcnt lgkmcnt(0)
	s_waitcnt lgkmcnt(0)
	v_mfma_f32_16x16x32_bf16 v[116:119], v[232:235], v[180:183], v[116:119]
	v_mfma_f32_16x16x32_bf16 v[112:115], v[240:243], v[180:183], v[112:115]
	v_mfma_f32_16x16x32_bf16 v[100:103], v[232:235], v[208:211], v[100:103]
	v_mfma_f32_16x16x32_bf16 v[96:99], v[240:243], v[208:211], v[96:99]
	v_mfma_f32_16x16x32_bf16 v[84:87], v[232:235], v[216:219], v[84:87]
	v_mfma_f32_16x16x32_bf16 v[80:83], v[240:243], v[216:219], v[80:83]
	v_mfma_f32_16x16x32_bf16 v[68:71], v[232:235], v[224:227], v[68:71]
	v_mfma_f32_16x16x32_bf16 v[64:67], v[240:243], v[224:227], v[64:67]
	v_mfma_f32_16x16x32_bf16 v[116:119], v[236:239], v[204:207], v[116:119]
	v_mfma_f32_16x16x32_bf16 v[112:115], v[244:247], v[204:207], v[112:115]
	v_mfma_f32_16x16x32_bf16 v[100:103], v[236:239], v[212:215], v[100:103]
	v_mfma_f32_16x16x32_bf16 v[96:99], v[244:247], v[212:215], v[96:99]
	v_mfma_f32_16x16x32_bf16 v[84:87], v[236:239], v[220:223], v[84:87]
	v_mfma_f32_16x16x32_bf16 v[80:83], v[244:247], v[220:223], v[80:83]
	v_mfma_f32_16x16x32_bf16 v[68:71], v[236:239], v[228:231], v[68:71]
	v_mfma_f32_16x16x32_bf16 v[64:67], v[244:247], v[228:231], v[64:67]
	s_mov_b32 m0, s66
	v_lshl_add_u64 v[250:251], s[16:17], 0, v[128:129]
	s_barrier
	ds_read_b128 v[180:183], v155 offset:16384
	ds_read_b128 v[204:207], v155 offset:17408
	ds_read_b128 v[208:211], v155 offset:18432
	ds_read_b128 v[212:215], v155 offset:19456
	ds_read_b128 v[216:219], v155 offset:20480
	ds_read_b128 v[220:223], v155 offset:21504
	ds_read_b128 v[224:227], v155 offset:22528
	ds_read_b128 v[228:231], v155 offset:23552
	global_load_lds_dwordx4 v[250:251], off
	v_lshl_add_u64 v[250:251], s[16:17], 0, v[132:133]
	s_mov_b32 m0, s67
	s_nop 0
	global_load_lds_dwordx4 v[250:251], off
	s_waitcnt vmcnt(10)
	s_barrier
	s_waitcnt lgkmcnt(0)
	s_waitcnt lgkmcnt(0)
	v_mfma_f32_16x16x32_bf16 v[60:63], v[156:159], v[180:183], v[60:63]
	v_mfma_f32_16x16x32_bf16 v[56:59], v[172:175], v[180:183], v[56:59]
	v_mfma_f32_16x16x32_bf16 v[44:47], v[156:159], v[208:211], v[44:47]
	v_mfma_f32_16x16x32_bf16 v[40:43], v[172:175], v[208:211], v[40:43]
	v_mfma_f32_16x16x32_bf16 v[28:31], v[156:159], v[216:219], v[28:31]
	v_mfma_f32_16x16x32_bf16 v[24:27], v[172:175], v[216:219], v[24:27]
	v_mfma_f32_16x16x32_bf16 v[12:15], v[156:159], v[224:227], v[12:15]
	v_mfma_f32_16x16x32_bf16 v[8:11], v[172:175], v[224:227], v[8:11]
	v_mfma_f32_16x16x32_bf16 v[60:63], v[168:171], v[204:207], v[60:63]
	v_mfma_f32_16x16x32_bf16 v[56:59], v[176:179], v[204:207], v[56:59]
	v_mfma_f32_16x16x32_bf16 v[44:47], v[168:171], v[212:215], v[44:47]
	v_mfma_f32_16x16x32_bf16 v[40:43], v[176:179], v[212:215], v[40:43]
	v_mfma_f32_16x16x32_bf16 v[28:31], v[168:171], v[220:223], v[28:31]
	v_mfma_f32_16x16x32_bf16 v[24:27], v[176:179], v[220:223], v[24:27]
	v_mfma_f32_16x16x32_bf16 v[12:15], v[168:171], v[228:231], v[12:15]
	v_mfma_f32_16x16x32_bf16 v[8:11], v[176:179], v[228:231], v[8:11]
	s_barrier
; #define PG8_STAGE(bufoff, gbase, voff) do { _Pragma("unroll") for (int _i = 0; _i < 2; ++_i) \
;         __builtin_amdgcn_global_load_lds((const unsigned*)((const char*)(gbase) + (voff)[_i]), (LAS unsigned*)(lds + (bufoff) + ldsw + _i * 8192), 16, 0, 0); } while (0)
; #define PG8_STAGE_A(bufoff, ptr, half, rev) do { if (REVA && (rev)) { const char* _p = (ptr) - ((half) ? hstepA : 0); PG8_STAGE(bufoff, _p, voffAr); } else { const char* _p = (ptr) + ((half) ? hstepA : 0); PG8_STAGE(bufoff, _p, voffA); } } while (0)
; #define PG8_LDA(dst, b, h) do { _Pragma("unroll") for (int m = 0; m < 4; ++m) _Pragma("unroll") for (int k = 0; k < 2; ++k) dst[m][k] = *(const LAS bf16x8*)(lds + PG8_SA(b, h) + aoff + m * 2048 + k * 1024); } while (0)
; #define PG8_LDB(dst, b, h) do { _Pragma("unroll") for (int n = 0; n < 2; ++n) _Pragma("unroll") for (int k = 0; k < 2; ++k) dst[n][k] = *(const LAS bf16x8*)(lds + PG8_SB(b, h) + boff + n * 2048 + k * 1024); } while (0)
; #define PG8_MMA(ai, bj, At, Bt) do { __builtin_amdgcn_s_setprio(1); _Pragma("unroll") for (int m = 0; m < 4; ++m) _Pragma("unroll") for (int n = 0; n < 2; ++n) _Pragma("unroll") for (int k = 0; k < 2; ++k) \
;         acc[ai][bj][m][n] = __builtin_amdgcn_mfma_f32_16x16x32_bf16(Bt[n][k], At[m][k], acc[ai][bj][m][n], 0, 0, 0); __builtin_amdgcn_s_setprio(0); } while (0)
; #define PG8_WAIT_V(n) asm volatile("s_waitcnt vmcnt(" #n ")" ::: "memory")
; #define PG8_WAIT_L(n) asm volatile("s_waitcnt lgkmcnt(" #n ")" ::: "memory")
; #define PG8_BAR __builtin_amdgcn_s_barrier()
; #define PG8_SCHED __builtin_amdgcn_sched_barrier(0)
;     ...
;             PG8_STAGE(PG8_SB(0, 1), b2 + hb2, voffB);
;             PG8_WAIT_V(6); PG8_BAR; PG8_MMA(1, 1, At, B1); PG8_BAR;
;             PG8_LDB(B0, 1, 0); PG8_SCHED; PG8_LDA(At, 1, 0); PG8_STAGE_A(PG8_SA(0, 1), a2, 1, r2);
;             PG8_WAIT_L(8); PG8_BAR; PG8_WAIT_L(0); PG8_MMA(0, 0, At, B0); PG8_BAR; PG8_SCHED;
;             PG8_LDB(B1, 1, 1); PG8_STAGE(PG8_SB(1, 0), b3, voffB);
;             PG8_BAR; PG8_WAIT_L(0); PG8_MMA(0, 1, At, B1); PG8_BAR;
;             PG8_LDA(At, 1, 1); PG8_STAGE_A(PG8_SA(1, 0), a3, 0, r3);
	s_add_u32 s20, s20, s91
	s_addc_u32 s21, s21, s90
	s_add_i32 s10, s10, s53
	v_lshl_add_u64 v[250:251], s[20:21], 0, v[130:131]
	s_mov_b32 m0, s10
	v_lshl_add_u64 v[190:191], s[20:21], 0, v[134:135]
	global_load_lds_dwordx4 v[250:251], off
	s_add_i32 m0, s10, 0x2000
	s_nop 0
	global_load_lds_dwordx4 v[190:191], off
	v_add_u32_e32 v160, 0x18000, v139
	ds_read_b128 v[156:159], v160
	ds_read_b128 v[168:171], v160 offset:1024
	ds_read_b128 v[172:175], v160 offset:2048
	ds_read_b128 v[176:179], v160 offset:3072
	s_waitcnt vmcnt(10)
	s_barrier
	v_mfma_f32_16x16x32_bf16 v[52:55], v[232:235], v[180:183], v[52:55]
	v_mfma_f32_16x16x32_bf16 v[48:51], v[240:243], v[180:183], v[48:51]
	v_mfma_f32_16x16x32_bf16 v[36:39], v[232:235], v[208:211], v[36:39]
	v_mfma_f32_16x16x32_bf16 v[32:35], v[240:243], v[208:211], v[32:35]
	v_mfma_f32_16x16x32_bf16 v[20:23], v[232:235], v[216:219], v[20:23]
	v_mfma_f32_16x16x32_bf16 v[16:19], v[240:243], v[216:219], v[16:19]
	v_mfma_f32_16x16x32_bf16 v[4:7], v[232:235], v[224:227], v[4:7]
	v_mfma_f32_16x16x32_bf16 v[0:3], v[240:243], v[224:227], v[0:3]
	v_mfma_f32_16x16x32_bf16 v[52:55], v[236:239], v[204:207], v[52:55]
	v_mfma_f32_16x16x32_bf16 v[48:51], v[244:247], v[204:207], v[48:51]
	v_mfma_f32_16x16x32_bf16 v[36:39], v[236:239], v[212:215], v[36:39]
	v_mfma_f32_16x16x32_bf16 v[32:35], v[244:247], v[212:215], v[32:35]
	v_mfma_f32_16x16x32_bf16 v[20:23], v[236:239], v[220:223], v[20:23]
	v_mfma_f32_16x16x32_bf16 v[16:19], v[244:247], v[220:223], v[16:19]
	v_mfma_f32_16x16x32_bf16 v[4:7], v[236:239], v[228:231], v[4:7]
	v_mfma_f32_16x16x32_bf16 v[0:3], v[244:247], v[228:231], v[0:3]
	s_add_i32 s10, 0, 0x18000
	s_barrier
	s_add_u32 s16, s16, 0x80000
	s_addc_u32 s17, s17, 0
	s_mov_b32 m0, s68
	v_lshl_add_u64 v[232:233], s[16:17], 0, v[128:129]
	ds_read_b128 v[180:183], v155 offset:32768
	ds_read_b128 v[204:207], v155 offset:33792
	ds_read_b128 v[208:211], v155 offset:34816
	ds_read_b128 v[212:215], v155 offset:35840
	ds_read_b128 v[216:219], v155 offset:36864
	ds_read_b128 v[220:223], v155 offset:37888
	ds_read_b128 v[224:227], v155 offset:38912
	ds_read_b128 v[228:231], v155 offset:39936
	global_load_lds_dwordx4 v[232:233], off
	v_lshl_add_u64 v[232:233], s[16:17], 0, v[132:133]
	s_mov_b32 m0, s69
	s_nop 0
	global_load_lds_dwordx4 v[232:233], off
	s_waitcnt lgkmcnt(8)
	s_waitcnt vmcnt(10)
	s_barrier
	s_waitcnt lgkmcnt(0)
	s_waitcnt lgkmcnt(0)
	v_mfma_f32_16x16x32_bf16 v[124:127], v[156:159], v[180:183], v[124:127]
	v_mfma_f32_16x16x32_bf16 v[120:123], v[172:175], v[180:183], v[120:123]
	v_mfma_f32_16x16x32_bf16 v[108:111], v[156:159], v[208:211], v[108:111]
	v_mfma_f32_16x16x32_bf16 v[104:107], v[172:175], v[208:211], v[104:107]
	v_mfma_f32_16x16x32_bf16 v[92:95], v[156:159], v[216:219], v[92:95]
	v_mfma_f32_16x16x32_bf16 v[88:91], v[172:175], v[216:219], v[88:91]
	v_mfma_f32_16x16x32_bf16 v[76:79], v[156:159], v[224:227], v[76:79]
	v_mfma_f32_16x16x32_bf16 v[72:75], v[172:175], v[224:227], v[72:75]
	v_mfma_f32_16x16x32_bf16 v[124:127], v[168:171], v[204:207], v[124:127]
	v_mfma_f32_16x16x32_bf16 v[120:123], v[176:179], v[204:207], v[120:123]
	v_mfma_f32_16x16x32_bf16 v[108:111], v[168:171], v[212:215], v[108:111]
	v_mfma_f32_16x16x32_bf16 v[104:107], v[176:179], v[212:215], v[104:107]
	v_mfma_f32_16x16x32_bf16 v[92:95], v[168:171], v[220:223], v[92:95]
	v_mfma_f32_16x16x32_bf16 v[88:91], v[176:179], v[220:223], v[88:91]
	v_mfma_f32_16x16x32_bf16 v[76:79], v[168:171], v[228:231], v[76:79]
	v_mfma_f32_16x16x32_bf16 v[72:75], v[176:179], v[228:231], v[72:75]
	s_barrier
	s_add_i32 s11, 0, 0x1c000
	s_add_i32 s10, s10, s53
	v_add_u32_e32 v160, s11, v139
	v_lshl_add_u64 v[184:185], v[184:185], 0, s[28:29]
	s_mov_b32 m0, s10
	ds_read_b128 v[232:235], v160
	ds_read_b128 v[236:239], v160 offset:1024
	ds_read_b128 v[240:243], v160 offset:2048
	ds_read_b128 v[244:247], v160 offset:3072
	global_load_lds_dwordx4 v[184:185], off
	v_lshl_add_u64 v[184:185], v[248:249], 0, s[28:29]
	s_add_i32 m0, s10, 0x2000
	s_nop 0
	global_load_lds_dwordx4 v[184:185], off
	s_waitcnt vmcnt(10)
	s_barrier
	s_waitcnt lgkmcnt(0)
	s_waitcnt lgkmcnt(0)
	v_mfma_f32_16x16x32_bf16 v[116:119], v[232:235], v[180:183], v[116:119]
	v_mfma_f32_16x16x32_bf16 v[112:115], v[240:243], v[180:183], v[112:115]
	v_mfma_f32_16x16x32_bf16 v[100:103], v[232:235], v[208:211], v[100:103]
	v_mfma_f32_16x16x32_bf16 v[96:99], v[240:243], v[208:211], v[96:99]
	v_mfma_f32_16x16x32_bf16 v[84:87], v[232:235], v[216:219], v[84:87]
	v_mfma_f32_16x16x32_bf16 v[80:83], v[240:243], v[216:219], v[80:83]
	v_mfma_f32_16x16x32_bf16 v[68:71], v[232:235], v[224:227], v[68:71]
	v_mfma_f32_16x16x32_bf16 v[64:67], v[240:243], v[224:227], v[64:67]
	v_mfma_f32_16x16x32_bf16 v[116:119], v[236:239], v[204:207], v[116:119]
	v_mfma_f32_16x16x32_bf16 v[112:115], v[244:247], v[204:207], v[112:115]
	v_mfma_f32_16x16x32_bf16 v[100:103], v[236:239], v[212:215], v[100:103]
	v_mfma_f32_16x16x32_bf16 v[96:99], v[244:247], v[212:215], v[96:99]
	v_mfma_f32_16x16x32_bf16 v[84:87], v[236:239], v[220:223], v[84:87]
	v_mfma_f32_16x16x32_bf16 v[80:83], v[244:247], v[220:223], v[80:83]
	v_mfma_f32_16x16x32_bf16 v[68:71], v[236:239], v[228:231], v[68:71]
	v_mfma_f32_16x16x32_bf16 v[64:67], v[244:247], v[228:231], v[64:67]
	s_mov_b32 m0, s70
	v_lshl_add_u64 v[184:185], s[14:15], 0, v[128:129]
	s_barrier
; __device__ __forceinline__ unsigned cvt_pk_bf16(float lo, float hi) { unsigned r; asm volatile("v_cvt_pk_bf16_f32 %0, %1, %2" : "=v"(r) : "v"(lo), "v"(hi)); return r; }
; #define PG8_STAGE(bufoff, gbase, voff) do { _Pragma("unroll") for (int _i = 0; _i < 2; ++_i) \
;         __builtin_amdgcn_global_load_lds((const unsigned*)((const char*)(gbase) + (voff)[_i]), (LAS unsigned*)(lds + (bufoff) + ldsw + _i * 8192), 16, 0, 0); } while (0)
; #define PG8_WAIT_V(n) asm volatile("s_waitcnt vmcnt(" #n ")" ::: "memory")
; #define PG8_WAIT_L(n) asm volatile("s_waitcnt lgkmcnt(" #n ")" ::: "memory")
; #define PG8_BAR __builtin_amdgcn_s_barrier()
; #define PG8_SCHED __builtin_amdgcn_sched_barrier(0)
;     ...
;             PG8_BAR; PG8_WAIT_L(0); PG8_MMA(1, 0, At, B0); PG8_BAR; PG8_SCHED;
;             PG8_STAGE(PG8_SB(1, 1), b3 + hb2, voffB);
;             PG8_WAIT_V(6); PG8_BAR; PG8_MMA(1, 1, At, B1); PG8_BAR;
;     __device__ __forceinline__ void generic(const f32x4 (&acc)[2][2][4][2], const Unit& u, int wr, int wc, int fr, int fq) const {
;     ...
;                         if (u.pm < 8 && u.pn < 128) {
;                             if (bj == 0) {
;                                 const f32x4 a0 = acc[ai][0][m][0], a1 = acc[ai][0][m][1], b0 = acc[ai][1][m][0], b1 = acc[ai][1][m][1];
;                                 const f32x4 e0 = a0 + b0, e1 = a1 + b1, o0 = a0 - b0, o1 = a1 - b1;
;                                 bf16_t* p = O + (size_t)(u.pm * BM + rt) * T + (u.pn >> 4) * 4096 + (u.pn & 15) * 128 + wc * 32 + 8 * fq;
;                                 u32x4 w; w.x = cvt_pk_bf16(e0[0], e0[1]); w.y = cvt_pk_bf16(e0[2], e0[3]); w.z = cvt_pk_bf16(e1[0], e1[1]); w.w = cvt_pk_bf16(e1[2], e1[3]);
;                                 *(u32x4*)p = w;
;                                 w.x = cvt_pk_bf16(o0[0], o0[1]); w.y = cvt_pk_bf16(o0[2], o0[3]); w.z = cvt_pk_bf16(o1[0], o1[1]); w.w = cvt_pk_bf16(o1[2], o1[3]);
;                                 *(u32x4*)(p + 2048) = w;
;                             }
;                         } else {
;                             u32x4 w; w.x = cvt_pk_bf16(v0[0], v0[1]); w.y = cvt_pk_bf16(v0[2], v0[3]); w.z = cvt_pk_bf16(v1[0], v1[1]); w.w = cvt_pk_bf16(v1[2], v1[3]);
;                             *(u32x4*)(O + (size_t)(u.pm * BM + rt) * T + u.pn * BM + ct) = w;
	ds_read_b128 v[180:183], v155 offset:49152
	ds_read_b128 v[204:207], v155 offset:50176
	ds_read_b128 v[208:211], v155 offset:51200
	ds_read_b128 v[212:215], v155 offset:52224
	ds_read_b128 v[216:219], v155 offset:53248
	ds_read_b128 v[220:223], v155 offset:54272
	ds_read_b128 v[224:227], v155 offset:55296
	ds_read_b128 v[228:231], v155 offset:56320
	global_load_lds_dwordx4 v[184:185], off
	v_lshl_add_u64 v[184:185], s[14:15], 0, v[132:133]
	s_mov_b32 m0, s71
	s_nop 0
	global_load_lds_dwordx4 v[184:185], off
	s_waitcnt vmcnt(10)
	s_barrier
	s_waitcnt lgkmcnt(0)
	s_waitcnt lgkmcnt(0)
	v_mfma_f32_16x16x32_bf16 v[60:63], v[156:159], v[180:183], v[60:63]
	v_mfma_f32_16x16x32_bf16 v[56:59], v[172:175], v[180:183], v[56:59]
	v_mfma_f32_16x16x32_bf16 v[44:47], v[156:159], v[208:211], v[44:47]
	v_mfma_f32_16x16x32_bf16 v[40:43], v[172:175], v[208:211], v[40:43]
	v_mfma_f32_16x16x32_bf16 v[28:31], v[156:159], v[216:219], v[28:31]
	v_mfma_f32_16x16x32_bf16 v[24:27], v[172:175], v[216:219], v[24:27]
	v_mfma_f32_16x16x32_bf16 v[12:15], v[156:159], v[224:227], v[12:15]
	v_mfma_f32_16x16x32_bf16 v[8:11], v[172:175], v[224:227], v[8:11]
	v_mfma_f32_16x16x32_bf16 v[60:63], v[168:171], v[204:207], v[60:63]
	v_mfma_f32_16x16x32_bf16 v[56:59], v[176:179], v[204:207], v[56:59]
	v_mfma_f32_16x16x32_bf16 v[44:47], v[168:171], v[212:215], v[44:47]
	v_mfma_f32_16x16x32_bf16 v[40:43], v[176:179], v[212:215], v[40:43]
	v_mfma_f32_16x16x32_bf16 v[28:31], v[168:171], v[220:223], v[28:31]
	v_mfma_f32_16x16x32_bf16 v[24:27], v[176:179], v[220:223], v[24:27]
	v_mfma_f32_16x16x32_bf16 v[12:15], v[168:171], v[228:231], v[12:15]
	v_mfma_f32_16x16x32_bf16 v[8:11], v[176:179], v[228:231], v[8:11]
	s_barrier
	s_add_i32 s10, s11, s53
	v_lshl_add_u64 v[156:157], v[250:251], 0, s[28:29]
	s_mov_b32 m0, s10
	s_nop 0
	global_load_lds_dwordx4 v[156:157], off
	v_lshl_add_u64 v[156:157], v[190:191], 0, s[28:29]
	s_add_i32 m0, s10, 0x2000
	s_nop 0
	global_load_lds_dwordx4 v[156:157], off
	v_add_u32_e32 v160, 0x10000, v139
	ds_read_b128 v[156:159], v160
	ds_read_b128 v[168:171], v160 offset:1024
	ds_read_b128 v[172:175], v160 offset:2048
	ds_read_b128 v[176:179], v160 offset:3072
	s_waitcnt vmcnt(10)
	s_barrier
	v_mfma_f32_16x16x32_bf16 v[52:55], v[232:235], v[180:183], v[52:55]
	v_mfma_f32_16x16x32_bf16 v[48:51], v[240:243], v[180:183], v[48:51]
	v_mfma_f32_16x16x32_bf16 v[36:39], v[232:235], v[208:211], v[36:39]
	v_mfma_f32_16x16x32_bf16 v[32:35], v[240:243], v[208:211], v[32:35]
	v_mfma_f32_16x16x32_bf16 v[20:23], v[232:235], v[216:219], v[20:23]
	v_mfma_f32_16x16x32_bf16 v[16:19], v[240:243], v[216:219], v[16:19]
	v_mfma_f32_16x16x32_bf16 v[4:7], v[232:235], v[224:227], v[4:7]
	v_mfma_f32_16x16x32_bf16 v[0:3], v[240:243], v[224:227], v[0:3]
	v_mfma_f32_16x16x32_bf16 v[52:55], v[236:239], v[204:207], v[52:55]
	v_mfma_f32_16x16x32_bf16 v[48:51], v[244:247], v[204:207], v[48:51]
	v_mfma_f32_16x16x32_bf16 v[36:39], v[236:239], v[212:215], v[36:39]
	v_mfma_f32_16x16x32_bf16 v[32:35], v[244:247], v[212:215], v[32:35]
	v_mfma_f32_16x16x32_bf16 v[20:23], v[236:239], v[220:223], v[20:23]
	v_mfma_f32_16x16x32_bf16 v[16:19], v[244:247], v[220:223], v[16:19]
	v_mfma_f32_16x16x32_bf16 v[4:7], v[236:239], v[228:231], v[4:7]
	v_mfma_f32_16x16x32_bf16 v[0:3], v[244:247], v[228:231], v[0:3]
	s_add_i32 s22, s22, 2
	s_add_u32 s0, s0, 0x100
	s_addc_u32 s1, s1, 0
	s_cmp_gt_u32 s22, 29
	s_barrier
	s_cbranch_scc0 .LBB0_522
	s_waitcnt lgkmcnt(0)
	s_cmp_gt_i32 s89, 7
	s_cselect_b64 s[0:1], -1, 0
	s_cmpk_gt_i32 s5, 0x7f
	s_cselect_b64 s[2:3], -1, 0
	s_or_b64 s[0:1], s[0:1], s[2:3]
	s_mov_b64 s[2:3], -1
	s_and_b64 vcc, exec, s[0:1]
	v_lshl_add_u32 v146, s89, 8, v137
	v_lshlrev_b32_e32 v144, 1, v138
	s_cbranch_vccz .LBB0_525
	v_mov_b64_e32 v[168:169], s[24:25]
	v_mad_i64_i32 v[168:169], s[2:3], v146, s80, v[168:169]
	s_lshl_b32 s2, s5, 8
	s_ashr_i32 s3, s2, 31
	v_lshl_add_u64 v[168:169], s[2:3], 1, v[168:169]
	v_mov_b32_e32 v145, v161
	v_lshl_add_u64 v[168:169], v[168:169], 0, v[144:145]
	v_cvt_pk_bf16_f32 v156, v124, v125
	v_cvt_pk_bf16_f32 v157, v126, v127
	v_cvt_pk_bf16_f32 v158, v120, v121
	v_cvt_pk_bf16_f32 v159, v122, v123
	global_store_dwordx4 v[168:169], v[156:159], off
	s_mov_b64 s[2:3], 0

; #define PG8_STAGE(bufoff, gbase, voff) do { _Pragma("unroll") for (int _i = 0; _i < 2; ++_i) \
;         __builtin_amdgcn_global_load_lds((const unsigned*)((const char*)(gbase) + (voff)[_i]), (LAS unsigned*)(lds + (bufoff) + ldsw + _i * 8192), 16, 0, 0); } while (0)
; #define PG8_STAGE_A(bufoff, ptr, half, rev) do { if (REVA && (rev)) { const char* _p = (ptr) - ((half) ? hstepA : 0); PG8_STAGE(bufoff, _p, voffAr); } else { const char* _p = (ptr) + ((half) ? hstepA : 0); PG8_STAGE(bufoff, _p, voffA); } } while (0)
; #define PG8_LDA(dst, b, h) do { _Pragma("unroll") for (int m = 0; m < 4; ++m) _Pragma("unroll") for (int k = 0; k < 2; ++k) dst[m][k] = *(const LAS bf16x8*)(lds + PG8_SA(b, h) + aoff + m * 2048 + k * 1024); } while (0)
; #define PG8_LDB(dst, b, h) do { _Pragma("unroll") for (int n = 0; n < 2; ++n) _Pragma("unroll") for (int k = 0; k < 2; ++k) dst[n][k] = *(const LAS bf16x8*)(lds + PG8_SB(b, h) + boff + n * 2048 + k * 1024); } while (0)
; #define PG8_MMA(ai, bj, At, Bt) do { __builtin_amdgcn_s_setprio(1); _Pragma("unroll") for (int m = 0; m < 4; ++m) _Pragma("unroll") for (int n = 0; n < 2; ++n) _Pragma("unroll") for (int k = 0; k < 2; ++k) \
;         acc[ai][bj][m][n] = __builtin_amdgcn_mfma_f32_16x16x32_bf16(Bt[n][k], At[m][k], acc[ai][bj][m][n], 0, 0, 0); __builtin_amdgcn_s_setprio(0); } while (0)
; #define PG8_WAIT_L(n) asm volatile("s_waitcnt lgkmcnt(" #n ")" ::: "memory")
; #define PG8_BAR __builtin_amdgcn_s_barrier()
; #define PG8_SCHED __builtin_amdgcn_sched_barrier(0)
;     ...
;             PG8_LDB(B0, 0, 0); PG8_SCHED; PG8_LDA(At, 0, 0); PG8_STAGE_A(PG8_SA(1, 1), a1, 1, r1);
;             PG8_WAIT_L(8); PG8_BAR; PG8_WAIT_L(0); PG8_MMA(0, 0, At, B0); PG8_BAR; PG8_SCHED;
;             PG8_LDB(B1, 0, 1); PG8_STAGE(PG8_SB(0, 0), b2, voffB);
;             PG8_BAR; PG8_WAIT_L(0); PG8_MMA(0, 1, At, B1); PG8_BAR;
;             PG8_LDA(At, 0, 1); PG8_STAGE_A(PG8_SA(0, 0), a2, 0, r2);
;             PG8_BAR; PG8_WAIT_L(0); PG8_MMA(1, 0, At, B0); PG8_BAR; PG8_SCHED;
.LBB0_567:
	s_add_u32 s10, s38, s0
	s_addc_u32 s11, s39, s1
	s_add_u32 s16, s10, 0x100
	s_addc_u32 s17, s11, 0
	s_add_u32 s10, s10, 0x180
	s_addc_u32 s11, s11, 0
	s_add_u32 s14, s52, s0
	s_addc_u32 s15, s53, s1
	s_add_i32 s67, 0, 0x10000
	s_cmpk_eq_i32 s0, 0xf00
	s_cselect_b32 s15, s45, s15
	s_cselect_b32 s14, s44, s14
	s_cselect_b32 s21, s37, s17
	s_cselect_b32 s20, s36, s16
	s_cselect_b32 s17, s27, s11
	s_cselect_b32 s16, s25, s10
	v_lshl_add_u64 v[158:159], v[140:141], 0, s[0:1]
	s_add_i32 m0, s22, 0xc000
	ds_read_b128 v[176:179], v149
	ds_read_b128 v[180:183], v149 offset:1024
	ds_read_b128 v[204:207], v149 offset:2048
	ds_read_b128 v[208:211], v149 offset:3072
	ds_read_b128 v[212:215], v149 offset:4096
	ds_read_b128 v[216:219], v149 offset:5120
	ds_read_b128 v[220:223], v149 offset:6144
	ds_read_b128 v[224:227], v149 offset:7168
	global_load_lds_dwordx4 v[158:159], off
	v_lshl_add_u64 v[158:159], v[142:143], 0, s[0:1]
	s_add_i32 m0, s22, 0xe000
	s_nop 0
	global_load_lds_dwordx4 v[158:159], off
	s_waitcnt lgkmcnt(8)
	s_waitcnt vmcnt(10)
	s_barrier
	s_waitcnt lgkmcnt(0)
	s_waitcnt lgkmcnt(0)
	v_mfma_f32_16x16x32_bf16 v[124:127], v[150:153], v[176:179], v[124:127]
	v_mfma_f32_16x16x32_bf16 v[120:123], v[168:171], v[176:179], v[120:123]
	v_mfma_f32_16x16x32_bf16 v[116:119], v[150:153], v[204:207], v[116:119]
	v_mfma_f32_16x16x32_bf16 v[108:111], v[168:171], v[204:207], v[108:111]
	v_mfma_f32_16x16x32_bf16 v[100:103], v[150:153], v[212:215], v[100:103]
	v_mfma_f32_16x16x32_bf16 v[92:95], v[168:171], v[212:215], v[92:95]
	v_mfma_f32_16x16x32_bf16 v[84:87], v[150:153], v[220:223], v[84:87]
	v_mfma_f32_16x16x32_bf16 v[76:79], v[168:171], v[220:223], v[76:79]
	v_mfma_f32_16x16x32_bf16 v[124:127], v[154:157], v[180:183], v[124:127]
	v_mfma_f32_16x16x32_bf16 v[120:123], v[172:175], v[180:183], v[120:123]
	v_mfma_f32_16x16x32_bf16 v[116:119], v[154:157], v[208:211], v[116:119]
	v_mfma_f32_16x16x32_bf16 v[108:111], v[172:175], v[208:211], v[108:111]
	v_mfma_f32_16x16x32_bf16 v[100:103], v[154:157], v[216:219], v[100:103]
	v_mfma_f32_16x16x32_bf16 v[92:95], v[172:175], v[216:219], v[92:95]
	v_mfma_f32_16x16x32_bf16 v[84:87], v[154:157], v[224:227], v[84:87]
	v_mfma_f32_16x16x32_bf16 v[76:79], v[172:175], v[224:227], v[76:79]
	s_barrier
	s_add_i32 s10, 0, 0x14000
	v_add_u32_e32 v158, s10, v145
	s_add_i32 s11, s67, s5
	ds_read_b128 v[228:231], v158
	ds_read_b128 v[232:235], v158 offset:1024
	ds_read_b128 v[236:239], v158 offset:2048
	ds_read_b128 v[240:243], v158 offset:3072
	v_lshl_add_u64 v[158:159], s[14:15], 0, v[132:133]
	s_mov_b32 m0, s11
	v_lshl_add_u64 v[184:185], s[14:15], 0, v[128:129]
	global_load_lds_dwordx4 v[158:159], off
	s_add_i32 m0, s11, 0x2000
	s_nop 0
	global_load_lds_dwordx4 v[184:185], off
	s_waitcnt vmcnt(10)
	s_barrier
	s_waitcnt lgkmcnt(0)
	s_waitcnt lgkmcnt(0)
	v_mfma_f32_16x16x32_bf16 v[112:115], v[228:231], v[176:179], v[112:115]
	v_mfma_f32_16x16x32_bf16 v[104:107], v[236:239], v[176:179], v[104:107]
	v_mfma_f32_16x16x32_bf16 v[96:99], v[228:231], v[204:207], v[96:99]
	v_mfma_f32_16x16x32_bf16 v[88:91], v[236:239], v[204:207], v[88:91]
	v_mfma_f32_16x16x32_bf16 v[80:83], v[228:231], v[212:215], v[80:83]
	v_mfma_f32_16x16x32_bf16 v[72:75], v[236:239], v[212:215], v[72:75]
	v_mfma_f32_16x16x32_bf16 v[68:71], v[228:231], v[220:223], v[68:71]
	v_mfma_f32_16x16x32_bf16 v[64:67], v[236:239], v[220:223], v[64:67]
	v_mfma_f32_16x16x32_bf16 v[112:115], v[232:235], v[180:183], v[112:115]
	v_mfma_f32_16x16x32_bf16 v[104:107], v[240:243], v[180:183], v[104:107]
	v_mfma_f32_16x16x32_bf16 v[96:99], v[232:235], v[208:211], v[96:99]
	v_mfma_f32_16x16x32_bf16 v[88:91], v[240:243], v[208:211], v[88:91]
	v_mfma_f32_16x16x32_bf16 v[80:83], v[232:235], v[216:219], v[80:83]
	v_mfma_f32_16x16x32_bf16 v[72:75], v[240:243], v[216:219], v[72:75]
	v_mfma_f32_16x16x32_bf16 v[68:71], v[232:235], v[224:227], v[68:71]
	v_mfma_f32_16x16x32_bf16 v[64:67], v[240:243], v[224:227], v[64:67]
	s_mov_b32 m0, s22
	v_lshl_add_u64 v[190:191], s[20:21], 0, v[134:135]
	s_barrier
	ds_read_b128 v[176:179], v149 offset:16384
	ds_read_b128 v[180:183], v149 offset:17408
	ds_read_b128 v[204:207], v149 offset:18432
	ds_read_b128 v[208:211], v149 offset:19456
	ds_read_b128 v[212:215], v149 offset:20480
	ds_read_b128 v[216:219], v149 offset:21504
	ds_read_b128 v[220:223], v149 offset:22528
	ds_read_b128 v[224:227], v149 offset:23552
	global_load_lds_dwordx4 v[190:191], off
	v_lshl_add_u64 v[190:191], s[20:21], 0, v[130:131]
	s_mov_b32 m0, s46
	s_nop 0
	global_load_lds_dwordx4 v[190:191], off
	s_waitcnt vmcnt(10)
	s_barrier
	s_waitcnt lgkmcnt(0)
	s_waitcnt lgkmcnt(0)
	v_mfma_f32_16x16x32_bf16 v[60:63], v[150:153], v[176:179], v[60:63]
	v_mfma_f32_16x16x32_bf16 v[56:59], v[168:171], v[176:179], v[56:59]
	v_mfma_f32_16x16x32_bf16 v[52:55], v[150:153], v[204:207], v[52:55]
	v_mfma_f32_16x16x32_bf16 v[44:47], v[168:171], v[204:207], v[44:47]
	v_mfma_f32_16x16x32_bf16 v[36:39], v[150:153], v[212:215], v[36:39]
	v_mfma_f32_16x16x32_bf16 v[28:31], v[168:171], v[212:215], v[28:31]
	v_mfma_f32_16x16x32_bf16 v[20:23], v[150:153], v[220:223], v[20:23]
	v_mfma_f32_16x16x32_bf16 v[12:15], v[168:171], v[220:223], v[12:15]
	v_mfma_f32_16x16x32_bf16 v[60:63], v[154:157], v[180:183], v[60:63]
	v_mfma_f32_16x16x32_bf16 v[56:59], v[172:175], v[180:183], v[56:59]
	v_mfma_f32_16x16x32_bf16 v[52:55], v[154:157], v[208:211], v[52:55]
	v_mfma_f32_16x16x32_bf16 v[44:47], v[172:175], v[208:211], v[44:47]
	v_mfma_f32_16x16x32_bf16 v[36:39], v[154:157], v[216:219], v[36:39]
	v_mfma_f32_16x16x32_bf16 v[28:31], v[172:175], v[216:219], v[28:31]
	v_mfma_f32_16x16x32_bf16 v[20:23], v[154:157], v[224:227], v[20:23]
	v_mfma_f32_16x16x32_bf16 v[12:15], v[172:175], v[224:227], v[12:15]
	s_barrier
; #define PG8_STAGE(bufoff, gbase, voff) do { _Pragma("unroll") for (int _i = 0; _i < 2; ++_i) \
;         __builtin_amdgcn_global_load_lds((const unsigned*)((const char*)(gbase) + (voff)[_i]), (LAS unsigned*)(lds + (bufoff) + ldsw + _i * 8192), 16, 0, 0); } while (0)
; #define PG8_STAGE_A(bufoff, ptr, half, rev) do { if (REVA && (rev)) { const char* _p = (ptr) - ((half) ? hstepA : 0); PG8_STAGE(bufoff, _p, voffAr); } else { const char* _p = (ptr) + ((half) ? hstepA : 0); PG8_STAGE(bufoff, _p, voffA); } } while (0)
; #define PG8_LDA(dst, b, h) do { _Pragma("unroll") for (int m = 0; m < 4; ++m) _Pragma("unroll") for (int k = 0; k < 2; ++k) dst[m][k] = *(const LAS bf16x8*)(lds + PG8_SA(b, h) + aoff + m * 2048 + k * 1024); } while (0)
; #define PG8_LDB(dst, b, h) do { _Pragma("unroll") for (int n = 0; n < 2; ++n) _Pragma("unroll") for (int k = 0; k < 2; ++k) dst[n][k] = *(const LAS bf16x8*)(lds + PG8_SB(b, h) + boff + n * 2048 + k * 1024); } while (0)
; #define PG8_MMA(ai, bj, At, Bt) do { __builtin_amdgcn_s_setprio(1); _Pragma("unroll") for (int m = 0; m < 4; ++m) _Pragma("unroll") for (int n = 0; n < 2; ++n) _Pragma("unroll") for (int k = 0; k < 2; ++k) \
;         acc[ai][bj][m][n] = __builtin_amdgcn_mfma_f32_16x16x32_bf16(Bt[n][k], At[m][k], acc[ai][bj][m][n], 0, 0, 0); __builtin_amdgcn_s_setprio(0); } while (0)
; #define PG8_WAIT_V(n) asm volatile("s_waitcnt vmcnt(" #n ")" ::: "memory")
; #define PG8_WAIT_L(n) asm volatile("s_waitcnt lgkmcnt(" #n ")" ::: "memory")
; #define PG8_BAR __builtin_amdgcn_s_barrier()
; #define PG8_SCHED __builtin_amdgcn_sched_barrier(0)
;     ...
;             PG8_STAGE(PG8_SB(0, 1), b2 + hb2, voffB);
;             PG8_WAIT_V(6); PG8_BAR; PG8_MMA(1, 1, At, B1); PG8_BAR;
;             PG8_LDB(B0, 1, 0); PG8_SCHED; PG8_LDA(At, 1, 0); PG8_STAGE_A(PG8_SA(0, 1), a2, 1, r2);
;             PG8_WAIT_L(8); PG8_BAR; PG8_WAIT_L(0); PG8_MMA(0, 0, At, B0); PG8_BAR; PG8_SCHED;
;             PG8_LDB(B1, 1, 1); PG8_STAGE(PG8_SB(1, 0), b3, voffB);
;             PG8_BAR; PG8_WAIT_L(0); PG8_MMA(0, 1, At, B1); PG8_BAR;
;             PG8_LDA(At, 1, 1); PG8_STAGE_A(PG8_SA(1, 0), a3, 0, r3);
	s_add_u32 s68, s14, 0x80000
	s_addc_u32 s69, s15, 0
	s_add_i32 s10, s10, s5
	v_lshl_add_u64 v[150:151], s[68:69], 0, v[132:133]
	s_mov_b32 m0, s10
	s_nop 0
	global_load_lds_dwordx4 v[150:151], off
	v_lshl_add_u64 v[150:151], s[68:69], 0, v[128:129]
	s_add_i32 m0, s10, 0x2000
	s_nop 0
	global_load_lds_dwordx4 v[150:151], off
	v_add_u32_e32 v172, 0x18000, v145
	ds_read_b128 v[150:153], v172
	ds_read_b128 v[154:157], v172 offset:1024
	ds_read_b128 v[168:171], v172 offset:2048
	ds_read_b128 v[172:175], v172 offset:3072
	s_waitcnt vmcnt(10)
	s_barrier
	v_mfma_f32_16x16x32_bf16 v[48:51], v[228:231], v[176:179], v[48:51]
	v_mfma_f32_16x16x32_bf16 v[40:43], v[236:239], v[176:179], v[40:43]
	v_mfma_f32_16x16x32_bf16 v[32:35], v[228:231], v[204:207], v[32:35]
	v_mfma_f32_16x16x32_bf16 v[24:27], v[236:239], v[204:207], v[24:27]
	v_mfma_f32_16x16x32_bf16 v[16:19], v[228:231], v[212:215], v[16:19]
	v_mfma_f32_16x16x32_bf16 v[8:11], v[236:239], v[212:215], v[8:11]
	v_mfma_f32_16x16x32_bf16 v[4:7], v[228:231], v[220:223], v[4:7]
	v_mfma_f32_16x16x32_bf16 v[0:3], v[236:239], v[220:223], v[0:3]
	v_mfma_f32_16x16x32_bf16 v[48:51], v[232:235], v[180:183], v[48:51]
	v_mfma_f32_16x16x32_bf16 v[40:43], v[240:243], v[180:183], v[40:43]
	v_mfma_f32_16x16x32_bf16 v[32:35], v[232:235], v[208:211], v[32:35]
	v_mfma_f32_16x16x32_bf16 v[24:27], v[240:243], v[208:211], v[24:27]
	v_mfma_f32_16x16x32_bf16 v[16:19], v[232:235], v[216:219], v[16:19]
	v_mfma_f32_16x16x32_bf16 v[8:11], v[240:243], v[216:219], v[8:11]
	v_mfma_f32_16x16x32_bf16 v[4:7], v[232:235], v[224:227], v[4:7]
	v_mfma_f32_16x16x32_bf16 v[0:3], v[240:243], v[224:227], v[0:3]
	s_add_i32 s10, 0, 0x18000
	s_barrier
	s_add_u32 s20, s20, 0x80000
	s_addc_u32 s21, s21, 0
	s_mov_b32 m0, s47
	v_lshl_add_u64 v[190:191], s[20:21], 0, v[134:135]
	ds_read_b128 v[176:179], v149 offset:32768
	ds_read_b128 v[180:183], v149 offset:33792
	ds_read_b128 v[204:207], v149 offset:34816
	ds_read_b128 v[208:211], v149 offset:35840
	ds_read_b128 v[212:215], v149 offset:36864
	ds_read_b128 v[216:219], v149 offset:37888
	ds_read_b128 v[220:223], v149 offset:38912
	ds_read_b128 v[224:227], v149 offset:39936
	global_load_lds_dwordx4 v[190:191], off
	v_lshl_add_u64 v[190:191], s[20:21], 0, v[130:131]
	s_mov_b32 m0, s50
	s_nop 0
	global_load_lds_dwordx4 v[190:191], off
	s_waitcnt lgkmcnt(8)
	s_waitcnt vmcnt(10)
	s_barrier
	s_waitcnt lgkmcnt(0)
	s_waitcnt lgkmcnt(0)
	v_mfma_f32_16x16x32_bf16 v[124:127], v[150:153], v[176:179], v[124:127]
	v_mfma_f32_16x16x32_bf16 v[120:123], v[168:171], v[176:179], v[120:123]
	v_mfma_f32_16x16x32_bf16 v[116:119], v[150:153], v[204:207], v[116:119]
	v_mfma_f32_16x16x32_bf16 v[108:111], v[168:171], v[204:207], v[108:111]
	v_mfma_f32_16x16x32_bf16 v[100:103], v[150:153], v[212:215], v[100:103]
	v_mfma_f32_16x16x32_bf16 v[92:95], v[168:171], v[212:215], v[92:95]
	v_mfma_f32_16x16x32_bf16 v[84:87], v[150:153], v[220:223], v[84:87]
	v_mfma_f32_16x16x32_bf16 v[76:79], v[168:171], v[220:223], v[76:79]
	v_mfma_f32_16x16x32_bf16 v[124:127], v[154:157], v[180:183], v[124:127]
	v_mfma_f32_16x16x32_bf16 v[120:123], v[172:175], v[180:183], v[120:123]
	v_mfma_f32_16x16x32_bf16 v[116:119], v[154:157], v[208:211], v[116:119]
	v_mfma_f32_16x16x32_bf16 v[108:111], v[172:175], v[208:211], v[108:111]
	v_mfma_f32_16x16x32_bf16 v[100:103], v[154:157], v[216:219], v[100:103]
	v_mfma_f32_16x16x32_bf16 v[92:95], v[172:175], v[216:219], v[92:95]
	v_mfma_f32_16x16x32_bf16 v[84:87], v[154:157], v[224:227], v[84:87]
	v_mfma_f32_16x16x32_bf16 v[76:79], v[172:175], v[224:227], v[76:79]
	s_barrier
	s_add_i32 s11, 0, 0x1c000
	s_add_i32 s10, s10, s5
	v_add_u32_e32 v190, s11, v145
	v_lshl_add_u64 v[158:159], v[158:159], 0, s[28:29]
	s_mov_b32 m0, s10
	ds_read_b128 v[228:231], v190
	ds_read_b128 v[232:235], v190 offset:1024
	ds_read_b128 v[236:239], v190 offset:2048
	ds_read_b128 v[240:243], v190 offset:3072
	global_load_lds_dwordx4 v[158:159], off
	v_lshl_add_u64 v[158:159], v[184:185], 0, s[28:29]
	s_add_i32 m0, s10, 0x2000
	s_nop 0
	global_load_lds_dwordx4 v[158:159], off
	s_waitcnt vmcnt(10)
	s_barrier
	s_waitcnt lgkmcnt(0)
	s_waitcnt lgkmcnt(0)
	v_mfma_f32_16x16x32_bf16 v[112:115], v[228:231], v[176:179], v[112:115]
	v_mfma_f32_16x16x32_bf16 v[104:107], v[236:239], v[176:179], v[104:107]
	v_mfma_f32_16x16x32_bf16 v[96:99], v[228:231], v[204:207], v[96:99]
	v_mfma_f32_16x16x32_bf16 v[88:91], v[236:239], v[204:207], v[88:91]
	v_mfma_f32_16x16x32_bf16 v[80:83], v[228:231], v[212:215], v[80:83]
	v_mfma_f32_16x16x32_bf16 v[72:75], v[236:239], v[212:215], v[72:75]
	v_mfma_f32_16x16x32_bf16 v[68:71], v[228:231], v[220:223], v[68:71]
	v_mfma_f32_16x16x32_bf16 v[64:67], v[236:239], v[220:223], v[64:67]
	v_mfma_f32_16x16x32_bf16 v[112:115], v[232:235], v[180:183], v[112:115]
	v_mfma_f32_16x16x32_bf16 v[104:107], v[240:243], v[180:183], v[104:107]
	v_mfma_f32_16x16x32_bf16 v[96:99], v[232:235], v[208:211], v[96:99]
	v_mfma_f32_16x16x32_bf16 v[88:91], v[240:243], v[208:211], v[88:91]
	v_mfma_f32_16x16x32_bf16 v[80:83], v[232:235], v[216:219], v[80:83]
	v_mfma_f32_16x16x32_bf16 v[72:75], v[240:243], v[216:219], v[72:75]
	v_mfma_f32_16x16x32_bf16 v[68:71], v[232:235], v[224:227], v[68:71]
	v_mfma_f32_16x16x32_bf16 v[64:67], v[240:243], v[224:227], v[64:67]
	s_mov_b32 m0, s48
	v_lshl_add_u64 v[158:159], s[16:17], 0, v[134:135]
	s_barrier
	ds_read_b128 v[176:179], v149 offset:49152
	ds_read_b128 v[180:183], v149 offset:50176
	ds_read_b128 v[204:207], v149 offset:51200
	ds_read_b128 v[208:211], v149 offset:52224
	ds_read_b128 v[212:215], v149 offset:53248
	ds_read_b128 v[216:219], v149 offset:54272
	ds_read_b128 v[220:223], v149 offset:55296
	ds_read_b128 v[224:227], v149 offset:56320
	global_load_lds_dwordx4 v[158:159], off
	v_lshl_add_u64 v[158:159], s[16:17], 0, v[130:131]
	s_mov_b32 m0, s49
	s_nop 0
	global_load_lds_dwordx4 v[158:159], off
	s_waitcnt vmcnt(10)
	s_barrier
; #define PG8_STAGE(bufoff, gbase, voff) do { _Pragma("unroll") for (int _i = 0; _i < 2; ++_i) \
;         __builtin_amdgcn_global_load_lds((const unsigned*)((const char*)(gbase) + (voff)[_i]), (LAS unsigned*)(lds + (bufoff) + ldsw + _i * 8192), 16, 0, 0); } while (0)
; #define PG8_MMA(ai, bj, At, Bt) do { __builtin_amdgcn_s_setprio(1); _Pragma("unroll") for (int m = 0; m < 4; ++m) _Pragma("unroll") for (int n = 0; n < 2; ++n) _Pragma("unroll") for (int k = 0; k < 2; ++k) \
;         acc[ai][bj][m][n] = __builtin_amdgcn_mfma_f32_16x16x32_bf16(Bt[n][k], At[m][k], acc[ai][bj][m][n], 0, 0, 0); __builtin_amdgcn_s_setprio(0); } while (0)
; #define PG8_WAIT_V(n) asm volatile("s_waitcnt vmcnt(" #n ")" ::: "memory")
; #define PG8_WAIT_L(n) asm volatile("s_waitcnt lgkmcnt(" #n ")" ::: "memory")
; #define PG8_BAR __builtin_amdgcn_s_barrier()
; #define PG8_SCHED __builtin_amdgcn_sched_barrier(0)
;     ...
;             PG8_BAR; PG8_WAIT_L(0); PG8_MMA(1, 0, At, B0); PG8_BAR; PG8_SCHED;
;             PG8_STAGE(PG8_SB(1, 1), b3 + hb2, voffB);
;             PG8_WAIT_V(6); PG8_BAR; PG8_MMA(1, 1, At, B1); PG8_BAR;
	s_waitcnt lgkmcnt(0)
	s_waitcnt lgkmcnt(0)
	v_mfma_f32_16x16x32_bf16 v[60:63], v[150:153], v[176:179], v[60:63]
	v_mfma_f32_16x16x32_bf16 v[56:59], v[168:171], v[176:179], v[56:59]
	v_mfma_f32_16x16x32_bf16 v[52:55], v[150:153], v[204:207], v[52:55]
	v_mfma_f32_16x16x32_bf16 v[44:47], v[168:171], v[204:207], v[44:47]
	v_mfma_f32_16x16x32_bf16 v[36:39], v[150:153], v[212:215], v[36:39]
	v_mfma_f32_16x16x32_bf16 v[28:31], v[168:171], v[212:215], v[28:31]
	v_mfma_f32_16x16x32_bf16 v[20:23], v[150:153], v[220:223], v[20:23]
	v_mfma_f32_16x16x32_bf16 v[12:15], v[168:171], v[220:223], v[12:15]
	v_mfma_f32_16x16x32_bf16 v[60:63], v[154:157], v[180:183], v[60:63]
	v_mfma_f32_16x16x32_bf16 v[56:59], v[172:175], v[180:183], v[56:59]
	v_mfma_f32_16x16x32_bf16 v[52:55], v[154:157], v[208:211], v[52:55]
	v_mfma_f32_16x16x32_bf16 v[44:47], v[172:175], v[208:211], v[44:47]
	v_mfma_f32_16x16x32_bf16 v[36:39], v[154:157], v[216:219], v[36:39]
	v_mfma_f32_16x16x32_bf16 v[28:31], v[172:175], v[216:219], v[28:31]
	v_mfma_f32_16x16x32_bf16 v[20:23], v[154:157], v[224:227], v[20:23]
	v_mfma_f32_16x16x32_bf16 v[12:15], v[172:175], v[224:227], v[12:15]
	s_barrier
	s_add_u32 s14, s14, 0x80080
	s_addc_u32 s15, s15, 0
	s_add_i32 s10, s11, s5
	v_lshl_add_u64 v[150:151], s[14:15], 0, v[132:133]
	s_mov_b32 m0, s10
	s_nop 0
	global_load_lds_dwordx4 v[150:151], off
	v_lshl_add_u64 v[150:151], s[14:15], 0, v[128:129]
	s_add_i32 m0, s10, 0x2000
	s_nop 0
	global_load_lds_dwordx4 v[150:151], off
	v_add_u32_e32 v158, 0x10000, v145
	ds_read_b128 v[150:153], v158
	ds_read_b128 v[154:157], v158 offset:1024
	ds_read_b128 v[168:171], v158 offset:2048
	ds_read_b128 v[172:175], v158 offset:3072
	s_waitcnt vmcnt(10)
	s_barrier
	v_mfma_f32_16x16x32_bf16 v[48:51], v[228:231], v[176:179], v[48:51]
	v_mfma_f32_16x16x32_bf16 v[40:43], v[236:239], v[176:179], v[40:43]
	v_mfma_f32_16x16x32_bf16 v[32:35], v[228:231], v[204:207], v[32:35]
	v_mfma_f32_16x16x32_bf16 v[24:27], v[236:239], v[204:207], v[24:27]
	v_mfma_f32_16x16x32_bf16 v[16:19], v[228:231], v[212:215], v[16:19]
	v_mfma_f32_16x16x32_bf16 v[8:11], v[236:239], v[212:215], v[8:11]
	v_mfma_f32_16x16x32_bf16 v[4:7], v[228:231], v[220:223], v[4:7]
	v_mfma_f32_16x16x32_bf16 v[0:3], v[236:239], v[220:223], v[0:3]
	v_mfma_f32_16x16x32_bf16 v[48:51], v[232:235], v[180:183], v[48:51]
	v_mfma_f32_16x16x32_bf16 v[40:43], v[240:243], v[180:183], v[40:43]
	v_mfma_f32_16x16x32_bf16 v[32:35], v[232:235], v[208:211], v[32:35]
	v_mfma_f32_16x16x32_bf16 v[24:27], v[240:243], v[208:211], v[24:27]
	v_mfma_f32_16x16x32_bf16 v[16:19], v[232:235], v[216:219], v[16:19]
	v_mfma_f32_16x16x32_bf16 v[8:11], v[240:243], v[216:219], v[8:11]
	v_mfma_f32_16x16x32_bf16 v[4:7], v[232:235], v[224:227], v[4:7]
	v_mfma_f32_16x16x32_bf16 v[0:3], v[240:243], v[224:227], v[0:3]
	s_add_i32 s66, s66, 2
	s_add_u32 s0, s0, 0x100
	s_addc_u32 s1, s1, 0
	s_cmp_gt_u32 s66, 29
	s_barrier
	s_cbranch_scc0 .LBB0_567
; __device__ __forceinline__ unsigned cvt_pk_bf16(float lo, float hi) { unsigned r; asm volatile("v_cvt_pk_bf16_f32 %0, %1, %2" : "=v"(r) : "v"(lo), "v"(hi)); return r; }
;     __device__ __forceinline__ void generic(const f32x4 (&acc)[2][2][4][2], const Unit& u, int wr, int wc, int fr, int fq) const {
;     ...
;                     } else if (MODE == 0) {
;                         u32x4 w; w.x = cvt_pk_bf16(v0[0], v0[1]); w.y = cvt_pk_bf16(v0[2], v0[3]); w.z = cvt_pk_bf16(v1[0], v1[1]); w.w = cvt_pk_bf16(v1[2], v1[3]);
;                         *(u32x4*)(O + (size_t)(u.pm * BM + rt) * ldc + u.pn * BM + ct) = w;
	s_waitcnt lgkmcnt(0)
	s_lshl_b32 s9, s9, 8
	v_cvt_pk_bf16_f32 v124, v124, v125
	v_cvt_pk_bf16_f32 v125, v126, v127
	v_cvt_pk_bf16_f32 v126, v120, v121
	v_add_u32_e32 v120, s9, v144
	v_ashrrev_i32_e32 v121, 31, v120
	s_lshl_b32 s0, s8, 8
	v_cvt_pk_bf16_f32 v127, v122, v123
	v_lshlrev_b64 v[122:123], 12, v[120:121]
	s_ashr_i32 s1, s0, 31
	v_lshl_add_u64 v[122:123], s[2:3], 0, v[122:123]
	s_lshl_b64 s[0:1], s[0:1], 1
	v_lshl_add_u64 v[122:123], v[122:123], 0, s[0:1]
	v_lshl_add_u64 v[122:123], v[122:123], 0, v[160:161]
	global_store_dwordx4 v[122:123], v[124:127], off
	v_cvt_pk_bf16_f32 v112, v112, v113
	v_cvt_pk_bf16_f32 v113, v114, v115
	v_cvt_pk_bf16_f32 v114, v104, v105
	v_cvt_pk_bf16_f32 v115, v106, v107
	global_store_dwordx4 v[122:123], v[112:115], off offset:256
	v_cvt_pk_bf16_f32 v104, v116, v117
	v_cvt_pk_bf16_f32 v105, v118, v119
	v_cvt_pk_bf16_f32 v106, v108, v109
	v_add_u32_e32 v108, s9, v146
	v_ashrrev_i32_e32 v109, 31, v108
	v_lshlrev_b64 v[108:109], 12, v[108:109]
	v_lshl_add_u64 v[108:109], s[2:3], 0, v[108:109]
	v_lshl_add_u64 v[108:109], v[108:109], 0, s[0:1]
	v_lshl_add_u64 v[108:109], v[108:109], 0, v[160:161]
	v_cvt_pk_bf16_f32 v107, v110, v111
	global_store_dwordx4 v[108:109], v[104:107], off
	v_cvt_pk_bf16_f32 v96, v96, v97
	v_cvt_pk_bf16_f32 v97, v98, v99
	v_cvt_pk_bf16_f32 v98, v88, v89
	v_cvt_pk_bf16_f32 v99, v90, v91
	global_store_dwordx4 v[108:109], v[96:99], off offset:256
	v_cvt_pk_bf16_f32 v88, v100, v101
	v_cvt_pk_bf16_f32 v89, v102, v103
	v_cvt_pk_bf16_f32 v90, v92, v93
	v_add_u32_e32 v92, s9, v147
	v_ashrrev_i32_e32 v93, 31, v92
	v_lshlrev_b64 v[92:93], 12, v[92:93]
	v_lshl_add_u64 v[92:93], s[2:3], 0, v[92:93]
	v_lshl_add_u64 v[92:93], v[92:93], 0, s[0:1]
	v_lshl_add_u64 v[92:93], v[92:93], 0, v[160:161]
	v_cvt_pk_bf16_f32 v91, v94, v95
	global_store_dwordx4 v[92:93], v[88:91], off
	v_cvt_pk_bf16_f32 v80, v80, v81
	v_cvt_pk_bf16_f32 v81, v82, v83
	v_cvt_pk_bf16_f32 v82, v72, v73
	v_cvt_pk_bf16_f32 v83, v74, v75
	global_store_dwordx4 v[92:93], v[80:83], off offset:256
	v_cvt_pk_bf16_f32 v72, v84, v85
	v_cvt_pk_bf16_f32 v73, v86, v87
	v_cvt_pk_bf16_f32 v74, v76, v77
	v_add_u32_e32 v76, s9, v148
	v_ashrrev_i32_e32 v77, 31, v76
	v_lshlrev_b64 v[76:77], 12, v[76:77]
	v_lshl_add_u64 v[76:77], s[2:3], 0, v[76:77]
	v_lshl_add_u64 v[76:77], v[76:77], 0, s[0:1]
	v_lshl_add_u64 v[76:77], v[76:77], 0, v[160:161]
	v_cvt_pk_bf16_f32 v75, v78, v79
	global_store_dwordx4 v[76:77], v[72:75], off
	v_cvt_pk_bf16_f32 v68, v68, v69
	v_cvt_pk_bf16_f32 v69, v70, v71
	v_cvt_pk_bf16_f32 v70, v64, v65
	v_cvt_pk_bf16_f32 v71, v66, v67
	global_store_dwordx4 v[76:77], v[68:71], off offset:256
	v_cvt_pk_bf16_f32 v60, v60, v61
	v_cvt_pk_bf16_f32 v61, v62, v63
	v_cvt_pk_bf16_f32 v62, v56, v57
	v_add_u32_e32 v56, 0x80, v120
	v_ashrrev_i32_e32 v57, 31, v56
	v_lshlrev_b64 v[56:57], 12, v[56:57]
	v_lshl_add_u64 v[56:57], s[2:3], 0, v[56:57]
	v_lshl_add_u64 v[56:57], v[56:57], 0, s[0:1]
	v_lshl_add_u64 v[56:57], v[56:57], 0, v[160:161]
	v_cvt_pk_bf16_f32 v63, v58, v59
	global_store_dwordx4 v[56:57], v[60:63], off
	v_cvt_pk_bf16_f32 v48, v48, v49
	v_cvt_pk_bf16_f32 v49, v50, v51
	v_cvt_pk_bf16_f32 v50, v40, v41
	v_cvt_pk_bf16_f32 v51, v42, v43
	global_store_dwordx4 v[56:57], v[48:51], off offset:256
	v_cvt_pk_bf16_f32 v40, v52, v53
	v_cvt_pk_bf16_f32 v41, v54, v55
	v_cvt_pk_bf16_f32 v42, v44, v45
	v_add_u32_e32 v44, 0x90, v120
	v_ashrrev_i32_e32 v45, 31, v44
	v_lshlrev_b64 v[44:45], 12, v[44:45]
	v_lshl_add_u64 v[44:45], s[2:3], 0, v[44:45]
	v_lshl_add_u64 v[44:45], v[44:45], 0, s[0:1]
	v_lshl_add_u64 v[44:45], v[44:45], 0, v[160:161]
	v_cvt_pk_bf16_f32 v43, v46, v47
	global_store_dwordx4 v[44:45], v[40:43], off
	v_cvt_pk_bf16_f32 v32, v32, v33
	v_cvt_pk_bf16_f32 v33, v34, v35
	v_cvt_pk_bf16_f32 v34, v24, v25
	v_cvt_pk_bf16_f32 v35, v26, v27
	global_store_dwordx4 v[44:45], v[32:35], off offset:256
	v_cvt_pk_bf16_f32 v24, v36, v37
	v_cvt_pk_bf16_f32 v25, v38, v39
	v_cvt_pk_bf16_f32 v26, v28, v29
	v_add_u32_e32 v28, 0xa0, v120
	v_ashrrev_i32_e32 v29, 31, v28
	v_lshlrev_b64 v[28:29], 12, v[28:29]
	v_lshl_add_u64 v[28:29], s[2:3], 0, v[28:29]
	v_lshl_add_u64 v[28:29], v[28:29], 0, s[0:1]
	v_lshl_add_u64 v[28:29], v[28:29], 0, v[160:161]
	v_cvt_pk_bf16_f32 v27, v30, v31
	global_store_dwordx4 v[28:29], v[24:27], off
	v_cvt_pk_bf16_f32 v16, v16, v17
	v_cvt_pk_bf16_f32 v17, v18, v19
	v_cvt_pk_bf16_f32 v18, v8, v9
	v_cvt_pk_bf16_f32 v19, v10, v11
	global_store_dwordx4 v[28:29], v[16:19], off offset:256
	v_cvt_pk_bf16_f32 v8, v20, v21
	v_cvt_pk_bf16_f32 v9, v22, v23
	v_cvt_pk_bf16_f32 v10, v12, v13
	v_add_u32_e32 v12, 0xb0, v120
	v_ashrrev_i32_e32 v13, 31, v12
	v_lshlrev_b64 v[12:13], 12, v[12:13]
	v_lshl_add_u64 v[12:13], s[2:3], 0, v[12:13]
	v_lshl_add_u64 v[12:13], v[12:13], 0, s[0:1]
	v_lshl_add_u64 v[12:13], v[12:13], 0, v[160:161]
	s_and_b64 vcc, exec, s[42:43]
	s_mov_b32 s8, s24
	s_mov_b32 s9, s26
	s_mov_b64 s[0:1], s[44:45]
	s_mov_b64 s[38:39], s[36:37]
	v_cvt_pk_bf16_f32 v11, v14, v15
	global_store_dwordx4 v[12:13], v[8:11], off
	v_cvt_pk_bf16_f32 v4, v4, v5
	v_cvt_pk_bf16_f32 v5, v6, v7
	v_cvt_pk_bf16_f32 v6, v0, v1
	v_cvt_pk_bf16_f32 v7, v2, v3
	global_store_dwordx4 v[12:13], v[4:7], off offset:256
	s_cbranch_vccz .LBB0_564
	s_waitcnt vmcnt(0)
	s_cmpk_gt_u32 s4, 0xff
	s_cbranch_scc1 .LBB0_571
	s_barrier

; #define PG8_STAGE(bufoff, gbase, voff) do { _Pragma("unroll") for (int _i = 0; _i < 2; ++_i) \
;         __builtin_amdgcn_global_load_lds((const unsigned*)((const char*)(gbase) + (voff)[_i]), (LAS unsigned*)(lds + (bufoff) + ldsw + _i * 8192), 16, 0, 0); } while (0)
; #define PG8_STAGE_A(bufoff, ptr, half, rev) do { if (REVA && (rev)) { const char* _p = (ptr) - ((half) ? hstepA : 0); PG8_STAGE(bufoff, _p, voffAr); } else { const char* _p = (ptr) + ((half) ? hstepA : 0); PG8_STAGE(bufoff, _p, voffA); } } while (0)
; #define PG8_LDA(dst, b, h) do { _Pragma("unroll") for (int m = 0; m < 4; ++m) _Pragma("unroll") for (int k = 0; k < 2; ++k) dst[m][k] = *(const LAS bf16x8*)(lds + PG8_SA(b, h) + aoff + m * 2048 + k * 1024); } while (0)
; #define PG8_LDB(dst, b, h) do { _Pragma("unroll") for (int n = 0; n < 2; ++n) _Pragma("unroll") for (int k = 0; k < 2; ++k) dst[n][k] = *(const LAS bf16x8*)(lds + PG8_SB(b, h) + boff + n * 2048 + k * 1024); } while (0)
; #define PG8_MMA(ai, bj, At, Bt) do { __builtin_amdgcn_s_setprio(1); _Pragma("unroll") for (int m = 0; m < 4; ++m) _Pragma("unroll") for (int n = 0; n < 2; ++n) _Pragma("unroll") for (int k = 0; k < 2; ++k) \
;         acc[ai][bj][m][n] = __builtin_amdgcn_mfma_f32_16x16x32_bf16(Bt[n][k], At[m][k], acc[ai][bj][m][n], 0, 0, 0); __builtin_amdgcn_s_setprio(0); } while (0)
; #define PG8_WAIT_L(n) asm volatile("s_waitcnt lgkmcnt(" #n ")" ::: "memory")
; #define PG8_BAR __builtin_amdgcn_s_barrier()
; #define PG8_SCHED __builtin_amdgcn_sched_barrier(0)
;     ...
;             PG8_LDB(B0, 0, 0); PG8_SCHED; PG8_LDA(At, 0, 0); PG8_STAGE_A(PG8_SA(1, 1), a1, 1, r1);
;             PG8_WAIT_L(8); PG8_BAR; PG8_WAIT_L(0); PG8_MMA(0, 0, At, B0); PG8_BAR; PG8_SCHED;
;             PG8_LDB(B1, 0, 1); PG8_STAGE(PG8_SB(0, 0), b2, voffB);
;             PG8_BAR; PG8_WAIT_L(0); PG8_MMA(0, 1, At, B1); PG8_BAR;
;             PG8_LDA(At, 0, 1); PG8_STAGE_A(PG8_SA(0, 0), a2, 0, r2);
;             PG8_BAR; PG8_WAIT_L(0); PG8_MMA(1, 0, At, B0); PG8_BAR; PG8_SCHED;
.LBB0_903:
	s_add_u32 s10, s38, s0
	s_addc_u32 s11, s39, s1
	s_add_u32 s20, s10, 0x100
	s_addc_u32 s21, s11, 0
	s_add_u32 s10, s10, 0x180
	s_addc_u32 s11, s11, 0
	s_add_u32 s14, s22, s0
	s_addc_u32 s15, s27, s1
	s_add_i32 s45, 0, 0x10000
	s_cmpk_eq_i32 s0, 0xf00
	s_cselect_b32 s15, s37, s15
	s_cselect_b32 s14, s36, s14
	s_cselect_b32 s17, s9, s11
	s_cselect_b32 s16, s8, s10
	s_cselect_b32 s21, s3, s21
	s_cselect_b32 s20, s2, s20
	v_lshl_add_u64 v[158:159], v[140:141], 0, s[0:1]
	s_add_i32 m0, s48, 0xc000
	ds_read_b128 v[180:183], v153
	ds_read_b128 v[204:207], v153 offset:1024
	ds_read_b128 v[208:211], v153 offset:2048
	ds_read_b128 v[212:215], v153 offset:3072
	ds_read_b128 v[216:219], v153 offset:4096
	ds_read_b128 v[220:223], v153 offset:5120
	ds_read_b128 v[224:227], v153 offset:6144
	ds_read_b128 v[228:231], v153 offset:7168
	global_load_lds_dwordx4 v[158:159], off
	v_lshl_add_u64 v[158:159], v[142:143], 0, s[0:1]
	s_add_i32 m0, s48, 0xe000
	s_nop 0
	global_load_lds_dwordx4 v[158:159], off
	s_waitcnt lgkmcnt(8)
	s_waitcnt vmcnt(10)
	s_barrier
	s_waitcnt lgkmcnt(0)
	s_waitcnt lgkmcnt(0)
	v_mfma_f32_16x16x32_bf16 v[124:127], v[154:157], v[180:183], v[124:127]
	v_mfma_f32_16x16x32_bf16 v[120:123], v[172:175], v[180:183], v[120:123]
	v_mfma_f32_16x16x32_bf16 v[108:111], v[154:157], v[208:211], v[108:111]
	v_mfma_f32_16x16x32_bf16 v[104:107], v[172:175], v[208:211], v[104:107]
	v_mfma_f32_16x16x32_bf16 v[92:95], v[154:157], v[216:219], v[92:95]
	v_mfma_f32_16x16x32_bf16 v[88:91], v[172:175], v[216:219], v[88:91]
	v_mfma_f32_16x16x32_bf16 v[76:79], v[154:157], v[224:227], v[76:79]
	v_mfma_f32_16x16x32_bf16 v[72:75], v[172:175], v[224:227], v[72:75]
	v_mfma_f32_16x16x32_bf16 v[124:127], v[168:171], v[204:207], v[124:127]
	v_mfma_f32_16x16x32_bf16 v[120:123], v[176:179], v[204:207], v[120:123]
	v_mfma_f32_16x16x32_bf16 v[108:111], v[168:171], v[212:215], v[108:111]
	v_mfma_f32_16x16x32_bf16 v[104:107], v[176:179], v[212:215], v[104:107]
	v_mfma_f32_16x16x32_bf16 v[92:95], v[168:171], v[220:223], v[92:95]
	v_mfma_f32_16x16x32_bf16 v[88:91], v[176:179], v[220:223], v[88:91]
	v_mfma_f32_16x16x32_bf16 v[76:79], v[168:171], v[228:231], v[76:79]
	v_mfma_f32_16x16x32_bf16 v[72:75], v[176:179], v[228:231], v[72:75]
	s_barrier
	s_add_i32 s10, 0, 0x14000
	v_add_u32_e32 v158, s10, v145
	s_add_i32 s11, s45, s47
	ds_read_b128 v[232:235], v158
	ds_read_b128 v[236:239], v158 offset:1024
	ds_read_b128 v[240:243], v158 offset:2048
	ds_read_b128 v[244:247], v158 offset:3072
	v_lshl_add_u64 v[158:159], s[14:15], 0, v[130:131]
	s_mov_b32 m0, s11
	v_lshl_add_u64 v[184:185], s[14:15], 0, v[134:135]
	global_load_lds_dwordx4 v[158:159], off
	s_add_i32 m0, s11, 0x2000
	s_nop 0
	global_load_lds_dwordx4 v[184:185], off
	s_waitcnt vmcnt(10)
	s_barrier
	s_waitcnt lgkmcnt(0)
	s_waitcnt lgkmcnt(0)
	v_mfma_f32_16x16x32_bf16 v[116:119], v[232:235], v[180:183], v[116:119]
	v_mfma_f32_16x16x32_bf16 v[112:115], v[240:243], v[180:183], v[112:115]
	v_mfma_f32_16x16x32_bf16 v[100:103], v[232:235], v[208:211], v[100:103]
	v_mfma_f32_16x16x32_bf16 v[96:99], v[240:243], v[208:211], v[96:99]
	v_mfma_f32_16x16x32_bf16 v[84:87], v[232:235], v[216:219], v[84:87]
	v_mfma_f32_16x16x32_bf16 v[80:83], v[240:243], v[216:219], v[80:83]
	v_mfma_f32_16x16x32_bf16 v[68:71], v[232:235], v[224:227], v[68:71]
	v_mfma_f32_16x16x32_bf16 v[64:67], v[240:243], v[224:227], v[64:67]
	v_mfma_f32_16x16x32_bf16 v[116:119], v[236:239], v[204:207], v[116:119]
	v_mfma_f32_16x16x32_bf16 v[112:115], v[244:247], v[204:207], v[112:115]
	v_mfma_f32_16x16x32_bf16 v[100:103], v[236:239], v[212:215], v[100:103]
	v_mfma_f32_16x16x32_bf16 v[96:99], v[244:247], v[212:215], v[96:99]
	v_mfma_f32_16x16x32_bf16 v[84:87], v[236:239], v[220:223], v[84:87]
	v_mfma_f32_16x16x32_bf16 v[80:83], v[244:247], v[220:223], v[80:83]
	v_mfma_f32_16x16x32_bf16 v[68:71], v[236:239], v[228:231], v[68:71]
	v_mfma_f32_16x16x32_bf16 v[64:67], v[244:247], v[228:231], v[64:67]
	s_mov_b32 m0, s48
	v_lshl_add_u64 v[190:191], s[20:21], 0, v[128:129]
	s_barrier
	ds_read_b128 v[180:183], v153 offset:16384
	ds_read_b128 v[204:207], v153 offset:17408
	ds_read_b128 v[208:211], v153 offset:18432
	ds_read_b128 v[212:215], v153 offset:19456
	ds_read_b128 v[216:219], v153 offset:20480
	ds_read_b128 v[220:223], v153 offset:21504
	ds_read_b128 v[224:227], v153 offset:22528
	ds_read_b128 v[228:231], v153 offset:23552
	global_load_lds_dwordx4 v[190:191], off
	v_lshl_add_u64 v[190:191], s[20:21], 0, v[132:133]
	s_mov_b32 m0, s49
	s_nop 0
	global_load_lds_dwordx4 v[190:191], off
	s_waitcnt vmcnt(10)
	s_barrier
	s_waitcnt lgkmcnt(0)
	s_waitcnt lgkmcnt(0)
	v_mfma_f32_16x16x32_bf16 v[60:63], v[154:157], v[180:183], v[60:63]
	v_mfma_f32_16x16x32_bf16 v[56:59], v[172:175], v[180:183], v[56:59]
	v_mfma_f32_16x16x32_bf16 v[44:47], v[154:157], v[208:211], v[44:47]
	v_mfma_f32_16x16x32_bf16 v[40:43], v[172:175], v[208:211], v[40:43]
	v_mfma_f32_16x16x32_bf16 v[28:31], v[154:157], v[216:219], v[28:31]
	v_mfma_f32_16x16x32_bf16 v[24:27], v[172:175], v[216:219], v[24:27]
	v_mfma_f32_16x16x32_bf16 v[12:15], v[154:157], v[224:227], v[12:15]
	v_mfma_f32_16x16x32_bf16 v[8:11], v[172:175], v[224:227], v[8:11]
	v_mfma_f32_16x16x32_bf16 v[60:63], v[168:171], v[204:207], v[60:63]
	v_mfma_f32_16x16x32_bf16 v[56:59], v[176:179], v[204:207], v[56:59]
	v_mfma_f32_16x16x32_bf16 v[44:47], v[168:171], v[212:215], v[44:47]
	v_mfma_f32_16x16x32_bf16 v[40:43], v[176:179], v[212:215], v[40:43]
	v_mfma_f32_16x16x32_bf16 v[28:31], v[168:171], v[220:223], v[28:31]
	v_mfma_f32_16x16x32_bf16 v[24:27], v[176:179], v[220:223], v[24:27]
	v_mfma_f32_16x16x32_bf16 v[12:15], v[168:171], v[228:231], v[12:15]
	v_mfma_f32_16x16x32_bf16 v[8:11], v[176:179], v[228:231], v[8:11]
	s_barrier
; #define PG8_STAGE(bufoff, gbase, voff) do { _Pragma("unroll") for (int _i = 0; _i < 2; ++_i) \
;         __builtin_amdgcn_global_load_lds((const unsigned*)((const char*)(gbase) + (voff)[_i]), (LAS unsigned*)(lds + (bufoff) + ldsw + _i * 8192), 16, 0, 0); } while (0)
; #define PG8_STAGE_A(bufoff, ptr, half, rev) do { if (REVA && (rev)) { const char* _p = (ptr) - ((half) ? hstepA : 0); PG8_STAGE(bufoff, _p, voffAr); } else { const char* _p = (ptr) + ((half) ? hstepA : 0); PG8_STAGE(bufoff, _p, voffA); } } while (0)
; #define PG8_LDA(dst, b, h) do { _Pragma("unroll") for (int m = 0; m < 4; ++m) _Pragma("unroll") for (int k = 0; k < 2; ++k) dst[m][k] = *(const LAS bf16x8*)(lds + PG8_SA(b, h) + aoff + m * 2048 + k * 1024); } while (0)
; #define PG8_LDB(dst, b, h) do { _Pragma("unroll") for (int n = 0; n < 2; ++n) _Pragma("unroll") for (int k = 0; k < 2; ++k) dst[n][k] = *(const LAS bf16x8*)(lds + PG8_SB(b, h) + boff + n * 2048 + k * 1024); } while (0)
; #define PG8_MMA(ai, bj, At, Bt) do { __builtin_amdgcn_s_setprio(1); _Pragma("unroll") for (int m = 0; m < 4; ++m) _Pragma("unroll") for (int n = 0; n < 2; ++n) _Pragma("unroll") for (int k = 0; k < 2; ++k) \
;         acc[ai][bj][m][n] = __builtin_amdgcn_mfma_f32_16x16x32_bf16(Bt[n][k], At[m][k], acc[ai][bj][m][n], 0, 0, 0); __builtin_amdgcn_s_setprio(0); } while (0)
; #define PG8_WAIT_V(n) asm volatile("s_waitcnt vmcnt(" #n ")" ::: "memory")
; #define PG8_WAIT_L(n) asm volatile("s_waitcnt lgkmcnt(" #n ")" ::: "memory")
; #define PG8_BAR __builtin_amdgcn_s_barrier()
; #define PG8_SCHED __builtin_amdgcn_sched_barrier(0)
;     ...
;             PG8_STAGE(PG8_SB(0, 1), b2 + hb2, voffB);
;             PG8_WAIT_V(6); PG8_BAR; PG8_MMA(1, 1, At, B1); PG8_BAR;
;             PG8_LDB(B0, 1, 0); PG8_SCHED; PG8_LDA(At, 1, 0); PG8_STAGE_A(PG8_SA(0, 1), a2, 1, r2);
;             PG8_WAIT_L(8); PG8_BAR; PG8_WAIT_L(0); PG8_MMA(0, 0, At, B0); PG8_BAR; PG8_SCHED;
;             PG8_LDB(B1, 1, 1); PG8_STAGE(PG8_SB(1, 0), b3, voffB);
;             PG8_BAR; PG8_WAIT_L(0); PG8_MMA(0, 1, At, B1); PG8_BAR;
;             PG8_LDA(At, 1, 1); PG8_STAGE_A(PG8_SA(1, 0), a3, 0, r3);
	s_add_u32 s70, s14, 0x880000
	s_addc_u32 s71, s15, 0
	s_add_i32 s10, s10, s47
	v_lshl_add_u64 v[154:155], s[70:71], 0, v[130:131]
	s_mov_b32 m0, s10
	s_nop 0
	global_load_lds_dwordx4 v[154:155], off
	v_lshl_add_u64 v[154:155], s[70:71], 0, v[134:135]
	s_add_i32 m0, s10, 0x2000
	s_nop 0
	global_load_lds_dwordx4 v[154:155], off
	v_add_u32_e32 v176, 0x18000, v145
	ds_read_b128 v[154:157], v176
	ds_read_b128 v[168:171], v176 offset:1024
	ds_read_b128 v[172:175], v176 offset:2048
	ds_read_b128 v[176:179], v176 offset:3072
	s_waitcnt vmcnt(10)
	s_barrier
	v_mfma_f32_16x16x32_bf16 v[52:55], v[232:235], v[180:183], v[52:55]
	v_mfma_f32_16x16x32_bf16 v[48:51], v[240:243], v[180:183], v[48:51]
	v_mfma_f32_16x16x32_bf16 v[36:39], v[232:235], v[208:211], v[36:39]
	v_mfma_f32_16x16x32_bf16 v[32:35], v[240:243], v[208:211], v[32:35]
	v_mfma_f32_16x16x32_bf16 v[20:23], v[232:235], v[216:219], v[20:23]
	v_mfma_f32_16x16x32_bf16 v[16:19], v[240:243], v[216:219], v[16:19]
	v_mfma_f32_16x16x32_bf16 v[4:7], v[232:235], v[224:227], v[4:7]
	v_mfma_f32_16x16x32_bf16 v[0:3], v[240:243], v[224:227], v[0:3]
	v_mfma_f32_16x16x32_bf16 v[52:55], v[236:239], v[204:207], v[52:55]
	v_mfma_f32_16x16x32_bf16 v[48:51], v[244:247], v[204:207], v[48:51]
	v_mfma_f32_16x16x32_bf16 v[36:39], v[236:239], v[212:215], v[36:39]
	v_mfma_f32_16x16x32_bf16 v[32:35], v[244:247], v[212:215], v[32:35]
	v_mfma_f32_16x16x32_bf16 v[20:23], v[236:239], v[220:223], v[20:23]
	v_mfma_f32_16x16x32_bf16 v[16:19], v[244:247], v[220:223], v[16:19]
	v_mfma_f32_16x16x32_bf16 v[4:7], v[236:239], v[228:231], v[4:7]
	v_mfma_f32_16x16x32_bf16 v[0:3], v[244:247], v[228:231], v[0:3]
	s_add_i32 s10, 0, 0x18000
	s_barrier
	s_add_u32 s20, s20, 0x80000
	s_addc_u32 s21, s21, 0
	s_mov_b32 m0, s50
	v_lshl_add_u64 v[190:191], s[20:21], 0, v[128:129]
	ds_read_b128 v[180:183], v153 offset:32768
	ds_read_b128 v[204:207], v153 offset:33792
	ds_read_b128 v[208:211], v153 offset:34816
	ds_read_b128 v[212:215], v153 offset:35840
	ds_read_b128 v[216:219], v153 offset:36864
	ds_read_b128 v[220:223], v153 offset:37888
	ds_read_b128 v[224:227], v153 offset:38912
	ds_read_b128 v[228:231], v153 offset:39936
	global_load_lds_dwordx4 v[190:191], off
	v_lshl_add_u64 v[190:191], s[20:21], 0, v[132:133]
	s_mov_b32 m0, s51
	s_nop 0
	global_load_lds_dwordx4 v[190:191], off
	s_waitcnt lgkmcnt(8)
	s_waitcnt vmcnt(10)
	s_barrier
	s_waitcnt lgkmcnt(0)
	s_waitcnt lgkmcnt(0)
	v_mfma_f32_16x16x32_bf16 v[124:127], v[154:157], v[180:183], v[124:127]
	v_mfma_f32_16x16x32_bf16 v[120:123], v[172:175], v[180:183], v[120:123]
	v_mfma_f32_16x16x32_bf16 v[108:111], v[154:157], v[208:211], v[108:111]
	v_mfma_f32_16x16x32_bf16 v[104:107], v[172:175], v[208:211], v[104:107]
	v_mfma_f32_16x16x32_bf16 v[92:95], v[154:157], v[216:219], v[92:95]
	v_mfma_f32_16x16x32_bf16 v[88:91], v[172:175], v[216:219], v[88:91]
	v_mfma_f32_16x16x32_bf16 v[76:79], v[154:157], v[224:227], v[76:79]
	v_mfma_f32_16x16x32_bf16 v[72:75], v[172:175], v[224:227], v[72:75]
	v_mfma_f32_16x16x32_bf16 v[124:127], v[168:171], v[204:207], v[124:127]
	v_mfma_f32_16x16x32_bf16 v[120:123], v[176:179], v[204:207], v[120:123]
	v_mfma_f32_16x16x32_bf16 v[108:111], v[168:171], v[212:215], v[108:111]
	v_mfma_f32_16x16x32_bf16 v[104:107], v[176:179], v[212:215], v[104:107]
	v_mfma_f32_16x16x32_bf16 v[92:95], v[168:171], v[220:223], v[92:95]
	v_mfma_f32_16x16x32_bf16 v[88:91], v[176:179], v[220:223], v[88:91]
	v_mfma_f32_16x16x32_bf16 v[76:79], v[168:171], v[228:231], v[76:79]
	v_mfma_f32_16x16x32_bf16 v[72:75], v[176:179], v[228:231], v[72:75]
	s_barrier
	s_add_i32 s11, 0, 0x1c000
	s_add_i32 s10, s10, s47
	v_add_u32_e32 v190, s11, v145
	v_lshl_add_u64 v[158:159], v[158:159], 0, s[28:29]
	s_mov_b32 m0, s10
	ds_read_b128 v[232:235], v190
	ds_read_b128 v[236:239], v190 offset:1024
	ds_read_b128 v[240:243], v190 offset:2048
	ds_read_b128 v[244:247], v190 offset:3072
	global_load_lds_dwordx4 v[158:159], off
	v_lshl_add_u64 v[158:159], v[184:185], 0, s[28:29]
	s_add_i32 m0, s10, 0x2000
	s_nop 0
	global_load_lds_dwordx4 v[158:159], off
	s_waitcnt vmcnt(10)
	s_barrier
	s_waitcnt lgkmcnt(0)
	s_waitcnt lgkmcnt(0)
	v_mfma_f32_16x16x32_bf16 v[116:119], v[232:235], v[180:183], v[116:119]
	v_mfma_f32_16x16x32_bf16 v[112:115], v[240:243], v[180:183], v[112:115]
	v_mfma_f32_16x16x32_bf16 v[100:103], v[232:235], v[208:211], v[100:103]
	v_mfma_f32_16x16x32_bf16 v[96:99], v[240:243], v[208:211], v[96:99]
	v_mfma_f32_16x16x32_bf16 v[84:87], v[232:235], v[216:219], v[84:87]
	v_mfma_f32_16x16x32_bf16 v[80:83], v[240:243], v[216:219], v[80:83]
	v_mfma_f32_16x16x32_bf16 v[68:71], v[232:235], v[224:227], v[68:71]
	v_mfma_f32_16x16x32_bf16 v[64:67], v[240:243], v[224:227], v[64:67]
	v_mfma_f32_16x16x32_bf16 v[116:119], v[236:239], v[204:207], v[116:119]
	v_mfma_f32_16x16x32_bf16 v[112:115], v[244:247], v[204:207], v[112:115]
	v_mfma_f32_16x16x32_bf16 v[100:103], v[236:239], v[212:215], v[100:103]
	v_mfma_f32_16x16x32_bf16 v[96:99], v[244:247], v[212:215], v[96:99]
	v_mfma_f32_16x16x32_bf16 v[84:87], v[236:239], v[220:223], v[84:87]
	v_mfma_f32_16x16x32_bf16 v[80:83], v[244:247], v[220:223], v[80:83]
	v_mfma_f32_16x16x32_bf16 v[68:71], v[236:239], v[228:231], v[68:71]
	v_mfma_f32_16x16x32_bf16 v[64:67], v[244:247], v[228:231], v[64:67]
	s_mov_b32 m0, s66
	v_lshl_add_u64 v[158:159], s[16:17], 0, v[128:129]
	s_barrier
; __device__ __forceinline__ unsigned cvt_pk_bf16(float lo, float hi) { unsigned r; asm volatile("v_cvt_pk_bf16_f32 %0, %1, %2" : "=v"(r) : "v"(lo), "v"(hi)); return r; }
; #define PG8_STAGE(bufoff, gbase, voff) do { _Pragma("unroll") for (int _i = 0; _i < 2; ++_i) \
;         __builtin_amdgcn_global_load_lds((const unsigned*)((const char*)(gbase) + (voff)[_i]), (LAS unsigned*)(lds + (bufoff) + ldsw + _i * 8192), 16, 0, 0); } while (0)
; #define PG8_MMA(ai, bj, At, Bt) do { __builtin_amdgcn_s_setprio(1); _Pragma("unroll") for (int m = 0; m < 4; ++m) _Pragma("unroll") for (int n = 0; n < 2; ++n) _Pragma("unroll") for (int k = 0; k < 2; ++k) \
;         acc[ai][bj][m][n] = __builtin_amdgcn_mfma_f32_16x16x32_bf16(Bt[n][k], At[m][k], acc[ai][bj][m][n], 0, 0, 0); __builtin_amdgcn_s_setprio(0); } while (0)
; #define PG8_WAIT_V(n) asm volatile("s_waitcnt vmcnt(" #n ")" ::: "memory")
; #define PG8_WAIT_L(n) asm volatile("s_waitcnt lgkmcnt(" #n ")" ::: "memory")
; #define PG8_BAR __builtin_amdgcn_s_barrier()
; #define PG8_SCHED __builtin_amdgcn_sched_barrier(0)
;     ...
;             PG8_BAR; PG8_WAIT_L(0); PG8_MMA(1, 0, At, B0); PG8_BAR; PG8_SCHED;
;             PG8_STAGE(PG8_SB(1, 1), b3 + hb2, voffB);
;             PG8_WAIT_V(6); PG8_BAR; PG8_MMA(1, 1, At, B1); PG8_BAR;
;     __device__ __forceinline__ void generic(const f32x4 (&acc)[2][2][4][2], const Unit& u, int wr, int wc, int fr, int fq) const {
;     ...
;                         const int b = u.pn >> 3, g = u.pn & 7, k = (Lb == 4096) ? (2 * ((u.pm & 7) * BM + rt) + (u.pm >> 3)) : (u.pm * BM + rt), rb = rowbase0 + b * (Lb + 1);
;                         u32x4 w; w.x = cvt_pk_bf16(v0[0], v0[1]); w.y = cvt_pk_bf16(v0[2], v0[3]); w.z = cvt_pk_bf16(v1[0], v1[1]); w.w = cvt_pk_bf16(v1[2], v1[3]);
;                         *(u32x4*)(O + (size_t)(rb + k) * 2048 + g * 256 + ct) = w;
;                         if (k == 0) *(u32x4*)(O + (size_t)(rb + Lb) * 2048 + g * 256 + ct) = w;
	ds_read_b128 v[180:183], v153 offset:49152
	ds_read_b128 v[204:207], v153 offset:50176
	ds_read_b128 v[208:211], v153 offset:51200
	ds_read_b128 v[212:215], v153 offset:52224
	ds_read_b128 v[216:219], v153 offset:53248
	ds_read_b128 v[220:223], v153 offset:54272
	ds_read_b128 v[224:227], v153 offset:55296
	ds_read_b128 v[228:231], v153 offset:56320
	global_load_lds_dwordx4 v[158:159], off
	v_lshl_add_u64 v[158:159], s[16:17], 0, v[132:133]
	s_mov_b32 m0, s67
	s_nop 0
	global_load_lds_dwordx4 v[158:159], off
	s_waitcnt vmcnt(10)
	s_barrier
	s_waitcnt lgkmcnt(0)
	s_waitcnt lgkmcnt(0)
	v_mfma_f32_16x16x32_bf16 v[60:63], v[154:157], v[180:183], v[60:63]
	v_mfma_f32_16x16x32_bf16 v[56:59], v[172:175], v[180:183], v[56:59]
	v_mfma_f32_16x16x32_bf16 v[44:47], v[154:157], v[208:211], v[44:47]
	v_mfma_f32_16x16x32_bf16 v[40:43], v[172:175], v[208:211], v[40:43]
	v_mfma_f32_16x16x32_bf16 v[28:31], v[154:157], v[216:219], v[28:31]
	v_mfma_f32_16x16x32_bf16 v[24:27], v[172:175], v[216:219], v[24:27]
	v_mfma_f32_16x16x32_bf16 v[12:15], v[154:157], v[224:227], v[12:15]
	v_mfma_f32_16x16x32_bf16 v[8:11], v[172:175], v[224:227], v[8:11]
	v_mfma_f32_16x16x32_bf16 v[60:63], v[168:171], v[204:207], v[60:63]
	v_mfma_f32_16x16x32_bf16 v[56:59], v[176:179], v[204:207], v[56:59]
	v_mfma_f32_16x16x32_bf16 v[44:47], v[168:171], v[212:215], v[44:47]
	v_mfma_f32_16x16x32_bf16 v[40:43], v[176:179], v[212:215], v[40:43]
	v_mfma_f32_16x16x32_bf16 v[28:31], v[168:171], v[220:223], v[28:31]
	v_mfma_f32_16x16x32_bf16 v[24:27], v[176:179], v[220:223], v[24:27]
	v_mfma_f32_16x16x32_bf16 v[12:15], v[168:171], v[228:231], v[12:15]
	v_mfma_f32_16x16x32_bf16 v[8:11], v[176:179], v[228:231], v[8:11]
	s_barrier
	s_add_u32 s14, s14, 0x880080
	s_addc_u32 s15, s15, 0
	s_add_i32 s10, s11, s47
	v_lshl_add_u64 v[154:155], s[14:15], 0, v[130:131]
	s_mov_b32 m0, s10
	s_nop 0
	global_load_lds_dwordx4 v[154:155], off
	v_lshl_add_u64 v[154:155], s[14:15], 0, v[134:135]
	s_add_i32 m0, s10, 0x2000
	s_nop 0
	global_load_lds_dwordx4 v[154:155], off
	v_add_u32_e32 v158, 0x10000, v145
	ds_read_b128 v[154:157], v158
	ds_read_b128 v[168:171], v158 offset:1024
	ds_read_b128 v[172:175], v158 offset:2048
	ds_read_b128 v[176:179], v158 offset:3072
	s_waitcnt vmcnt(10)
	s_barrier
	v_mfma_f32_16x16x32_bf16 v[52:55], v[232:235], v[180:183], v[52:55]
	v_mfma_f32_16x16x32_bf16 v[48:51], v[240:243], v[180:183], v[48:51]
	v_mfma_f32_16x16x32_bf16 v[36:39], v[232:235], v[208:211], v[36:39]
	v_mfma_f32_16x16x32_bf16 v[32:35], v[240:243], v[208:211], v[32:35]
	v_mfma_f32_16x16x32_bf16 v[20:23], v[232:235], v[216:219], v[20:23]
	v_mfma_f32_16x16x32_bf16 v[16:19], v[240:243], v[216:219], v[16:19]
	v_mfma_f32_16x16x32_bf16 v[4:7], v[232:235], v[224:227], v[4:7]
	v_mfma_f32_16x16x32_bf16 v[0:3], v[240:243], v[224:227], v[0:3]
	v_mfma_f32_16x16x32_bf16 v[52:55], v[236:239], v[204:207], v[52:55]
	v_mfma_f32_16x16x32_bf16 v[48:51], v[244:247], v[204:207], v[48:51]
	v_mfma_f32_16x16x32_bf16 v[36:39], v[236:239], v[212:215], v[36:39]
	v_mfma_f32_16x16x32_bf16 v[32:35], v[244:247], v[212:215], v[32:35]
	v_mfma_f32_16x16x32_bf16 v[20:23], v[236:239], v[220:223], v[20:23]
	v_mfma_f32_16x16x32_bf16 v[16:19], v[244:247], v[220:223], v[16:19]
	v_mfma_f32_16x16x32_bf16 v[4:7], v[236:239], v[228:231], v[4:7]
	v_mfma_f32_16x16x32_bf16 v[0:3], v[244:247], v[228:231], v[0:3]
	s_add_i32 s44, s44, 2
	s_add_u32 s0, s0, 0x100
	s_addc_u32 s1, s1, 0
	s_cmp_gt_u32 s44, 29
	s_barrier
	s_cbranch_scc0 .LBB0_903
	s_waitcnt lgkmcnt(0)
	s_lshl_b32 s1, s7, 8
	s_and_b32 s8, s1, 0x700
	s_ashr_i32 s0, s6, 3
	v_add_u32_e32 v140, s8, v144
	s_ashr_i32 s7, s7, 3
	v_lshl_add_u32 v140, v140, 1, s7
	s_mulk_i32 s0, 0x1001
	v_cvt_pk_bf16_f32 v124, v124, v125
	v_cvt_pk_bf16_f32 v125, v126, v127
	v_cvt_pk_bf16_f32 v126, v120, v121
	v_add_u32_e32 v120, s0, v140
	v_ashrrev_i32_e32 v121, 31, v120
	s_lshl_b32 s1, s6, 8
	v_lshlrev_b64 v[120:121], 12, v[120:121]
	s_and_b32 s1, s1, 0x700
	v_lshl_add_u64 v[120:121], s[24:25], 0, v[120:121]
	s_lshl_b32 s22, s1, 1
	v_lshl_add_u64 v[120:121], v[120:121], 0, s[22:23]
	v_lshl_add_u64 v[120:121], v[120:121], 0, v[160:161]
	v_cmp_eq_u32_e64 s[44:45], 0, v140
	v_cvt_pk_bf16_f32 v127, v122, v123
	global_store_dwordx4 v[120:121], v[124:127], off
	s_and_saveexec_b64 s[14:15], s[44:45]
	s_cbranch_execz .LBB0_906
	s_ashr_i32 s1, s0, 31
	s_lshl_b64 s[16:17], s[0:1], 12
	s_add_u32 s1, s24, s16
	s_addc_u32 s6, s25, s17
	s_add_u32 s16, s1, s22
	s_addc_u32 s17, s6, 0
	v_lshl_add_u64 v[122:123], s[16:17], 0, v[160:161]
	v_add_co_u32_e32 v122, vcc, 0x1000000, v122
	s_nop 1
	v_addc_co_u32_e32 v123, vcc, 0, v123, vcc
	global_store_dwordx4 v[122:123], v[124:127], off

; #define PG8_STAGE(bufoff, gbase, voff) do { _Pragma("unroll") for (int _i = 0; _i < 2; ++_i) \
;         __builtin_amdgcn_global_load_lds((const unsigned*)((const char*)(gbase) + (voff)[_i]), (LAS unsigned*)(lds + (bufoff) + ldsw + _i * 8192), 16, 0, 0); } while (0)
; #define PG8_STAGE_A(bufoff, ptr, half, rev) do { if (REVA && (rev)) { const char* _p = (ptr) - ((half) ? hstepA : 0); PG8_STAGE(bufoff, _p, voffAr); } else { const char* _p = (ptr) + ((half) ? hstepA : 0); PG8_STAGE(bufoff, _p, voffA); } } while (0)
; #define PG8_LDA(dst, b, h) do { _Pragma("unroll") for (int m = 0; m < 4; ++m) _Pragma("unroll") for (int k = 0; k < 2; ++k) dst[m][k] = *(const LAS bf16x8*)(lds + PG8_SA(b, h) + aoff + m * 2048 + k * 1024); } while (0)
; #define PG8_LDB(dst, b, h) do { _Pragma("unroll") for (int n = 0; n < 2; ++n) _Pragma("unroll") for (int k = 0; k < 2; ++k) dst[n][k] = *(const LAS bf16x8*)(lds + PG8_SB(b, h) + boff + n * 2048 + k * 1024); } while (0)
; #define PG8_MMA(ai, bj, At, Bt) do { __builtin_amdgcn_s_setprio(1); _Pragma("unroll") for (int m = 0; m < 4; ++m) _Pragma("unroll") for (int n = 0; n < 2; ++n) _Pragma("unroll") for (int k = 0; k < 2; ++k) \
;         acc[ai][bj][m][n] = __builtin_amdgcn_mfma_f32_16x16x32_bf16(Bt[n][k], At[m][k], acc[ai][bj][m][n], 0, 0, 0); __builtin_amdgcn_s_setprio(0); } while (0)
; #define PG8_WAIT_L(n) asm volatile("s_waitcnt lgkmcnt(" #n ")" ::: "memory")
; #define PG8_BAR __builtin_amdgcn_s_barrier()
; #define PG8_SCHED __builtin_amdgcn_sched_barrier(0)
;     ...
;             PG8_LDB(B0, 0, 0); PG8_SCHED; PG8_LDA(At, 0, 0); PG8_STAGE_A(PG8_SA(1, 1), a1, 1, r1);
;             PG8_WAIT_L(8); PG8_BAR; PG8_WAIT_L(0); PG8_MMA(0, 0, At, B0); PG8_BAR; PG8_SCHED;
;             PG8_LDB(B1, 0, 1); PG8_STAGE(PG8_SB(0, 0), b2, voffB);
;             PG8_BAR; PG8_WAIT_L(0); PG8_MMA(0, 1, At, B1); PG8_BAR;
;             PG8_LDA(At, 0, 1); PG8_STAGE_A(PG8_SA(0, 0), a2, 0, r2);
;             PG8_BAR; PG8_WAIT_L(0); PG8_MMA(1, 0, At, B0); PG8_BAR; PG8_SCHED;
.LBB0_1132:
	s_add_u32 s10, s0, s2
	s_addc_u32 s11, s1, s3
	s_add_u32 s16, s10, 0x100
	s_addc_u32 s17, s11, 0
	s_add_u32 s10, s10, 0x180
	s_addc_u32 s11, s11, 0
	s_add_u32 s14, s8, s2
	s_addc_u32 s15, s9, s3
	s_add_i32 s27, 0, 0x10000
	s_cmpk_eq_i32 s2, 0xf00
	s_cselect_b32 s15, s25, s15
	s_cselect_b32 s14, s24, s14
	s_cselect_b32 s21, s79, s17
	s_cselect_b32 s20, s78, s16
	s_cselect_b32 s17, s7, s11
	s_cselect_b32 s16, s6, s10
	v_lshl_add_u64 v[184:185], v[96:97], 0, s[2:3]
	s_add_i32 m0, s70, 0xc000
	ds_read_b128 v[148:151], v209
	ds_read_b128 v[152:155], v209 offset:1024
	ds_read_b128 v[156:159], v209 offset:2048
	ds_read_b128 v[180:183], v209 offset:3072
	ds_read_b128 v[210:213], v209 offset:4096
	ds_read_b128 v[214:217], v209 offset:5120
	ds_read_b128 v[218:221], v209 offset:6144
	ds_read_b128 v[222:225], v209 offset:7168
	global_load_lds_dwordx4 v[184:185], off
	v_lshl_add_u64 v[184:185], v[98:99], 0, s[2:3]
	s_add_i32 m0, s70, 0xe000
	s_nop 0
	global_load_lds_dwordx4 v[184:185], off
	s_waitcnt lgkmcnt(8)
	s_waitcnt vmcnt(10)
	s_barrier
	s_waitcnt lgkmcnt(0)
	s_waitcnt lgkmcnt(0)
	v_mfma_f32_16x16x32_bf16 v[144:147], v[108:111], v[148:151], v[144:147]
	v_mfma_f32_16x16x32_bf16 v[136:139], v[132:135], v[148:151], v[136:139]
	v_mfma_f32_16x16x32_bf16 v[116:119], v[108:111], v[156:159], v[116:119]
	v_mfma_f32_16x16x32_bf16 v[112:115], v[132:135], v[156:159], v[112:115]
	v_mfma_f32_16x16x32_bf16 v[92:95], v[108:111], v[210:213], v[92:95]
	v_mfma_f32_16x16x32_bf16 v[88:91], v[132:135], v[210:213], v[88:91]
	v_mfma_f32_16x16x32_bf16 v[76:79], v[108:111], v[218:221], v[76:79]
	v_mfma_f32_16x16x32_bf16 v[72:75], v[132:135], v[218:221], v[72:75]
	v_mfma_f32_16x16x32_bf16 v[144:147], v[120:123], v[152:155], v[144:147]
	v_mfma_f32_16x16x32_bf16 v[136:139], v[140:143], v[152:155], v[136:139]
	v_mfma_f32_16x16x32_bf16 v[116:119], v[120:123], v[180:183], v[116:119]
	v_mfma_f32_16x16x32_bf16 v[112:115], v[140:143], v[180:183], v[112:115]
	v_mfma_f32_16x16x32_bf16 v[92:95], v[120:123], v[214:217], v[92:95]
	v_mfma_f32_16x16x32_bf16 v[88:91], v[140:143], v[214:217], v[88:91]
	v_mfma_f32_16x16x32_bf16 v[76:79], v[120:123], v[222:225], v[76:79]
	v_mfma_f32_16x16x32_bf16 v[72:75], v[140:143], v[222:225], v[72:75]
	s_barrier
	s_add_i32 s10, 0, 0x14000
	v_add_u32_e32 v184, s10, v205
	s_add_i32 s11, s27, s69
	ds_read_b128 v[226:229], v184
	ds_read_b128 v[230:233], v184 offset:1024
	ds_read_b128 v[234:237], v184 offset:2048
	ds_read_b128 v[238:241], v184 offset:3072
	v_lshl_add_u64 v[184:185], s[14:15], 0, v[172:173]
	s_mov_b32 m0, s11
	v_lshl_add_u64 v[190:191], s[14:15], 0, v[168:169]
	global_load_lds_dwordx4 v[184:185], off
	s_add_i32 m0, s11, 0x2000
	s_nop 0
	global_load_lds_dwordx4 v[190:191], off
	s_waitcnt vmcnt(10)
	s_barrier
	s_waitcnt lgkmcnt(0)
	s_waitcnt lgkmcnt(0)
	v_mfma_f32_16x16x32_bf16 v[128:131], v[226:229], v[148:151], v[128:131]
	v_mfma_f32_16x16x32_bf16 v[124:127], v[234:237], v[148:151], v[124:127]
	v_mfma_f32_16x16x32_bf16 v[104:107], v[226:229], v[156:159], v[104:107]
	v_mfma_f32_16x16x32_bf16 v[100:103], v[234:237], v[156:159], v[100:103]
	v_mfma_f32_16x16x32_bf16 v[84:87], v[226:229], v[210:213], v[84:87]
	v_mfma_f32_16x16x32_bf16 v[80:83], v[234:237], v[210:213], v[80:83]
	v_mfma_f32_16x16x32_bf16 v[68:71], v[226:229], v[218:221], v[68:71]
	v_mfma_f32_16x16x32_bf16 v[64:67], v[234:237], v[218:221], v[64:67]
	v_mfma_f32_16x16x32_bf16 v[128:131], v[230:233], v[152:155], v[128:131]
	v_mfma_f32_16x16x32_bf16 v[124:127], v[238:241], v[152:155], v[124:127]
	v_mfma_f32_16x16x32_bf16 v[104:107], v[230:233], v[180:183], v[104:107]
	v_mfma_f32_16x16x32_bf16 v[100:103], v[238:241], v[180:183], v[100:103]
	v_mfma_f32_16x16x32_bf16 v[84:87], v[230:233], v[214:217], v[84:87]
	v_mfma_f32_16x16x32_bf16 v[80:83], v[238:241], v[214:217], v[80:83]
	v_mfma_f32_16x16x32_bf16 v[68:71], v[230:233], v[222:225], v[68:71]
	v_mfma_f32_16x16x32_bf16 v[64:67], v[238:241], v[222:225], v[64:67]
	s_mov_b32 m0, s70
	v_lshl_add_u64 v[242:243], s[20:21], 0, v[174:175]
	s_barrier
	ds_read_b128 v[148:151], v209 offset:16384
	ds_read_b128 v[152:155], v209 offset:17408
	ds_read_b128 v[156:159], v209 offset:18432
	ds_read_b128 v[180:183], v209 offset:19456
	ds_read_b128 v[210:213], v209 offset:20480
	ds_read_b128 v[214:217], v209 offset:21504
	ds_read_b128 v[218:221], v209 offset:22528
	ds_read_b128 v[222:225], v209 offset:23552
	global_load_lds_dwordx4 v[242:243], off
	v_lshl_add_u64 v[242:243], s[20:21], 0, v[170:171]
	s_mov_b32 m0, s71
	s_nop 0
	global_load_lds_dwordx4 v[242:243], off
	s_waitcnt vmcnt(10)
	s_barrier
	s_waitcnt lgkmcnt(0)
	s_waitcnt lgkmcnt(0)
	v_mfma_f32_16x16x32_bf16 v[60:63], v[108:111], v[148:151], v[60:63]
	v_mfma_f32_16x16x32_bf16 v[56:59], v[132:135], v[148:151], v[56:59]
	v_mfma_f32_16x16x32_bf16 v[44:47], v[108:111], v[156:159], v[44:47]
	v_mfma_f32_16x16x32_bf16 v[40:43], v[132:135], v[156:159], v[40:43]
	v_mfma_f32_16x16x32_bf16 v[28:31], v[108:111], v[210:213], v[28:31]
	v_mfma_f32_16x16x32_bf16 v[24:27], v[132:135], v[210:213], v[24:27]
	v_mfma_f32_16x16x32_bf16 v[12:15], v[108:111], v[218:221], v[12:15]
	v_mfma_f32_16x16x32_bf16 v[8:11], v[132:135], v[218:221], v[8:11]
	v_mfma_f32_16x16x32_bf16 v[60:63], v[120:123], v[152:155], v[60:63]
	v_mfma_f32_16x16x32_bf16 v[56:59], v[140:143], v[152:155], v[56:59]
	v_mfma_f32_16x16x32_bf16 v[44:47], v[120:123], v[180:183], v[44:47]
	v_mfma_f32_16x16x32_bf16 v[40:43], v[140:143], v[180:183], v[40:43]
	v_mfma_f32_16x16x32_bf16 v[28:31], v[120:123], v[214:217], v[28:31]
	v_mfma_f32_16x16x32_bf16 v[24:27], v[140:143], v[214:217], v[24:27]
	v_mfma_f32_16x16x32_bf16 v[12:15], v[120:123], v[222:225], v[12:15]
	v_mfma_f32_16x16x32_bf16 v[8:11], v[140:143], v[222:225], v[8:11]
	s_barrier
; #define PG8_STAGE(bufoff, gbase, voff) do { _Pragma("unroll") for (int _i = 0; _i < 2; ++_i) \
;         __builtin_amdgcn_global_load_lds((const unsigned*)((const char*)(gbase) + (voff)[_i]), (LAS unsigned*)(lds + (bufoff) + ldsw + _i * 8192), 16, 0, 0); } while (0)
; #define PG8_STAGE_A(bufoff, ptr, half, rev) do { if (REVA && (rev)) { const char* _p = (ptr) - ((half) ? hstepA : 0); PG8_STAGE(bufoff, _p, voffAr); } else { const char* _p = (ptr) + ((half) ? hstepA : 0); PG8_STAGE(bufoff, _p, voffA); } } while (0)
; #define PG8_LDA(dst, b, h) do { _Pragma("unroll") for (int m = 0; m < 4; ++m) _Pragma("unroll") for (int k = 0; k < 2; ++k) dst[m][k] = *(const LAS bf16x8*)(lds + PG8_SA(b, h) + aoff + m * 2048 + k * 1024); } while (0)
; #define PG8_LDB(dst, b, h) do { _Pragma("unroll") for (int n = 0; n < 2; ++n) _Pragma("unroll") for (int k = 0; k < 2; ++k) dst[n][k] = *(const LAS bf16x8*)(lds + PG8_SB(b, h) + boff + n * 2048 + k * 1024); } while (0)
; #define PG8_MMA(ai, bj, At, Bt) do { __builtin_amdgcn_s_setprio(1); _Pragma("unroll") for (int m = 0; m < 4; ++m) _Pragma("unroll") for (int n = 0; n < 2; ++n) _Pragma("unroll") for (int k = 0; k < 2; ++k) \
;         acc[ai][bj][m][n] = __builtin_amdgcn_mfma_f32_16x16x32_bf16(Bt[n][k], At[m][k], acc[ai][bj][m][n], 0, 0, 0); __builtin_amdgcn_s_setprio(0); } while (0)
; #define PG8_WAIT_V(n) asm volatile("s_waitcnt vmcnt(" #n ")" ::: "memory")
; #define PG8_WAIT_L(n) asm volatile("s_waitcnt lgkmcnt(" #n ")" ::: "memory")
; #define PG8_BAR __builtin_amdgcn_s_barrier()
; #define PG8_SCHED __builtin_amdgcn_sched_barrier(0)
;     ...
;             PG8_STAGE(PG8_SB(0, 1), b2 + hb2, voffB);
;             PG8_WAIT_V(6); PG8_BAR; PG8_MMA(1, 1, At, B1); PG8_BAR;
;             PG8_LDB(B0, 1, 0); PG8_SCHED; PG8_LDA(At, 1, 0); PG8_STAGE_A(PG8_SA(0, 1), a2, 1, r2);
;             PG8_WAIT_L(8); PG8_BAR; PG8_WAIT_L(0); PG8_MMA(0, 0, At, B0); PG8_BAR; PG8_SCHED;
;             PG8_LDB(B1, 1, 1); PG8_STAGE(PG8_SB(1, 0), b3, voffB);
;             PG8_BAR; PG8_WAIT_L(0); PG8_MMA(0, 1, At, B1); PG8_BAR;
;             PG8_LDA(At, 1, 1); PG8_STAGE_A(PG8_SA(1, 0), a3, 0, r3);
	s_add_u32 s36, s14, 0x80000
	s_addc_u32 s37, s15, 0
	s_add_i32 s10, s10, s69
	v_lshl_add_u64 v[108:109], s[36:37], 0, v[172:173]
	s_mov_b32 m0, s10
	s_nop 0
	global_load_lds_dwordx4 v[108:109], off
	v_lshl_add_u64 v[108:109], s[36:37], 0, v[168:169]
	s_add_i32 m0, s10, 0x2000
	s_nop 0
	global_load_lds_dwordx4 v[108:109], off
	v_add_u32_e32 v140, 0x18000, v205
	ds_read_b128 v[108:111], v140
	ds_read_b128 v[120:123], v140 offset:1024
	ds_read_b128 v[132:135], v140 offset:2048
	ds_read_b128 v[140:143], v140 offset:3072
	s_waitcnt vmcnt(10)
	s_barrier
	v_mfma_f32_16x16x32_bf16 v[52:55], v[226:229], v[148:151], v[52:55]
	v_mfma_f32_16x16x32_bf16 v[48:51], v[234:237], v[148:151], v[48:51]
	v_mfma_f32_16x16x32_bf16 v[36:39], v[226:229], v[156:159], v[36:39]
	v_mfma_f32_16x16x32_bf16 v[32:35], v[234:237], v[156:159], v[32:35]
	v_mfma_f32_16x16x32_bf16 v[20:23], v[226:229], v[210:213], v[20:23]
	v_mfma_f32_16x16x32_bf16 v[16:19], v[234:237], v[210:213], v[16:19]
	v_mfma_f32_16x16x32_bf16 v[4:7], v[226:229], v[218:221], v[4:7]
	v_mfma_f32_16x16x32_bf16 v[0:3], v[234:237], v[218:221], v[0:3]
	v_mfma_f32_16x16x32_bf16 v[52:55], v[230:233], v[152:155], v[52:55]
	v_mfma_f32_16x16x32_bf16 v[48:51], v[238:241], v[152:155], v[48:51]
	v_mfma_f32_16x16x32_bf16 v[36:39], v[230:233], v[180:183], v[36:39]
	v_mfma_f32_16x16x32_bf16 v[32:35], v[238:241], v[180:183], v[32:35]
	v_mfma_f32_16x16x32_bf16 v[20:23], v[230:233], v[214:217], v[20:23]
	v_mfma_f32_16x16x32_bf16 v[16:19], v[238:241], v[214:217], v[16:19]
	v_mfma_f32_16x16x32_bf16 v[4:7], v[230:233], v[222:225], v[4:7]
	v_mfma_f32_16x16x32_bf16 v[0:3], v[238:241], v[222:225], v[0:3]
	s_add_i32 s10, 0, 0x18000
	s_barrier
	s_add_u32 s20, s20, 0x80000
	s_addc_u32 s21, s21, 0
	s_mov_b32 m0, s89
	v_lshl_add_u64 v[226:227], s[20:21], 0, v[174:175]
	ds_read_b128 v[148:151], v209 offset:32768
	ds_read_b128 v[152:155], v209 offset:33792
	ds_read_b128 v[156:159], v209 offset:34816
	ds_read_b128 v[180:183], v209 offset:35840
	ds_read_b128 v[210:213], v209 offset:36864
	ds_read_b128 v[214:217], v209 offset:37888
	ds_read_b128 v[218:221], v209 offset:38912
	ds_read_b128 v[222:225], v209 offset:39936
	global_load_lds_dwordx4 v[226:227], off
	v_lshl_add_u64 v[226:227], s[20:21], 0, v[170:171]
	s_mov_b32 m0, s90
	s_nop 0
	global_load_lds_dwordx4 v[226:227], off
	s_waitcnt lgkmcnt(8)
	s_waitcnt vmcnt(10)
	s_barrier
	s_waitcnt lgkmcnt(0)
	s_waitcnt lgkmcnt(0)
	v_mfma_f32_16x16x32_bf16 v[144:147], v[108:111], v[148:151], v[144:147]
	v_mfma_f32_16x16x32_bf16 v[136:139], v[132:135], v[148:151], v[136:139]
	v_mfma_f32_16x16x32_bf16 v[116:119], v[108:111], v[156:159], v[116:119]
	v_mfma_f32_16x16x32_bf16 v[112:115], v[132:135], v[156:159], v[112:115]
	v_mfma_f32_16x16x32_bf16 v[92:95], v[108:111], v[210:213], v[92:95]
	v_mfma_f32_16x16x32_bf16 v[88:91], v[132:135], v[210:213], v[88:91]
	v_mfma_f32_16x16x32_bf16 v[76:79], v[108:111], v[218:221], v[76:79]
	v_mfma_f32_16x16x32_bf16 v[72:75], v[132:135], v[218:221], v[72:75]
	v_mfma_f32_16x16x32_bf16 v[144:147], v[120:123], v[152:155], v[144:147]
	v_mfma_f32_16x16x32_bf16 v[136:139], v[140:143], v[152:155], v[136:139]
	v_mfma_f32_16x16x32_bf16 v[116:119], v[120:123], v[180:183], v[116:119]
	v_mfma_f32_16x16x32_bf16 v[112:115], v[140:143], v[180:183], v[112:115]
	v_mfma_f32_16x16x32_bf16 v[92:95], v[120:123], v[214:217], v[92:95]
	v_mfma_f32_16x16x32_bf16 v[88:91], v[140:143], v[214:217], v[88:91]
	v_mfma_f32_16x16x32_bf16 v[76:79], v[120:123], v[222:225], v[76:79]
	v_mfma_f32_16x16x32_bf16 v[72:75], v[140:143], v[222:225], v[72:75]
	s_barrier
	s_add_i32 s11, 0, 0x1c000
	s_add_i32 s10, s10, s69
	v_add_u32_e32 v238, s11, v205
	v_lshl_add_u64 v[184:185], v[184:185], 0, s[28:29]
	s_mov_b32 m0, s10
	ds_read_b128 v[226:229], v238
	ds_read_b128 v[230:233], v238 offset:1024
	ds_read_b128 v[234:237], v238 offset:2048
	ds_read_b128 v[238:241], v238 offset:3072
	global_load_lds_dwordx4 v[184:185], off
	v_lshl_add_u64 v[184:185], v[190:191], 0, s[28:29]
	s_add_i32 m0, s10, 0x2000
	s_nop 0
	global_load_lds_dwordx4 v[184:185], off
	s_waitcnt vmcnt(10)
	s_barrier
	s_waitcnt lgkmcnt(0)
	s_waitcnt lgkmcnt(0)
	v_mfma_f32_16x16x32_bf16 v[128:131], v[226:229], v[148:151], v[128:131]
	v_mfma_f32_16x16x32_bf16 v[124:127], v[234:237], v[148:151], v[124:127]
	v_mfma_f32_16x16x32_bf16 v[104:107], v[226:229], v[156:159], v[104:107]
	v_mfma_f32_16x16x32_bf16 v[100:103], v[234:237], v[156:159], v[100:103]
	v_mfma_f32_16x16x32_bf16 v[84:87], v[226:229], v[210:213], v[84:87]
	v_mfma_f32_16x16x32_bf16 v[80:83], v[234:237], v[210:213], v[80:83]
	v_mfma_f32_16x16x32_bf16 v[68:71], v[226:229], v[218:221], v[68:71]
	v_mfma_f32_16x16x32_bf16 v[64:67], v[234:237], v[218:221], v[64:67]
	v_mfma_f32_16x16x32_bf16 v[128:131], v[230:233], v[152:155], v[128:131]
	v_mfma_f32_16x16x32_bf16 v[124:127], v[238:241], v[152:155], v[124:127]
	v_mfma_f32_16x16x32_bf16 v[104:107], v[230:233], v[180:183], v[104:107]
	v_mfma_f32_16x16x32_bf16 v[100:103], v[238:241], v[180:183], v[100:103]
	v_mfma_f32_16x16x32_bf16 v[84:87], v[230:233], v[214:217], v[84:87]
	v_mfma_f32_16x16x32_bf16 v[80:83], v[238:241], v[214:217], v[80:83]
	v_mfma_f32_16x16x32_bf16 v[68:71], v[230:233], v[222:225], v[68:71]
	v_mfma_f32_16x16x32_bf16 v[64:67], v[238:241], v[222:225], v[64:67]
	s_mov_b32 m0, s97
	v_lshl_add_u64 v[184:185], s[16:17], 0, v[174:175]
	s_barrier
; #define PG8_STAGE(bufoff, gbase, voff) do { _Pragma("unroll") for (int _i = 0; _i < 2; ++_i) \
;         __builtin_amdgcn_global_load_lds((const unsigned*)((const char*)(gbase) + (voff)[_i]), (LAS unsigned*)(lds + (bufoff) + ldsw + _i * 8192), 16, 0, 0); } while (0)
; #define PG8_MMA(ai, bj, At, Bt) do { __builtin_amdgcn_s_setprio(1); _Pragma("unroll") for (int m = 0; m < 4; ++m) _Pragma("unroll") for (int n = 0; n < 2; ++n) _Pragma("unroll") for (int k = 0; k < 2; ++k) \
;         acc[ai][bj][m][n] = __builtin_amdgcn_mfma_f32_16x16x32_bf16(Bt[n][k], At[m][k], acc[ai][bj][m][n], 0, 0, 0); __builtin_amdgcn_s_setprio(0); } while (0)
; #define PG8_WAIT_V(n) asm volatile("s_waitcnt vmcnt(" #n ")" ::: "memory")
; #define PG8_WAIT_L(n) asm volatile("s_waitcnt lgkmcnt(" #n ")" ::: "memory")
; #define PG8_BAR __builtin_amdgcn_s_barrier()
; #define PG8_SCHED __builtin_amdgcn_sched_barrier(0)
;     ...
;             PG8_BAR; PG8_WAIT_L(0); PG8_MMA(1, 0, At, B0); PG8_BAR; PG8_SCHED;
;             PG8_STAGE(PG8_SB(1, 1), b3 + hb2, voffB);
;             PG8_WAIT_V(6); PG8_BAR; PG8_MMA(1, 1, At, B1); PG8_BAR;
;     __device__ __forceinline__ void gates(const f32x4 (&acc)[2][2][4][2], const Unit& u, int wr, int wc, int fr, int fq) const {
;         const bool ret = u.pn < 8;
;         const bf16_t* mulp = ret ? (OFp + u.pn * BM) : (Y + (u.pn - 8) * BM);
; #pragma unroll
;         for (int ai = 0; ai < 2; ++ai) {
;             u32x4 yv[4][2]; float rs[4];
; #pragma unroll
;             for (int m = 0; m < 4; ++m) {
;                 const size_t row = (size_t)(u.pm * BM + ai * HALF + wr * 64 + m * 16 + fr);
; #pragma unroll
;                 for (int bj = 0; bj < 2; ++bj) yv[m][bj] = *(const u32x4*)(mulp + row * 2048 + bj * HALF + wc * 32 + 8 * fq);
;                 rs[m] = 1.0f;
;                 if (ret) { const f32x4 sq = *(const f32x4*)(SSp + row * 32 + u.pn * 4); rs[m] = rsqrtf((sq[0] + sq[1] + sq[2] + sq[3]) * (1.0f / 256.0f) + 1e-6f); }
	ds_read_b128 v[148:151], v209 offset:49152
	ds_read_b128 v[152:155], v209 offset:50176
	ds_read_b128 v[156:159], v209 offset:51200
	ds_read_b128 v[180:183], v209 offset:52224
	ds_read_b128 v[210:213], v209 offset:53248
	ds_read_b128 v[214:217], v209 offset:54272
	ds_read_b128 v[218:221], v209 offset:55296
	ds_read_b128 v[222:225], v209 offset:56320
	global_load_lds_dwordx4 v[184:185], off
	v_lshl_add_u64 v[184:185], s[16:17], 0, v[170:171]
	s_mov_b32 m0, s52
	s_nop 0
	global_load_lds_dwordx4 v[184:185], off
	s_waitcnt vmcnt(10)
	s_barrier
	s_waitcnt lgkmcnt(0)
	s_waitcnt lgkmcnt(0)
	v_mfma_f32_16x16x32_bf16 v[60:63], v[108:111], v[148:151], v[60:63]
	v_mfma_f32_16x16x32_bf16 v[56:59], v[132:135], v[148:151], v[56:59]
	v_mfma_f32_16x16x32_bf16 v[44:47], v[108:111], v[156:159], v[44:47]
	v_mfma_f32_16x16x32_bf16 v[40:43], v[132:135], v[156:159], v[40:43]
	v_mfma_f32_16x16x32_bf16 v[28:31], v[108:111], v[210:213], v[28:31]
	v_mfma_f32_16x16x32_bf16 v[24:27], v[132:135], v[210:213], v[24:27]
	v_mfma_f32_16x16x32_bf16 v[12:15], v[108:111], v[218:221], v[12:15]
	v_mfma_f32_16x16x32_bf16 v[8:11], v[132:135], v[218:221], v[8:11]
	v_mfma_f32_16x16x32_bf16 v[60:63], v[120:123], v[152:155], v[60:63]
	v_mfma_f32_16x16x32_bf16 v[56:59], v[140:143], v[152:155], v[56:59]
	v_mfma_f32_16x16x32_bf16 v[44:47], v[120:123], v[180:183], v[44:47]
	v_mfma_f32_16x16x32_bf16 v[40:43], v[140:143], v[180:183], v[40:43]
	v_mfma_f32_16x16x32_bf16 v[28:31], v[120:123], v[214:217], v[28:31]
	v_mfma_f32_16x16x32_bf16 v[24:27], v[140:143], v[214:217], v[24:27]
	v_mfma_f32_16x16x32_bf16 v[12:15], v[120:123], v[222:225], v[12:15]
	v_mfma_f32_16x16x32_bf16 v[8:11], v[140:143], v[222:225], v[8:11]
	s_barrier
	s_add_u32 s14, s14, 0x80080
	s_addc_u32 s15, s15, 0
	s_add_i32 s10, s11, s69
	v_lshl_add_u64 v[108:109], s[14:15], 0, v[172:173]
	s_mov_b32 m0, s10
	s_nop 0
	global_load_lds_dwordx4 v[108:109], off
	v_lshl_add_u64 v[108:109], s[14:15], 0, v[168:169]
	s_add_i32 m0, s10, 0x2000
	s_nop 0
	global_load_lds_dwordx4 v[108:109], off
	v_add_u32_e32 v140, 0x10000, v205
	ds_read_b128 v[108:111], v140
	ds_read_b128 v[120:123], v140 offset:1024
	ds_read_b128 v[132:135], v140 offset:2048
	ds_read_b128 v[140:143], v140 offset:3072
	s_waitcnt vmcnt(10)
	s_barrier
	v_mfma_f32_16x16x32_bf16 v[52:55], v[226:229], v[148:151], v[52:55]
	v_mfma_f32_16x16x32_bf16 v[48:51], v[234:237], v[148:151], v[48:51]
	v_mfma_f32_16x16x32_bf16 v[36:39], v[226:229], v[156:159], v[36:39]
	v_mfma_f32_16x16x32_bf16 v[32:35], v[234:237], v[156:159], v[32:35]
	v_mfma_f32_16x16x32_bf16 v[20:23], v[226:229], v[210:213], v[20:23]
	v_mfma_f32_16x16x32_bf16 v[16:19], v[234:237], v[210:213], v[16:19]
	v_mfma_f32_16x16x32_bf16 v[4:7], v[226:229], v[218:221], v[4:7]
	v_mfma_f32_16x16x32_bf16 v[0:3], v[234:237], v[218:221], v[0:3]
	v_mfma_f32_16x16x32_bf16 v[52:55], v[230:233], v[152:155], v[52:55]
	v_mfma_f32_16x16x32_bf16 v[48:51], v[238:241], v[152:155], v[48:51]
	v_mfma_f32_16x16x32_bf16 v[36:39], v[230:233], v[180:183], v[36:39]
	v_mfma_f32_16x16x32_bf16 v[32:35], v[238:241], v[180:183], v[32:35]
	v_mfma_f32_16x16x32_bf16 v[20:23], v[230:233], v[214:217], v[20:23]
	v_mfma_f32_16x16x32_bf16 v[16:19], v[238:241], v[214:217], v[16:19]
	v_mfma_f32_16x16x32_bf16 v[4:7], v[230:233], v[222:225], v[4:7]
	v_mfma_f32_16x16x32_bf16 v[0:3], v[238:241], v[222:225], v[0:3]
	s_add_i32 s26, s26, 2
	s_add_u32 s2, s2, 0x100
	s_addc_u32 s3, s3, 0
	s_cmp_gt_u32 s26, 29
	s_barrier
	s_cbranch_scc0 .LBB0_1132
	s_waitcnt lgkmcnt(0)
	s_lshl_b32 s0, s4, 8
	s_ashr_i32 s1, s0, 31
	s_lshl_b64 s[26:27], s[0:1], 1
	s_add_u32 s6, s93, s26
	s_addc_u32 s7, s94, s27
	s_addk_i32 s0, 0xf800
	s_mov_b32 s1, s23
	s_lshl_b64 s[0:1], s[0:1], 1
	s_add_u32 s8, s91, s0
	s_addc_u32 s9, s92, s1
	s_cmp_lt_i32 s4, 8
	s_cselect_b64 s[0:1], -1, 0
	s_and_b64 s[2:3], s[0:1], exec
	s_cselect_b32 s3, s6, s8
	s_cselect_b32 s2, s7, s9
	s_add_u32 s6, s3, s22
	s_addc_u32 s7, s2, 0
	s_lshl_b32 s2, s5, 8
	v_add_u32_e32 v180, s2, v204
	v_ashrrev_i32_e32 v181, 31, v180
	v_lshl_add_u64 v[182:183], s[6:7], 0, v[160:161]
	v_lshlrev_b64 v[96:97], 12, v[180:181]
	v_lshl_add_u64 v[96:97], v[182:183], 0, v[96:97]
	global_load_dwordx4 v[156:159], v[96:97], off
	global_load_dwordx4 v[152:155], v[96:97], off offset:256
	s_lshl_b32 s6, s4, 2
	s_ashr_i32 s7, s6, 31
	s_lshl_b64 s[6:7], s[6:7], 2
	s_add_u32 s36, s95, s6
	s_addc_u32 s37, s96, s7
	s_cmp_gt_i32 s4, 7
	v_mov_b32_e32 v212, 1.0
	v_mov_b32_e32 v213, 1.0
	s_cbranch_scc1 .LBB0_1135
	v_lshlrev_b64 v[96:97], 7, v[180:181]
	v_lshl_add_u64 v[96:97], s[36:37], 0, v[96:97]
	global_load_dwordx4 v[96:99], v[96:97], off
	s_waitcnt vmcnt(0)
	v_add_f32_e32 v96, v96, v97
	v_add_f32_e32 v96, v98, v96
	v_add_f32_e32 v96, v99, v96
	v_fmamk_f32 v96, v96, 0x3b800000, v194
	v_mul_f32_e32 v97, 0x4b800000, v96
	v_cmp_gt_f32_e32 vcc, s55, v96
	s_nop 1
	v_cndmask_b32_e32 v96, v96, v97, vcc
	v_rsq_f32_e32 v96, v96
	s_nop 0
	v_mul_f32_e32 v97, 0x45800000, v96
	v_cndmask_b32_e32 v213, v96, v97, vcc

; #define PG8_STAGE(bufoff, gbase, voff) do { _Pragma("unroll") for (int _i = 0; _i < 2; ++_i) \
;         __builtin_amdgcn_global_load_lds((const unsigned*)((const char*)(gbase) + (voff)[_i]), (LAS unsigned*)(lds + (bufoff) + ldsw + _i * 8192), 16, 0, 0); } while (0)
; #define PG8_STAGE_A(bufoff, ptr, half, rev) do { if (REVA && (rev)) { const char* _p = (ptr) - ((half) ? hstepA : 0); PG8_STAGE(bufoff, _p, voffAr); } else { const char* _p = (ptr) + ((half) ? hstepA : 0); PG8_STAGE(bufoff, _p, voffA); } } while (0)
; #define PG8_LDA(dst, b, h) do { _Pragma("unroll") for (int m = 0; m < 4; ++m) _Pragma("unroll") for (int k = 0; k < 2; ++k) dst[m][k] = *(const LAS bf16x8*)(lds + PG8_SA(b, h) + aoff + m * 2048 + k * 1024); } while (0)
; #define PG8_LDB(dst, b, h) do { _Pragma("unroll") for (int n = 0; n < 2; ++n) _Pragma("unroll") for (int k = 0; k < 2; ++k) dst[n][k] = *(const LAS bf16x8*)(lds + PG8_SB(b, h) + boff + n * 2048 + k * 1024); } while (0)
; #define PG8_MMA(ai, bj, At, Bt) do { __builtin_amdgcn_s_setprio(1); _Pragma("unroll") for (int m = 0; m < 4; ++m) _Pragma("unroll") for (int n = 0; n < 2; ++n) _Pragma("unroll") for (int k = 0; k < 2; ++k) \
;         acc[ai][bj][m][n] = __builtin_amdgcn_mfma_f32_16x16x32_bf16(Bt[n][k], At[m][k], acc[ai][bj][m][n], 0, 0, 0); __builtin_amdgcn_s_setprio(0); } while (0)
; #define PG8_WAIT_L(n) asm volatile("s_waitcnt lgkmcnt(" #n ")" ::: "memory")
; #define PG8_BAR __builtin_amdgcn_s_barrier()
; #define PG8_SCHED __builtin_amdgcn_sched_barrier(0)
;     ...
;             PG8_LDB(B0, 0, 0); PG8_SCHED; PG8_LDA(At, 0, 0); PG8_STAGE_A(PG8_SA(1, 1), a1, 1, r1);
;             PG8_WAIT_L(8); PG8_BAR; PG8_WAIT_L(0); PG8_MMA(0, 0, At, B0); PG8_BAR; PG8_SCHED;
;             PG8_LDB(B1, 0, 1); PG8_STAGE(PG8_SB(0, 0), b2, voffB);
;             PG8_BAR; PG8_WAIT_L(0); PG8_MMA(0, 1, At, B1); PG8_BAR;
;             PG8_LDA(At, 0, 1); PG8_STAGE_A(PG8_SA(0, 0), a2, 0, r2);
;             PG8_BAR; PG8_WAIT_L(0); PG8_MMA(1, 0, At, B0); PG8_BAR; PG8_SCHED;
.LBB0_1229:
	s_add_u32 s10, s0, s42
	s_addc_u32 s11, s1, s43
	s_add_u32 s16, s10, 0x100
	s_addc_u32 s17, s11, 0
	s_add_u32 s10, s10, 0x180
	s_addc_u32 s11, s11, 0
	s_add_u32 s14, s69, s42
	s_addc_u32 s15, s70, s43
	s_add_i32 s78, 0, 0x10000
	s_cmpk_eq_i32 s42, 0x1f00
	s_cselect_b32 s15, s39, s15
	s_cselect_b32 s14, s38, s14
	s_cselect_b32 s21, s37, s17
	s_cselect_b32 s20, s36, s16
	s_cselect_b32 s17, s27, s11
	s_cselect_b32 s16, s3, s10
	v_lshl_add_u64 v[158:159], v[128:129], 0, s[42:43]
	s_add_i32 m0, s48, 0xc000
	ds_read_b128 v[178:181], v172
	ds_read_b128 v[182:185], v172 offset:1024
	ds_read_b128 v[204:207], v172 offset:2048
	ds_read_b128 v[208:211], v172 offset:3072
	ds_read_b128 v[212:215], v172 offset:4096
	ds_read_b128 v[216:219], v172 offset:5120
	ds_read_b128 v[220:223], v172 offset:6144
	ds_read_b128 v[224:227], v172 offset:7168
	global_load_lds_dwordx4 v[158:159], off
	v_lshl_add_u64 v[158:159], v[130:131], 0, s[42:43]
	s_add_i32 m0, s48, 0xe000
	s_nop 0
	global_load_lds_dwordx4 v[158:159], off
	s_waitcnt lgkmcnt(8)
	s_waitcnt vmcnt(10)
	s_barrier
	s_waitcnt lgkmcnt(0)
	s_waitcnt lgkmcnt(0)
	v_mfma_f32_16x16x32_bf16 v[124:127], v[132:135], v[178:181], v[124:127]
	v_mfma_f32_16x16x32_bf16 v[120:123], v[140:143], v[178:181], v[120:123]
	v_mfma_f32_16x16x32_bf16 v[112:115], v[132:135], v[204:207], v[112:115]
	v_mfma_f32_16x16x32_bf16 v[108:111], v[140:143], v[204:207], v[108:111]
	v_mfma_f32_16x16x32_bf16 v[92:95], v[132:135], v[212:215], v[92:95]
	v_mfma_f32_16x16x32_bf16 v[88:91], v[140:143], v[212:215], v[88:91]
	v_mfma_f32_16x16x32_bf16 v[84:87], v[132:135], v[220:223], v[84:87]
	v_mfma_f32_16x16x32_bf16 v[76:79], v[140:143], v[220:223], v[76:79]
	v_mfma_f32_16x16x32_bf16 v[124:127], v[136:139], v[182:185], v[124:127]
	v_mfma_f32_16x16x32_bf16 v[120:123], v[174:177], v[182:185], v[120:123]
	v_mfma_f32_16x16x32_bf16 v[112:115], v[136:139], v[208:211], v[112:115]
	v_mfma_f32_16x16x32_bf16 v[108:111], v[174:177], v[208:211], v[108:111]
	v_mfma_f32_16x16x32_bf16 v[92:95], v[136:139], v[216:219], v[92:95]
	v_mfma_f32_16x16x32_bf16 v[88:91], v[174:177], v[216:219], v[88:91]
	v_mfma_f32_16x16x32_bf16 v[84:87], v[136:139], v[224:227], v[84:87]
	v_mfma_f32_16x16x32_bf16 v[76:79], v[174:177], v[224:227], v[76:79]
	s_barrier
	s_add_i32 s10, 0, 0x14000
	v_add_u32_e32 v158, s10, v171
	s_add_i32 s11, s78, s5
	ds_read_b128 v[228:231], v158
	ds_read_b128 v[232:235], v158 offset:1024
	ds_read_b128 v[236:239], v158 offset:2048
	ds_read_b128 v[240:243], v158 offset:3072
	v_lshl_add_u64 v[158:159], s[14:15], 0, v[150:151]
	s_mov_b32 m0, s11
	v_lshl_add_u64 v[168:169], s[14:15], 0, v[148:149]
	global_load_lds_dwordx4 v[158:159], off
	s_add_i32 m0, s11, 0x2000
	s_nop 0
	global_load_lds_dwordx4 v[168:169], off
	s_waitcnt vmcnt(10)
	s_barrier
	s_waitcnt lgkmcnt(0)
	s_waitcnt lgkmcnt(0)
	v_mfma_f32_16x16x32_bf16 v[116:119], v[228:231], v[178:181], v[116:119]
	v_mfma_f32_16x16x32_bf16 v[104:107], v[236:239], v[178:181], v[104:107]
	v_mfma_f32_16x16x32_bf16 v[100:103], v[228:231], v[204:207], v[100:103]
	v_mfma_f32_16x16x32_bf16 v[96:99], v[236:239], v[204:207], v[96:99]
	v_mfma_f32_16x16x32_bf16 v[80:83], v[228:231], v[212:215], v[80:83]
	v_mfma_f32_16x16x32_bf16 v[72:75], v[236:239], v[212:215], v[72:75]
	v_mfma_f32_16x16x32_bf16 v[68:71], v[228:231], v[220:223], v[68:71]
	v_mfma_f32_16x16x32_bf16 v[64:67], v[236:239], v[220:223], v[64:67]
	v_mfma_f32_16x16x32_bf16 v[116:119], v[232:235], v[182:185], v[116:119]
	v_mfma_f32_16x16x32_bf16 v[104:107], v[240:243], v[182:185], v[104:107]
	v_mfma_f32_16x16x32_bf16 v[100:103], v[232:235], v[208:211], v[100:103]
	v_mfma_f32_16x16x32_bf16 v[96:99], v[240:243], v[208:211], v[96:99]
	v_mfma_f32_16x16x32_bf16 v[80:83], v[232:235], v[216:219], v[80:83]
	v_mfma_f32_16x16x32_bf16 v[72:75], v[240:243], v[216:219], v[72:75]
	v_mfma_f32_16x16x32_bf16 v[68:71], v[232:235], v[224:227], v[68:71]
	v_mfma_f32_16x16x32_bf16 v[64:67], v[240:243], v[224:227], v[64:67]
	s_mov_b32 m0, s48
	v_lshl_add_u64 v[190:191], s[20:21], 0, v[150:151]
	s_barrier
	ds_read_b128 v[178:181], v172 offset:16384
	ds_read_b128 v[182:185], v172 offset:17408
	ds_read_b128 v[204:207], v172 offset:18432
	ds_read_b128 v[208:211], v172 offset:19456
	ds_read_b128 v[212:215], v172 offset:20480
	ds_read_b128 v[216:219], v172 offset:21504
	ds_read_b128 v[220:223], v172 offset:22528
	ds_read_b128 v[224:227], v172 offset:23552
	global_load_lds_dwordx4 v[190:191], off
	v_lshl_add_u64 v[190:191], s[20:21], 0, v[148:149]
	s_mov_b32 m0, s49
	s_nop 0
	global_load_lds_dwordx4 v[190:191], off
	s_waitcnt vmcnt(10)
	s_barrier
	s_waitcnt lgkmcnt(0)
	s_waitcnt lgkmcnt(0)
	v_mfma_f32_16x16x32_bf16 v[60:63], v[132:135], v[178:181], v[60:63]
	v_mfma_f32_16x16x32_bf16 v[56:59], v[140:143], v[178:181], v[56:59]
	v_mfma_f32_16x16x32_bf16 v[52:55], v[132:135], v[204:207], v[52:55]
	v_mfma_f32_16x16x32_bf16 v[40:43], v[140:143], v[204:207], v[40:43]
	v_mfma_f32_16x16x32_bf16 v[28:31], v[132:135], v[212:215], v[28:31]
	v_mfma_f32_16x16x32_bf16 v[24:27], v[140:143], v[212:215], v[24:27]
	v_mfma_f32_16x16x32_bf16 v[20:23], v[132:135], v[220:223], v[20:23]
	v_mfma_f32_16x16x32_bf16 v[8:11], v[140:143], v[220:223], v[8:11]
	v_mfma_f32_16x16x32_bf16 v[60:63], v[136:139], v[182:185], v[60:63]
	v_mfma_f32_16x16x32_bf16 v[56:59], v[174:177], v[182:185], v[56:59]
	v_mfma_f32_16x16x32_bf16 v[52:55], v[136:139], v[208:211], v[52:55]
	v_mfma_f32_16x16x32_bf16 v[40:43], v[174:177], v[208:211], v[40:43]
	v_mfma_f32_16x16x32_bf16 v[28:31], v[136:139], v[216:219], v[28:31]
	v_mfma_f32_16x16x32_bf16 v[24:27], v[174:177], v[216:219], v[24:27]
	v_mfma_f32_16x16x32_bf16 v[20:23], v[136:139], v[224:227], v[20:23]
	v_mfma_f32_16x16x32_bf16 v[8:11], v[174:177], v[224:227], v[8:11]
	s_barrier
; #define PG8_STAGE(bufoff, gbase, voff) do { _Pragma("unroll") for (int _i = 0; _i < 2; ++_i) \
;         __builtin_amdgcn_global_load_lds((const unsigned*)((const char*)(gbase) + (voff)[_i]), (LAS unsigned*)(lds + (bufoff) + ldsw + _i * 8192), 16, 0, 0); } while (0)
; #define PG8_STAGE_A(bufoff, ptr, half, rev) do { if (REVA && (rev)) { const char* _p = (ptr) - ((half) ? hstepA : 0); PG8_STAGE(bufoff, _p, voffAr); } else { const char* _p = (ptr) + ((half) ? hstepA : 0); PG8_STAGE(bufoff, _p, voffA); } } while (0)
; #define PG8_LDA(dst, b, h) do { _Pragma("unroll") for (int m = 0; m < 4; ++m) _Pragma("unroll") for (int k = 0; k < 2; ++k) dst[m][k] = *(const LAS bf16x8*)(lds + PG8_SA(b, h) + aoff + m * 2048 + k * 1024); } while (0)
; #define PG8_LDB(dst, b, h) do { _Pragma("unroll") for (int n = 0; n < 2; ++n) _Pragma("unroll") for (int k = 0; k < 2; ++k) dst[n][k] = *(const LAS bf16x8*)(lds + PG8_SB(b, h) + boff + n * 2048 + k * 1024); } while (0)
; #define PG8_MMA(ai, bj, At, Bt) do { __builtin_amdgcn_s_setprio(1); _Pragma("unroll") for (int m = 0; m < 4; ++m) _Pragma("unroll") for (int n = 0; n < 2; ++n) _Pragma("unroll") for (int k = 0; k < 2; ++k) \
;         acc[ai][bj][m][n] = __builtin_amdgcn_mfma_f32_16x16x32_bf16(Bt[n][k], At[m][k], acc[ai][bj][m][n], 0, 0, 0); __builtin_amdgcn_s_setprio(0); } while (0)
; #define PG8_WAIT_V(n) asm volatile("s_waitcnt vmcnt(" #n ")" ::: "memory")
; #define PG8_WAIT_L(n) asm volatile("s_waitcnt lgkmcnt(" #n ")" ::: "memory")
; #define PG8_BAR __builtin_amdgcn_s_barrier()
; #define PG8_SCHED __builtin_amdgcn_sched_barrier(0)
;     ...
;             PG8_STAGE(PG8_SB(0, 1), b2 + hb2, voffB);
;             PG8_WAIT_V(6); PG8_BAR; PG8_MMA(1, 1, At, B1); PG8_BAR;
;             PG8_LDB(B0, 1, 0); PG8_SCHED; PG8_LDA(At, 1, 0); PG8_STAGE_A(PG8_SA(0, 1), a2, 1, r2);
;             PG8_WAIT_L(8); PG8_BAR; PG8_WAIT_L(0); PG8_MMA(0, 0, At, B0); PG8_BAR; PG8_SCHED;
;             PG8_LDB(B1, 1, 1); PG8_STAGE(PG8_SB(1, 0), b3, voffB);
;             PG8_BAR; PG8_WAIT_L(0); PG8_MMA(0, 1, At, B1); PG8_BAR;
;             PG8_LDA(At, 1, 1); PG8_STAGE_A(PG8_SA(1, 0), a3, 0, r3);
	s_add_u32 s78, s14, 0x100000
	s_addc_u32 s79, s15, 0
	s_add_i32 s10, s10, s5
	v_lshl_add_u64 v[132:133], s[78:79], 0, v[150:151]
	s_mov_b32 m0, s10
	s_nop 0
	global_load_lds_dwordx4 v[132:133], off
	v_lshl_add_u64 v[132:133], s[78:79], 0, v[148:149]
	s_add_i32 m0, s10, 0x2000
	s_nop 0
	global_load_lds_dwordx4 v[132:133], off
	v_add_u32_e32 v173, 0x18000, v171
	ds_read_b128 v[132:135], v173
	ds_read_b128 v[136:139], v173 offset:1024
	ds_read_b128 v[140:143], v173 offset:2048
	ds_read_b128 v[174:177], v173 offset:3072
	s_waitcnt vmcnt(10)
	s_barrier
	v_mfma_f32_16x16x32_bf16 v[48:51], v[228:231], v[178:181], v[48:51]
	v_mfma_f32_16x16x32_bf16 v[44:47], v[236:239], v[178:181], v[44:47]
	v_mfma_f32_16x16x32_bf16 v[36:39], v[228:231], v[204:207], v[36:39]
	v_mfma_f32_16x16x32_bf16 v[32:35], v[236:239], v[204:207], v[32:35]
	v_mfma_f32_16x16x32_bf16 v[16:19], v[228:231], v[212:215], v[16:19]
	v_mfma_f32_16x16x32_bf16 v[12:15], v[236:239], v[212:215], v[12:15]
	v_mfma_f32_16x16x32_bf16 v[4:7], v[228:231], v[220:223], v[4:7]
	v_mfma_f32_16x16x32_bf16 v[0:3], v[236:239], v[220:223], v[0:3]
	v_mfma_f32_16x16x32_bf16 v[48:51], v[232:235], v[182:185], v[48:51]
	v_mfma_f32_16x16x32_bf16 v[44:47], v[240:243], v[182:185], v[44:47]
	v_mfma_f32_16x16x32_bf16 v[36:39], v[232:235], v[208:211], v[36:39]
	v_mfma_f32_16x16x32_bf16 v[32:35], v[240:243], v[208:211], v[32:35]
	v_mfma_f32_16x16x32_bf16 v[16:19], v[232:235], v[216:219], v[16:19]
	v_mfma_f32_16x16x32_bf16 v[12:15], v[240:243], v[216:219], v[12:15]
	v_mfma_f32_16x16x32_bf16 v[4:7], v[232:235], v[224:227], v[4:7]
	v_mfma_f32_16x16x32_bf16 v[0:3], v[240:243], v[224:227], v[0:3]
	s_add_i32 s10, 0, 0x18000
	s_barrier
	s_add_u32 s20, s20, 0x100000
	s_addc_u32 s21, s21, 0
	s_mov_b32 m0, s50
	v_lshl_add_u64 v[190:191], s[20:21], 0, v[150:151]
	ds_read_b128 v[178:181], v172 offset:32768
	ds_read_b128 v[182:185], v172 offset:33792
	ds_read_b128 v[204:207], v172 offset:34816
	ds_read_b128 v[208:211], v172 offset:35840
	ds_read_b128 v[212:215], v172 offset:36864
	ds_read_b128 v[216:219], v172 offset:37888
	ds_read_b128 v[220:223], v172 offset:38912
	ds_read_b128 v[224:227], v172 offset:39936
	global_load_lds_dwordx4 v[190:191], off
	v_lshl_add_u64 v[190:191], s[20:21], 0, v[148:149]
	s_mov_b32 m0, s51
	s_nop 0
	global_load_lds_dwordx4 v[190:191], off
	s_waitcnt lgkmcnt(8)
	s_waitcnt vmcnt(10)
	s_barrier
	s_waitcnt lgkmcnt(0)
	s_waitcnt lgkmcnt(0)
	v_mfma_f32_16x16x32_bf16 v[124:127], v[132:135], v[178:181], v[124:127]
	v_mfma_f32_16x16x32_bf16 v[120:123], v[140:143], v[178:181], v[120:123]
	v_mfma_f32_16x16x32_bf16 v[112:115], v[132:135], v[204:207], v[112:115]
	v_mfma_f32_16x16x32_bf16 v[108:111], v[140:143], v[204:207], v[108:111]
	v_mfma_f32_16x16x32_bf16 v[92:95], v[132:135], v[212:215], v[92:95]
	v_mfma_f32_16x16x32_bf16 v[88:91], v[140:143], v[212:215], v[88:91]
	v_mfma_f32_16x16x32_bf16 v[84:87], v[132:135], v[220:223], v[84:87]
	v_mfma_f32_16x16x32_bf16 v[76:79], v[140:143], v[220:223], v[76:79]
	v_mfma_f32_16x16x32_bf16 v[124:127], v[136:139], v[182:185], v[124:127]
	v_mfma_f32_16x16x32_bf16 v[120:123], v[174:177], v[182:185], v[120:123]
	v_mfma_f32_16x16x32_bf16 v[112:115], v[136:139], v[208:211], v[112:115]
	v_mfma_f32_16x16x32_bf16 v[108:111], v[174:177], v[208:211], v[108:111]
	v_mfma_f32_16x16x32_bf16 v[92:95], v[136:139], v[216:219], v[92:95]
	v_mfma_f32_16x16x32_bf16 v[88:91], v[174:177], v[216:219], v[88:91]
	v_mfma_f32_16x16x32_bf16 v[84:87], v[136:139], v[224:227], v[84:87]
	v_mfma_f32_16x16x32_bf16 v[76:79], v[174:177], v[224:227], v[76:79]
	s_barrier
	s_add_i32 s11, 0, 0x1c000
	s_add_i32 s10, s10, s5
	v_add_u32_e32 v173, s11, v171
	v_lshl_add_u64 v[158:159], v[158:159], 0, s[28:29]
	s_mov_b32 m0, s10
	ds_read_b128 v[228:231], v173
	ds_read_b128 v[232:235], v173 offset:1024
	ds_read_b128 v[236:239], v173 offset:2048
	ds_read_b128 v[240:243], v173 offset:3072
	global_load_lds_dwordx4 v[158:159], off
	v_lshl_add_u64 v[158:159], v[168:169], 0, s[28:29]
	s_add_i32 m0, s10, 0x2000
	s_nop 0
	global_load_lds_dwordx4 v[158:159], off
	s_waitcnt vmcnt(10)
	s_barrier
	s_waitcnt lgkmcnt(0)
	s_waitcnt lgkmcnt(0)
	v_mfma_f32_16x16x32_bf16 v[116:119], v[228:231], v[178:181], v[116:119]
	v_mfma_f32_16x16x32_bf16 v[104:107], v[236:239], v[178:181], v[104:107]
	v_mfma_f32_16x16x32_bf16 v[100:103], v[228:231], v[204:207], v[100:103]
	v_mfma_f32_16x16x32_bf16 v[96:99], v[236:239], v[204:207], v[96:99]
	v_mfma_f32_16x16x32_bf16 v[80:83], v[228:231], v[212:215], v[80:83]
	v_mfma_f32_16x16x32_bf16 v[72:75], v[236:239], v[212:215], v[72:75]
	v_mfma_f32_16x16x32_bf16 v[68:71], v[228:231], v[220:223], v[68:71]
	v_mfma_f32_16x16x32_bf16 v[64:67], v[236:239], v[220:223], v[64:67]
	v_mfma_f32_16x16x32_bf16 v[116:119], v[232:235], v[182:185], v[116:119]
	v_mfma_f32_16x16x32_bf16 v[104:107], v[240:243], v[182:185], v[104:107]
	v_mfma_f32_16x16x32_bf16 v[100:103], v[232:235], v[208:211], v[100:103]
	v_mfma_f32_16x16x32_bf16 v[96:99], v[240:243], v[208:211], v[96:99]
	v_mfma_f32_16x16x32_bf16 v[80:83], v[232:235], v[216:219], v[80:83]
	v_mfma_f32_16x16x32_bf16 v[72:75], v[240:243], v[216:219], v[72:75]
	v_mfma_f32_16x16x32_bf16 v[68:71], v[232:235], v[224:227], v[68:71]
	v_mfma_f32_16x16x32_bf16 v[64:67], v[240:243], v[224:227], v[64:67]
	s_mov_b32 m0, s66
	v_lshl_add_u64 v[158:159], s[16:17], 0, v[150:151]
	s_barrier
	ds_read_b128 v[178:181], v172 offset:49152
	ds_read_b128 v[182:185], v172 offset:50176
	ds_read_b128 v[204:207], v172 offset:51200
	ds_read_b128 v[208:211], v172 offset:52224
	ds_read_b128 v[212:215], v172 offset:53248
	ds_read_b128 v[216:219], v172 offset:54272
	ds_read_b128 v[220:223], v172 offset:55296
	ds_read_b128 v[224:227], v172 offset:56320
	global_load_lds_dwordx4 v[158:159], off
	v_lshl_add_u64 v[158:159], s[16:17], 0, v[148:149]
	s_mov_b32 m0, s67
	s_nop 0
	global_load_lds_dwordx4 v[158:159], off
	s_waitcnt vmcnt(10)
	s_barrier
; #define PG8_STAGE(bufoff, gbase, voff) do { _Pragma("unroll") for (int _i = 0; _i < 2; ++_i) \
;         __builtin_amdgcn_global_load_lds((const unsigned*)((const char*)(gbase) + (voff)[_i]), (LAS unsigned*)(lds + (bufoff) + ldsw + _i * 8192), 16, 0, 0); } while (0)
; #define PG8_MMA(ai, bj, At, Bt) do { __builtin_amdgcn_s_setprio(1); _Pragma("unroll") for (int m = 0; m < 4; ++m) _Pragma("unroll") for (int n = 0; n < 2; ++n) _Pragma("unroll") for (int k = 0; k < 2; ++k) \
;         acc[ai][bj][m][n] = __builtin_amdgcn_mfma_f32_16x16x32_bf16(Bt[n][k], At[m][k], acc[ai][bj][m][n], 0, 0, 0); __builtin_amdgcn_s_setprio(0); } while (0)
; #define PG8_WAIT_V(n) asm volatile("s_waitcnt vmcnt(" #n ")" ::: "memory")
; #define PG8_WAIT_L(n) asm volatile("s_waitcnt lgkmcnt(" #n ")" ::: "memory")
; #define PG8_BAR __builtin_amdgcn_s_barrier()
; #define PG8_SCHED __builtin_amdgcn_sched_barrier(0)
;     ...
;             PG8_BAR; PG8_WAIT_L(0); PG8_MMA(1, 0, At, B0); PG8_BAR; PG8_SCHED;
;             PG8_STAGE(PG8_SB(1, 1), b3 + hb2, voffB);
;             PG8_WAIT_V(6); PG8_BAR; PG8_MMA(1, 1, At, B1); PG8_BAR;
;     __device__ __forceinline__ void operator()(const f32x4 (&acc)[2][2][4][2], const Unit& u, int wr, int wc, int fr, int fq, int lane) const {
;         const bool lat = u.pm < 128;
;         const int s = lat ? (u.pm >> 4) : 8;
;         const float* gate = modi + s * 6144 + 4096 + u.pn * BM + wc * 32 + 4 * fq;
;         const size_t r0 = lat ? (size_t)u.pm * BM : (size_t)(u.pm - 128) * BM;
;         const float* base = (lat ? baseL : baseC) + u.pn * BM + wc * 32 + 4 * fq;
;         float* out = (lat ? outL : outC) + u.pn * BM + wc * 32 + 4 * fq;
;         f32x4 gv[2][2];
; #pragma unroll
;         for (int bj = 0; bj < 2; ++bj)
; #pragma unroll
;             for (int n = 0; n < 2; ++n) gv[bj][n] = *(const f32x4*)(gate + bj * HALF + n * 16);
	s_waitcnt lgkmcnt(0)
	s_waitcnt lgkmcnt(0)
	v_mfma_f32_16x16x32_bf16 v[60:63], v[132:135], v[178:181], v[60:63]
	v_mfma_f32_16x16x32_bf16 v[56:59], v[140:143], v[178:181], v[56:59]
	v_mfma_f32_16x16x32_bf16 v[52:55], v[132:135], v[204:207], v[52:55]
	v_mfma_f32_16x16x32_bf16 v[40:43], v[140:143], v[204:207], v[40:43]
	v_mfma_f32_16x16x32_bf16 v[28:31], v[132:135], v[212:215], v[28:31]
	v_mfma_f32_16x16x32_bf16 v[24:27], v[140:143], v[212:215], v[24:27]
	v_mfma_f32_16x16x32_bf16 v[20:23], v[132:135], v[220:223], v[20:23]
	v_mfma_f32_16x16x32_bf16 v[8:11], v[140:143], v[220:223], v[8:11]
	v_mfma_f32_16x16x32_bf16 v[60:63], v[136:139], v[182:185], v[60:63]
	v_mfma_f32_16x16x32_bf16 v[56:59], v[174:177], v[182:185], v[56:59]
	v_mfma_f32_16x16x32_bf16 v[52:55], v[136:139], v[208:211], v[52:55]
	v_mfma_f32_16x16x32_bf16 v[40:43], v[174:177], v[208:211], v[40:43]
	v_mfma_f32_16x16x32_bf16 v[28:31], v[136:139], v[216:219], v[28:31]
	v_mfma_f32_16x16x32_bf16 v[24:27], v[174:177], v[216:219], v[24:27]
	v_mfma_f32_16x16x32_bf16 v[20:23], v[136:139], v[224:227], v[20:23]
	v_mfma_f32_16x16x32_bf16 v[8:11], v[174:177], v[224:227], v[8:11]
	s_barrier
	s_add_u32 s14, s14, 0x100080
	s_addc_u32 s15, s15, 0
	s_add_i32 s10, s11, s5
	v_lshl_add_u64 v[132:133], s[14:15], 0, v[150:151]
	s_mov_b32 m0, s10
	s_nop 0
	global_load_lds_dwordx4 v[132:133], off
	v_lshl_add_u64 v[132:133], s[14:15], 0, v[148:149]
	s_add_i32 m0, s10, 0x2000
	s_nop 0
	global_load_lds_dwordx4 v[132:133], off
	v_add_u32_e32 v158, 0x10000, v171
	ds_read_b128 v[132:135], v158
	ds_read_b128 v[136:139], v158 offset:1024
	ds_read_b128 v[140:143], v158 offset:2048
	ds_read_b128 v[174:177], v158 offset:3072
	s_waitcnt vmcnt(10)
	s_barrier
	v_mfma_f32_16x16x32_bf16 v[48:51], v[228:231], v[178:181], v[48:51]
	v_mfma_f32_16x16x32_bf16 v[44:47], v[236:239], v[178:181], v[44:47]
	v_mfma_f32_16x16x32_bf16 v[36:39], v[228:231], v[204:207], v[36:39]
	v_mfma_f32_16x16x32_bf16 v[32:35], v[236:239], v[204:207], v[32:35]
	v_mfma_f32_16x16x32_bf16 v[16:19], v[228:231], v[212:215], v[16:19]
	v_mfma_f32_16x16x32_bf16 v[12:15], v[236:239], v[212:215], v[12:15]
	v_mfma_f32_16x16x32_bf16 v[4:7], v[228:231], v[220:223], v[4:7]
	v_mfma_f32_16x16x32_bf16 v[0:3], v[236:239], v[220:223], v[0:3]
	v_mfma_f32_16x16x32_bf16 v[48:51], v[232:235], v[182:185], v[48:51]
	v_mfma_f32_16x16x32_bf16 v[44:47], v[240:243], v[182:185], v[44:47]
	v_mfma_f32_16x16x32_bf16 v[36:39], v[232:235], v[208:211], v[36:39]
	v_mfma_f32_16x16x32_bf16 v[32:35], v[240:243], v[208:211], v[32:35]
	v_mfma_f32_16x16x32_bf16 v[16:19], v[232:235], v[216:219], v[16:19]
	v_mfma_f32_16x16x32_bf16 v[12:15], v[240:243], v[216:219], v[12:15]
	v_mfma_f32_16x16x32_bf16 v[4:7], v[232:235], v[224:227], v[4:7]
	v_mfma_f32_16x16x32_bf16 v[0:3], v[240:243], v[224:227], v[0:3]
	s_add_i32 s71, s71, 2
	s_add_u32 s42, s42, 0x100
	s_addc_u32 s43, s43, 0
	s_cmp_gt_u32 s71, 61
	s_barrier
	s_cbranch_scc0 .LBB0_1229
	s_waitcnt lgkmcnt(0)
	s_cmpk_lt_i32 s9, 0x80
	s_cselect_b64 vcc, -1, 0
	s_cselect_b32 s3, s61, s53
	s_cselect_b32 s10, s60, s52
	s_add_i32 s0, s9, 0xffffff80
	s_cmpk_lt_i32 s9, 0x80
	s_cselect_b32 s0, s9, s0
	s_lshr_b32 s1, s9, 4
	s_cmpk_lt_i32 s9, 0x80
	s_mulk_i32 s1, 0x1800
	s_cselect_b32 s14, s1, 0xc000
	s_ashr_i32 s15, s14, 31
	s_lshl_b64 s[14:15], s[14:15], 2
	s_add_u32 s1, s6, s14
	s_addc_u32 s11, s7, s15
	s_lshl_b32 s8, s8, 8
	s_ashr_i32 s9, s8, 31
	s_lshl_b64 s[8:9], s[8:9], 2
	s_add_u32 s1, s1, s8
	s_addc_u32 s11, s11, s9
	s_add_u32 s14, s1, s22
	s_waitcnt vmcnt(0)
	v_cndmask_b32_e32 v129, v147, v145, vcc
	v_cndmask_b32_e32 v128, v146, v144, vcc
	s_addc_u32 s15, s11, 0
	s_ashr_i32 s1, s0, 31
	v_lshl_add_u64 v[128:129], v[128:129], 0, s[8:9]
	s_add_u32 s8, s10, s8
	s_addc_u32 s3, s3, s9
	s_add_u32 s8, s8, s22
	v_lshl_add_u64 v[130:131], s[14:15], 0, v[160:161]
	s_addc_u32 s9, s3, 0
	s_mov_b32 s3, 0x704000
	s_lshl_b64 s[0:1], s[0:1], 21
	s_mov_b64 s[14:15], 0x704000
	v_lshl_add_u64 v[168:169], v[128:129], 0, s[22:23]
	v_add_co_u32_e32 v128, vcc, s3, v130
	v_lshl_add_u64 v[224:225], s[0:1], 0, v[152:153]
	v_lshl_add_u64 v[158:159], v[130:131], 0, s[14:15]
	v_addc_co_u32_e32 v129, vcc, 0, v131, vcc
	v_lshl_add_u64 v[190:191], v[168:169], 0, v[160:161]
	v_or_b32_e32 v226, 0x20000, v224
	v_mov_b32_e32 v227, v225
	global_load_dwordx4 v[136:139], v[158:159], off offset:64
	global_load_dwordx4 v[132:135], v[158:159], off offset:512
	global_load_dwordx4 v[140:143], v[128:129], off
	s_nop 0
	global_load_dwordx4 v[128:131], v[158:159], off offset:576
	v_lshl_add_u64 v[168:169], v[190:191], 0, v[224:225]
	v_lshl_add_u64 v[158:159], v[190:191], 0, v[226:227]
	global_load_dwordx4 v[174:177], v[168:169], off
	global_load_dwordx4 v[178:181], v[168:169], off offset:64
	global_load_dwordx4 v[182:185], v[168:169], off offset:512
	global_load_dwordx4 v[204:207], v[168:169], off offset:576
	global_load_dwordx4 v[208:211], v[158:159], off
	global_load_dwordx4 v[212:215], v[158:159], off offset:64
	global_load_dwordx4 v[216:219], v[158:159], off offset:512
	global_load_dwordx4 v[220:223], v[158:159], off offset:576
	v_lshl_add_u64 v[228:229], s[8:9], 0, v[160:161]
	v_lshl_add_u64 v[158:159], v[228:229], 0, v[224:225]
	s_waitcnt vmcnt(0)
;     __device__ __forceinline__ void operator()(const f32x4 (&acc)[2][2][4][2], const Unit& u, int wr, int wc, int fr, int fq, int lane) const {
;     ...
;         for (int ai = 0; ai < 2; ++ai)
; #pragma unroll
;           for (int mh = 0; mh < 2; ++mh) {
;             f32x4 bs[2][2][2];
; #pragma unroll
;             for (int m2 = 0; m2 < 2; ++m2) {
;                 const size_t ro = (r0 + ai * HALF + wr * 64 + (mh * 2 + m2) * 16 + fr) * (size_t)D;
; #pragma unroll
;                 for (int bj = 0; bj < 2; ++bj)
; #pragma unroll
;                     for (int n = 0; n < 2; ++n) bs[m2][bj][n] = *(const f32x4*)(base + ro + bj * HALF + n * 16);
;             }
;             __builtin_amdgcn_sched_barrier(0);
; #pragma unroll
;             for (int m2 = 0; m2 < 2; ++m2) {
;                 const size_t ro = (r0 + ai * HALF + wr * 64 + (mh * 2 + m2) * 16 + fr) * (size_t)D;
; #pragma unroll
;                 for (int bj = 0; bj < 2; ++bj)
; #pragma unroll
;                     for (int n = 0; n < 2; ++n) *(f32x4*)(out + ro + bj * HALF + n * 16) = bs[m2][bj][n] + gv[bj][n] * acc[ai][bj][mh * 2 + m2][n];
;             }
;             __builtin_amdgcn_sched_barrier(0);
	v_pk_fma_f32 v[118:119], v[118:119], v[134:135], v[184:185]
	v_pk_fma_f32 v[116:117], v[116:117], v[132:133], v[182:183]
	v_pk_fma_f32 v[106:107], v[106:107], v[130:131], v[206:207]
	v_pk_fma_f32 v[104:105], v[104:105], v[128:129], v[204:205]
	global_store_dwordx4 v[158:159], v[116:119], off offset:512
	global_store_dwordx4 v[158:159], v[104:107], off offset:576
	v_pk_fma_f32 v[126:127], v[126:127], v[142:143], v[176:177]
	v_lshl_add_u64 v[116:117], v[228:229], 0, v[226:227]
	v_pk_fma_f32 v[106:107], v[114:115], v[142:143], v[210:211]
	v_pk_fma_f32 v[104:105], v[112:113], v[140:141], v[208:209]
	v_pk_fma_f32 v[124:125], v[124:125], v[140:141], v[174:175]
	v_pk_fma_f32 v[122:123], v[122:123], v[138:139], v[180:181]
	v_pk_fma_f32 v[120:121], v[120:121], v[136:137], v[178:179]
	global_store_dwordx4 v[116:117], v[104:107], off
	v_pk_fma_f32 v[102:103], v[102:103], v[134:135], v[218:219]
	v_pk_fma_f32 v[100:101], v[100:101], v[132:133], v[216:217]
	v_pk_fma_f32 v[106:107], v[110:111], v[138:139], v[214:215]
	v_pk_fma_f32 v[104:105], v[108:109], v[136:137], v[212:213]
	v_pk_fma_f32 v[98:99], v[98:99], v[130:131], v[222:223]
	v_pk_fma_f32 v[96:97], v[96:97], v[128:129], v[220:221]
	global_store_dwordx4 v[158:159], v[124:127], off
	global_store_dwordx4 v[158:159], v[120:123], off offset:64
	global_store_dwordx4 v[116:117], v[104:107], off offset:64
	global_store_dwordx4 v[116:117], v[100:103], off offset:512
	global_store_dwordx4 v[116:117], v[96:99], off offset:576
	v_or_b32_e32 v174, 0x40000, v224
	v_mov_b32_e32 v175, v225
	v_or_b32_e32 v224, 0x60000, v224
	v_lshl_add_u64 v[108:109], v[190:191], 0, v[174:175]
	v_lshl_add_u64 v[124:125], v[190:191], 0, v[224:225]
	global_load_dwordx4 v[96:99], v[108:109], off
	global_load_dwordx4 v[100:103], v[108:109], off offset:64
	global_load_dwordx4 v[104:107], v[108:109], off offset:512
	s_nop 0
	global_load_dwordx4 v[108:111], v[108:109], off offset:576
	s_nop 0
	global_load_dwordx4 v[112:115], v[124:125], off
	global_load_dwordx4 v[116:119], v[124:125], off offset:64
	global_load_dwordx4 v[120:123], v[124:125], off offset:512
	s_nop 0
	global_load_dwordx4 v[124:127], v[124:125], off offset:576
	v_lshl_add_u64 v[174:175], v[228:229], 0, v[174:175]
	s_waitcnt vmcnt(0)
	v_pk_fma_f32 v[82:83], v[82:83], v[134:135], v[106:107]
	v_pk_fma_f32 v[80:81], v[80:81], v[132:133], v[104:105]
	v_pk_fma_f32 v[74:75], v[74:75], v[130:131], v[110:111]
	v_pk_fma_f32 v[72:73], v[72:73], v[128:129], v[108:109]
	global_store_dwordx4 v[174:175], v[80:83], off offset:512
	global_store_dwordx4 v[174:175], v[72:75], off offset:576
	v_pk_fma_f32 v[94:95], v[94:95], v[142:143], v[98:99]
	v_lshl_add_u64 v[80:81], v[228:229], 0, v[224:225]
	v_pk_fma_f32 v[74:75], v[86:87], v[142:143], v[114:115]
	v_pk_fma_f32 v[72:73], v[84:85], v[140:141], v[112:113]
	v_pk_fma_f32 v[92:93], v[92:93], v[140:141], v[96:97]
	v_pk_fma_f32 v[90:91], v[90:91], v[138:139], v[102:103]
	v_pk_fma_f32 v[88:89], v[88:89], v[136:137], v[100:101]
	global_store_dwordx4 v[80:81], v[72:75], off
	v_pk_fma_f32 v[70:71], v[70:71], v[134:135], v[122:123]
	v_pk_fma_f32 v[68:69], v[68:69], v[132:133], v[120:121]
	v_pk_fma_f32 v[74:75], v[78:79], v[138:139], v[118:119]
	v_pk_fma_f32 v[72:73], v[76:77], v[136:137], v[116:117]
	v_pk_fma_f32 v[66:67], v[66:67], v[130:131], v[126:127]
	v_pk_fma_f32 v[64:65], v[64:65], v[128:129], v[124:125]
	global_store_dwordx4 v[174:175], v[92:95], off
	global_store_dwordx4 v[174:175], v[88:91], off offset:64
	global_store_dwordx4 v[80:81], v[72:75], off offset:64
	global_store_dwordx4 v[80:81], v[68:71], off offset:512
	global_store_dwordx4 v[80:81], v[64:67], off offset:576
	s_mov_b32 s3, 0x100000
	v_add_co_u32_e32 v72, vcc, s3, v168
	s_mov_b32 s8, 0x120000
	s_nop 0
	v_addc_co_u32_e32 v73, vcc, 0, v169, vcc
	s_mov_b64 s[0:1], 0x100000
	s_mov_b64 s[10:11], 0x120000
	v_add_co_u32_e32 v88, vcc, s8, v168
	v_lshl_add_u64 v[76:77], v[168:169], 0, s[0:1]
	v_lshl_add_u64 v[92:93], v[168:169], 0, s[10:11]
	v_addc_co_u32_e32 v89, vcc, 0, v169, vcc
	global_load_dwordx4 v[64:67], v[76:77], off offset:64
	global_load_dwordx4 v[68:71], v[76:77], off offset:512
	s_nop 0
	global_load_dwordx4 v[72:75], v[72:73], off
	s_nop 0
	global_load_dwordx4 v[76:79], v[76:77], off offset:576
	s_nop 0
	global_load_dwordx4 v[80:83], v[92:93], off offset:64
	global_load_dwordx4 v[84:87], v[92:93], off offset:512
	s_nop 0
	global_load_dwordx4 v[88:91], v[88:89], off
	s_nop 0
	global_load_dwordx4 v[92:95], v[92:93], off offset:576
	s_waitcnt vmcnt(0)
; #define PG8_WAIT_V(n) asm volatile("s_waitcnt vmcnt(" #n ")" ::: "memory")
; #define PG8_BAR __builtin_amdgcn_s_barrier()
;     ...
;         if (!has_next) break;
; #pragma unroll
;         for (int a = 0; a < 2; ++a)
; #pragma unroll
;             for (int b = 0; b < 2; ++b)
; #pragma unroll
;                 for (int m = 0; m < 4; ++m)
; #pragma unroll
;                     for (int n = 0; n < 2; ++n) acc[a][b][m][n] = (f32x4){0.f, 0.f, 0.f, 0.f};
;         cur = nxt; cA = nA; cB = nB; cAr = nAr; cHb = nHb; ++ui;
;     }
;     PG8_WAIT_V(0);
;     if (wr == 0) PG8_BAR;
;     PG8_BAR;
;     __device__ __forceinline__ void operator()(const f32x4 (&acc)[2][2][4][2], const Unit& u, int wr, int wc, int fr, int fq, int lane) const {
;     ...
;         for (int ai = 0; ai < 2; ++ai)
; #pragma unroll
;           for (int mh = 0; mh < 2; ++mh) {
;             f32x4 bs[2][2][2];
; #pragma unroll
;             for (int m2 = 0; m2 < 2; ++m2) {
;                 const size_t ro = (r0 + ai * HALF + wr * 64 + (mh * 2 + m2) * 16 + fr) * (size_t)D;
; #pragma unroll
;                 for (int bj = 0; bj < 2; ++bj)
; #pragma unroll
;                     for (int n = 0; n < 2; ++n) bs[m2][bj][n] = *(const f32x4*)(base + ro + bj * HALF + n * 16);
;             }
;             __builtin_amdgcn_sched_barrier(0);
; #pragma unroll
;             for (int m2 = 0; m2 < 2; ++m2) {
;                 const size_t ro = (r0 + ai * HALF + wr * 64 + (mh * 2 + m2) * 16 + fr) * (size_t)D;
; #pragma unroll
;                 for (int bj = 0; bj < 2; ++bj)
; #pragma unroll
;                     for (int n = 0; n < 2; ++n) *(f32x4*)(out + ro + bj * HALF + n * 16) = bs[m2][bj][n] + gv[bj][n] * acc[ai][bj][mh * 2 + m2][n];
;             }
;             __builtin_amdgcn_sched_barrier(0);
;           }
	v_pk_fma_f32 v[60:61], v[60:61], v[140:141], v[72:73]
	v_add_co_u32_e32 v72, vcc, s3, v158
	v_lshl_add_u64 v[96:97], v[158:159], 0, s[0:1]
	s_nop 0
	v_addc_co_u32_e32 v73, vcc, 0, v159, vcc
	v_pk_fma_f32 v[50:51], v[50:51], v[134:135], v[70:71]
	v_pk_fma_f32 v[48:49], v[48:49], v[132:133], v[68:69]
	global_store_dwordx4 v[96:97], v[48:51], off offset:512
	v_pk_fma_f32 v[46:47], v[46:47], v[130:131], v[78:79]
	v_pk_fma_f32 v[44:45], v[44:45], v[128:129], v[76:77]
	v_add_co_u32_e32 v50, vcc, s8, v158
	s_mov_b64 s[74:75], 0x100000
	v_pk_fma_f32 v[62:63], v[62:63], v[142:143], v[74:75]
	s_mov_b32 s76, 0x100000
	v_pk_fma_f32 v[58:59], v[58:59], v[138:139], v[66:67]
	v_pk_fma_f32 v[56:57], v[56:57], v[136:137], v[64:65]
	global_store_dwordx4 v[96:97], v[44:47], off offset:576
	v_lshl_add_u64 v[48:49], v[158:159], 0, s[10:11]
	s_mov_b32 s77, 0x120000
	v_pk_fma_f32 v[46:47], v[54:55], v[142:143], v[90:91]
	v_pk_fma_f32 v[44:45], v[52:53], v[140:141], v[88:89]
	v_addc_co_u32_e32 v51, vcc, 0, v159, vcc
	v_pk_fma_f32 v[42:43], v[42:43], v[138:139], v[82:83]
	v_pk_fma_f32 v[40:41], v[40:41], v[136:137], v[80:81]
	v_pk_fma_f32 v[38:39], v[38:39], v[134:135], v[86:87]
	v_pk_fma_f32 v[36:37], v[36:37], v[132:133], v[84:85]
	v_pk_fma_f32 v[34:35], v[34:35], v[130:131], v[94:95]
	v_pk_fma_f32 v[32:33], v[32:33], v[128:129], v[92:93]
	global_store_dwordx4 v[72:73], v[60:63], off
	global_store_dwordx4 v[96:97], v[56:59], off offset:64
	global_store_dwordx4 v[50:51], v[44:47], off
	global_store_dwordx4 v[48:49], v[40:43], off offset:64
	global_store_dwordx4 v[48:49], v[36:39], off offset:512
	global_store_dwordx4 v[48:49], v[32:35], off offset:576
	s_mov_b32 s0, 0x140000
	v_add_co_u32_e32 v40, vcc, s0, v168
	s_mov_b32 s1, 0x160000
	s_nop 0
	v_addc_co_u32_e32 v41, vcc, 0, v169, vcc
	s_mov_b64 s[8:9], 0x140000
	s_mov_b64 s[10:11], 0x160000
	v_add_co_u32_e32 v56, vcc, s1, v168
	v_lshl_add_u64 v[44:45], v[168:169], 0, s[8:9]
	v_lshl_add_u64 v[60:61], v[168:169], 0, s[10:11]
	v_addc_co_u32_e32 v57, vcc, 0, v169, vcc
	global_load_dwordx4 v[32:35], v[44:45], off offset:64
	global_load_dwordx4 v[36:39], v[44:45], off offset:512
	s_nop 0
	global_load_dwordx4 v[40:43], v[40:41], off
	s_nop 0
	global_load_dwordx4 v[44:47], v[44:45], off offset:576
	s_nop 0
	global_load_dwordx4 v[48:51], v[60:61], off offset:64
	global_load_dwordx4 v[52:55], v[60:61], off offset:512
	s_nop 0
	global_load_dwordx4 v[56:59], v[56:57], off
	s_nop 0
	global_load_dwordx4 v[60:63], v[60:61], off offset:576
	s_waitcnt vmcnt(0)
	v_pk_fma_f32 v[28:29], v[28:29], v[140:141], v[40:41]
	v_add_co_u32_e32 v40, vcc, s0, v158
	v_lshl_add_u64 v[64:65], v[158:159], 0, s[8:9]
	s_nop 0
	v_addc_co_u32_e32 v41, vcc, 0, v159, vcc
	v_pk_fma_f32 v[18:19], v[18:19], v[134:135], v[38:39]
	v_pk_fma_f32 v[16:17], v[16:17], v[132:133], v[36:37]
	global_store_dwordx4 v[64:65], v[16:19], off offset:512
	v_pk_fma_f32 v[14:15], v[14:15], v[130:131], v[46:47]
	v_pk_fma_f32 v[12:13], v[12:13], v[128:129], v[44:45]
	v_add_co_u32_e32 v18, vcc, s1, v158
	v_pk_fma_f32 v[30:31], v[30:31], v[142:143], v[42:43]
	s_mov_b32 s18, 0x140000
	v_pk_fma_f32 v[26:27], v[26:27], v[138:139], v[34:35]
	v_pk_fma_f32 v[24:25], v[24:25], v[136:137], v[32:33]
	global_store_dwordx4 v[64:65], v[12:15], off offset:576
	v_lshl_add_u64 v[16:17], v[158:159], 0, s[10:11]
	s_mov_b32 s54, 0x160000
	v_pk_fma_f32 v[14:15], v[22:23], v[142:143], v[58:59]
	v_pk_fma_f32 v[12:13], v[20:21], v[140:141], v[56:57]
	v_addc_co_u32_e32 v19, vcc, 0, v159, vcc
	v_pk_fma_f32 v[10:11], v[10:11], v[138:139], v[50:51]
	v_pk_fma_f32 v[8:9], v[8:9], v[136:137], v[48:49]
	v_pk_fma_f32 v[6:7], v[6:7], v[134:135], v[54:55]
	v_pk_fma_f32 v[4:5], v[4:5], v[132:133], v[52:53]
	v_pk_fma_f32 v[2:3], v[2:3], v[130:131], v[62:63]
	v_pk_fma_f32 v[0:1], v[0:1], v[128:129], v[60:61]
	global_store_dwordx4 v[40:41], v[28:31], off
	global_store_dwordx4 v[64:65], v[24:27], off offset:64
	global_store_dwordx4 v[18:19], v[12:15], off
	global_store_dwordx4 v[16:17], v[8:11], off offset:64
	global_store_dwordx4 v[16:17], v[4:7], off offset:512
	global_store_dwordx4 v[16:17], v[0:3], off offset:576
	s_and_b64 vcc, exec, s[40:41]
	s_mov_b32 s8, s2
	s_mov_b32 s9, s26
	s_mov_b64 s[20:21], s[38:39]
	s_mov_b64 s[0:1], s[36:37]
	s_cbranch_vccz .LBB0_1226
	s_waitcnt vmcnt(0)
	v_readlane_b32 s52, v255, 4
	s_cmpk_gt_u32 s4, 0xff
	v_readlane_b32 s53, v255, 5
	s_cbranch_scc1 .LBB0_1233
	s_barrier
